# priority A/B strategy: all per-cluster s_setprio 1/0 flips deleted from the 8-phase K-loops (timing-only)
# speedup vs baseline: 1.0097x; 1.0097x over previous
; #define LDA(dst, b, h) for (int m = 0; m < 4; ++m) for (int k = 0; k < 2; ++k) \
;     dst[m][k] = *reinterpret_cast<const bf16x8*>((char*)SA(b, h) + lds_byte(wr * 64 + m * 16 + fr, k * 32 + fq * 8))
; #define LDB(dst, b, h) for (int n = 0; n < 2; ++n) for (int k = 0; k < 2; ++k) \
;     dst[n][k] = *reinterpret_cast<const bf16x8*>((char*)SB(b, h) + lds_byte(wc * 32 + n * 16 + fr, k * 32 + fq * 8))
; #define MMA(ai, bj, At_, Bt_) do { __builtin_amdgcn_s_setprio(1); \
;     for (int m = 0; m < 4; ++m) for (int n = 0; n < 2; ++n) for (int k = 0; k < 2; ++k) \
;       acc[ai][bj][m][n] = MFMA16(Bt_[n][k], At_[m][k], acc[ai][bj][m][n]); \
;     __builtin_amdgcn_s_setprio(0); } while (0)
; #define WAIT_V(n) asm volatile("s_waitcnt vmcnt(" #n ")" ::: "memory")
; #define WAIT_L(n) asm volatile("s_waitcnt lgkmcnt(" #n ")" ::: "memory")
; #define BAR __builtin_amdgcn_s_barrier()
; #define SCHED __builtin_amdgcn_sched_barrier(0)
; template <int PART  , bool SYNC_FIRST = true>
; __device__ __forceinline__ void kloop_t(const u16* __restrict__ A, int lda, const u16* __restrict__ Bt, int ldb, int K, Acc& acc, const int wv) {
;     ...
;     LDB(B0, 0, 0); SCHED; LDA(At, 0, 0); STAGE(SA(1, 1), A, lda, HALF, t + 1);
;     WAIT_L(8); BAR; WAIT_L(0); MMA(0, 0, At, B0); BAR; SCHED;
;     LDB(B1, 0, 1); STAGE(SB(0, 0), Bt, ldb, 0, t + 2);
;     BAR; WAIT_L(0); MMA(0, 1, At, B1); BAR;
;     LDA(At, 0, 1); STAGE(SA(0, 0), A, lda, 0, t + 2);
;     BAR; WAIT_L(0); MMA(1, 0, At, B0); BAR; SCHED;
;     STAGE(SB(0, 1), Bt, ldb, HALF, t + 2);
;     WAIT_V(6); BAR; MMA(1, 1, At, B1); BAR;
.LBB0_193:
	v_add_u32_e32 v157, v149, v153
	v_add_u32_e32 v159, v149, v155
	v_add_u32_e32 v158, v149, v154
	ds_read_b128 v[168:171], v157
	ds_read_b128 v[172:175], v158
	v_add_u32_e32 v160, v149, v156
	ds_read_b128 v[176:179], v159
	ds_read_b128 v[180:183], v160
	s_add_u32 s42, s4, s40
	v_mov_b32_e32 v162, v141
	v_mov_b32_e32 v128, v139
	s_addc_u32 s43, s5, s41
	v_add_u32_e32 v161, 0xc000, v144
	ds_read_b128 v[184:187], v130
	ds_read_b128 v[188:191], v131
	ds_read_b128 v[192:195], v132
	ds_read_b128 v[196:199], v133
	ds_read_b128 v[200:203], v134
	ds_read_b128 v[204:207], v135
	ds_read_b128 v[208:211], v137
	ds_read_b128 v[212:215], v138
	v_readfirstlane_b32 s44, v161
	v_lshl_add_u64 v[164:165], s[42:43], 0, v[128:129]
	v_mov_b32_e32 v163, v129
	v_lshl_add_u64 v[164:165], v[164:165], 0, s[14:15]
	s_mov_b32 m0, s44
	v_lshl_add_u64 v[162:163], s[42:43], 0, v[162:163]
	global_load_lds_dwordx4 v[164:165], off
	v_lshl_add_u64 v[164:165], v[162:163], 0, s[14:15]
	v_add_u32_e32 v162, 0xe000, v144
	s_nop 0
	v_readfirstlane_b32 s44, v162
	s_mov_b32 m0, s44
	s_nop 0
	global_load_lds_dwordx4 v[164:165], off
	s_waitcnt lgkmcnt(8)
	s_barrier
	s_waitcnt lgkmcnt(0)
	s_waitcnt lgkmcnt(0)
	v_mfma_f32_16x16x32_bf16 v[124:127], v[168:171], v[184:187], v[124:127]
	v_mfma_f32_16x16x32_bf16 v[120:123], v[176:179], v[184:187], v[120:123]
	v_mfma_f32_16x16x32_bf16 v[116:119], v[168:171], v[192:195], v[116:119]
	v_mfma_f32_16x16x32_bf16 v[112:115], v[176:179], v[192:195], v[112:115]
	v_mfma_f32_16x16x32_bf16 v[108:111], v[168:171], v[200:203], v[108:111]
	v_mfma_f32_16x16x32_bf16 v[104:107], v[176:179], v[200:203], v[104:107]
	v_mfma_f32_16x16x32_bf16 v[100:103], v[168:171], v[208:211], v[100:103]
	v_mfma_f32_16x16x32_bf16 v[96:99], v[176:179], v[208:211], v[96:99]
	v_mfma_f32_16x16x32_bf16 v[124:127], v[172:175], v[188:191], v[124:127]
	v_mfma_f32_16x16x32_bf16 v[120:123], v[180:183], v[188:191], v[120:123]
	v_mfma_f32_16x16x32_bf16 v[116:119], v[172:175], v[196:199], v[116:119]
	v_mfma_f32_16x16x32_bf16 v[112:115], v[180:183], v[196:199], v[112:115]
	v_mfma_f32_16x16x32_bf16 v[108:111], v[172:175], v[204:207], v[108:111]
	v_mfma_f32_16x16x32_bf16 v[104:107], v[180:183], v[204:207], v[104:107]
	v_mfma_f32_16x16x32_bf16 v[100:103], v[172:175], v[212:215], v[100:103]
	v_mfma_f32_16x16x32_bf16 v[96:99], v[180:183], v[212:215], v[96:99]
	s_barrier
	v_add_u32_e32 v163, v150, v153
	v_add_u32_e32 v165, v150, v155
	v_mov_b32_e32 v232, v141
	v_mov_b32_e32 v128, v139
	s_add_u32 s44, s36, s40
	v_add_u32_e32 v164, v150, v154
	ds_read_b128 v[216:219], v163
	ds_read_b128 v[220:223], v164
	v_add_u32_e32 v166, v150, v156
	ds_read_b128 v[224:227], v165
	ds_read_b128 v[228:231], v166
	s_addc_u32 s45, s37, s41
	v_lshl_add_u64 v[234:235], s[44:45], 0, v[128:129]
	v_add_u32_e32 v128, s31, v140
	v_mov_b32_e32 v233, v129
	v_readfirstlane_b32 s53, v128
	v_add_u32_e32 v128, 0x2000, v128
	v_lshl_add_u64 v[234:235], v[234:235], 0, s[16:17]
	s_mov_b32 m0, s53
	v_lshl_add_u64 v[232:233], s[44:45], 0, v[232:233]
	v_readfirstlane_b32 s53, v128
	global_load_lds_dwordx4 v[234:235], off
	v_lshl_add_u64 v[232:233], v[232:233], 0, s[16:17]
	s_mov_b32 m0, s53
	s_nop 0
	global_load_lds_dwordx4 v[232:233], off
	s_barrier
	s_waitcnt lgkmcnt(0)
	s_waitcnt lgkmcnt(0)
	v_mfma_f32_16x16x32_bf16 v[92:95], v[216:219], v[184:187], v[92:95]
	v_mfma_f32_16x16x32_bf16 v[88:91], v[224:227], v[184:187], v[88:91]
	v_mfma_f32_16x16x32_bf16 v[84:87], v[216:219], v[192:195], v[84:87]
	v_mfma_f32_16x16x32_bf16 v[80:83], v[224:227], v[192:195], v[80:83]
	v_mfma_f32_16x16x32_bf16 v[76:79], v[216:219], v[200:203], v[76:79]
	v_mfma_f32_16x16x32_bf16 v[72:75], v[224:227], v[200:203], v[72:75]
	v_mfma_f32_16x16x32_bf16 v[68:71], v[216:219], v[208:211], v[68:71]
	v_mfma_f32_16x16x32_bf16 v[64:67], v[224:227], v[208:211], v[64:67]
	v_mfma_f32_16x16x32_bf16 v[92:95], v[220:223], v[188:191], v[92:95]
	v_mfma_f32_16x16x32_bf16 v[88:91], v[228:231], v[188:191], v[88:91]
	v_mfma_f32_16x16x32_bf16 v[84:87], v[220:223], v[196:199], v[84:87]
	v_mfma_f32_16x16x32_bf16 v[80:83], v[228:231], v[196:199], v[80:83]
	v_mfma_f32_16x16x32_bf16 v[76:79], v[220:223], v[204:207], v[76:79]
	v_mfma_f32_16x16x32_bf16 v[72:75], v[228:231], v[204:207], v[72:75]
	v_mfma_f32_16x16x32_bf16 v[68:71], v[220:223], v[212:215], v[68:71]
	v_mfma_f32_16x16x32_bf16 v[64:67], v[228:231], v[212:215], v[64:67]
	v_mov_b32_e32 v232, v141
	v_mov_b32_e32 v128, v139
	s_barrier
	ds_read_b128 v[184:187], v130 offset:16384
	ds_read_b128 v[188:191], v131 offset:16384
	ds_read_b128 v[192:195], v132 offset:16384
	ds_read_b128 v[196:199], v133 offset:16384
	ds_read_b128 v[200:203], v134 offset:16384
	ds_read_b128 v[204:207], v135 offset:16384
	ds_read_b128 v[208:211], v137 offset:16384
	ds_read_b128 v[212:215], v138 offset:16384
	v_readfirstlane_b32 s53, v144
	v_lshl_add_u64 v[234:235], s[42:43], 0, v[128:129]
	v_mov_b32_e32 v233, v129
	v_add_u32_e32 v128, 0x2000, v144
	v_lshl_add_u64 v[234:235], v[234:235], 0, s[16:17]
	s_mov_b32 m0, s53
	v_lshl_add_u64 v[232:233], s[42:43], 0, v[232:233]
	v_readfirstlane_b32 s53, v128
	global_load_lds_dwordx4 v[234:235], off
	v_lshl_add_u64 v[232:233], v[232:233], 0, s[16:17]
	s_mov_b32 m0, s53
	s_nop 0
	global_load_lds_dwordx4 v[232:233], off
	s_barrier
; #define LDA(dst, b, h) for (int m = 0; m < 4; ++m) for (int k = 0; k < 2; ++k) \
;     dst[m][k] = *reinterpret_cast<const bf16x8*>((char*)SA(b, h) + lds_byte(wr * 64 + m * 16 + fr, k * 32 + fq * 8))
; #define LDB(dst, b, h) for (int n = 0; n < 2; ++n) for (int k = 0; k < 2; ++k) \
;     dst[n][k] = *reinterpret_cast<const bf16x8*>((char*)SB(b, h) + lds_byte(wc * 32 + n * 16 + fr, k * 32 + fq * 8))
; #define MMA(ai, bj, At_, Bt_) do { __builtin_amdgcn_s_setprio(1); \
;     for (int m = 0; m < 4; ++m) for (int n = 0; n < 2; ++n) for (int k = 0; k < 2; ++k) \
;       acc[ai][bj][m][n] = MFMA16(Bt_[n][k], At_[m][k], acc[ai][bj][m][n]); \
;     __builtin_amdgcn_s_setprio(0); } while (0)
; #define WAIT_V(n) asm volatile("s_waitcnt vmcnt(" #n ")" ::: "memory")
; #define WAIT_L(n) asm volatile("s_waitcnt lgkmcnt(" #n ")" ::: "memory")
; #define BAR __builtin_amdgcn_s_barrier()
; #define SCHED __builtin_amdgcn_sched_barrier(0)
; template <int PART  , bool SYNC_FIRST = true>
; __device__ __forceinline__ void kloop_t(const u16* __restrict__ A, int lda, const u16* __restrict__ Bt, int ldb, int K, Acc& acc, const int wv) {
;     ...
;     BAR; WAIT_L(0); MMA(1, 0, At, B0); BAR; SCHED;
;     STAGE(SB(0, 1), Bt, ldb, HALF, t + 2);
;     WAIT_V(6); BAR; MMA(1, 1, At, B1); BAR;
;     LDB(B0, 1, 0); SCHED; LDA(At, 1, 0); STAGE(SA(0, 1), A, lda, HALF, t + 2);
;     WAIT_L(8); BAR; WAIT_L(0); MMA(0, 0, At, B0); BAR; SCHED;
;     LDB(B1, 1, 1); STAGE(SB(1, 0), Bt, ldb, 0, t + 3);
;     BAR; WAIT_L(0); MMA(0, 1, At, B1); BAR;
	s_waitcnt lgkmcnt(0)
	s_waitcnt lgkmcnt(0)
	v_mfma_f32_16x16x32_bf16 v[60:63], v[168:171], v[184:187], v[60:63]
	v_mfma_f32_16x16x32_bf16 v[56:59], v[176:179], v[184:187], v[56:59]
	v_mfma_f32_16x16x32_bf16 v[52:55], v[168:171], v[192:195], v[52:55]
	v_mfma_f32_16x16x32_bf16 v[48:51], v[176:179], v[192:195], v[48:51]
	v_mfma_f32_16x16x32_bf16 v[44:47], v[168:171], v[200:203], v[44:47]
	v_mfma_f32_16x16x32_bf16 v[40:43], v[176:179], v[200:203], v[40:43]
	v_mfma_f32_16x16x32_bf16 v[36:39], v[168:171], v[208:211], v[36:39]
	v_mfma_f32_16x16x32_bf16 v[32:35], v[176:179], v[208:211], v[32:35]
	v_mfma_f32_16x16x32_bf16 v[60:63], v[172:175], v[188:191], v[60:63]
	v_mfma_f32_16x16x32_bf16 v[56:59], v[180:183], v[188:191], v[56:59]
	v_mfma_f32_16x16x32_bf16 v[52:55], v[172:175], v[196:199], v[52:55]
	v_mfma_f32_16x16x32_bf16 v[48:51], v[180:183], v[196:199], v[48:51]
	v_mfma_f32_16x16x32_bf16 v[44:47], v[172:175], v[204:207], v[44:47]
	v_mfma_f32_16x16x32_bf16 v[40:43], v[180:183], v[204:207], v[40:43]
	v_mfma_f32_16x16x32_bf16 v[36:39], v[172:175], v[212:215], v[36:39]
	v_mfma_f32_16x16x32_bf16 v[32:35], v[180:183], v[212:215], v[32:35]
	s_barrier
	v_mov_b32_e32 v168, v141
	v_mov_b32_e32 v128, v139
	v_mov_b32_e32 v169, v129
	v_lshl_add_u64 v[170:171], s[44:45], 0, v[128:129]
	v_add_u32_e32 v128, s35, v140
	v_lshl_add_u64 v[170:171], v[170:171], 0, s[18:19]
	v_readfirstlane_b32 s53, v128
	v_add_u32_e32 v128, 0x2000, v128
	s_mov_b32 m0, s53
	v_lshl_add_u64 v[168:169], s[44:45], 0, v[168:169]
	v_readfirstlane_b32 s53, v128
	global_load_lds_dwordx4 v[170:171], off
	v_lshl_add_u64 v[168:169], v[168:169], 0, s[18:19]
	s_mov_b32 m0, s53
	s_nop 0
	global_load_lds_dwordx4 v[168:169], off
	s_waitcnt vmcnt(6)
	s_barrier
	v_mfma_f32_16x16x32_bf16 v[28:31], v[216:219], v[184:187], v[28:31]
	v_mfma_f32_16x16x32_bf16 v[24:27], v[224:227], v[184:187], v[24:27]
	v_mfma_f32_16x16x32_bf16 v[20:23], v[216:219], v[192:195], v[20:23]
	v_mfma_f32_16x16x32_bf16 v[16:19], v[224:227], v[192:195], v[16:19]
	v_mfma_f32_16x16x32_bf16 v[12:15], v[216:219], v[200:203], v[12:15]
	v_mfma_f32_16x16x32_bf16 v[8:11], v[224:227], v[200:203], v[8:11]
	v_mfma_f32_16x16x32_bf16 v[4:7], v[216:219], v[208:211], v[4:7]
	v_mfma_f32_16x16x32_bf16 v[0:3], v[224:227], v[208:211], v[0:3]
	v_mfma_f32_16x16x32_bf16 v[28:31], v[220:223], v[188:191], v[28:31]
	v_mfma_f32_16x16x32_bf16 v[24:27], v[228:231], v[188:191], v[24:27]
	v_mfma_f32_16x16x32_bf16 v[20:23], v[220:223], v[196:199], v[20:23]
	v_mfma_f32_16x16x32_bf16 v[16:19], v[228:231], v[196:199], v[16:19]
	v_mfma_f32_16x16x32_bf16 v[12:15], v[220:223], v[204:207], v[12:15]
	v_mfma_f32_16x16x32_bf16 v[8:11], v[228:231], v[204:207], v[8:11]
	v_mfma_f32_16x16x32_bf16 v[4:7], v[220:223], v[212:215], v[4:7]
	v_mfma_f32_16x16x32_bf16 v[0:3], v[228:231], v[212:215], v[0:3]
	v_add_u32_e32 v167, v151, v153
	v_add_u32_e32 v169, v151, v155
	s_barrier
	v_add_u32_e32 v168, v151, v154
	ds_read_b128 v[176:179], v167
	ds_read_b128 v[180:183], v168
	v_add_u32_e32 v170, v151, v156
	ds_read_b128 v[184:187], v169
	ds_read_b128 v[188:191], v170
	v_mov_b32_e32 v172, v141
	v_mov_b32_e32 v128, v139
	ds_read_b128 v[192:195], v130 offset:32768
	ds_read_b128 v[196:199], v131 offset:32768
	ds_read_b128 v[200:203], v132 offset:32768
	ds_read_b128 v[204:207], v133 offset:32768
	ds_read_b128 v[208:211], v134 offset:32768
	ds_read_b128 v[212:215], v135 offset:32768
	ds_read_b128 v[216:219], v137 offset:32768
	ds_read_b128 v[220:223], v138 offset:32768
	v_mov_b32_e32 v173, v129
	v_lshl_add_u64 v[174:175], s[42:43], 0, v[128:129]
	v_add_u32_e32 v128, 0x4000, v144
	v_lshl_add_u64 v[174:175], v[174:175], 0, s[18:19]
	v_readfirstlane_b32 s53, v128
	v_add_u32_e32 v128, 0x6000, v144
	s_mov_b32 m0, s53
	v_lshl_add_u64 v[172:173], s[42:43], 0, v[172:173]
	v_readfirstlane_b32 s53, v128
	global_load_lds_dwordx4 v[174:175], off
	v_lshl_add_u64 v[172:173], v[172:173], 0, s[18:19]
	s_mov_b32 m0, s53
	s_nop 0
	global_load_lds_dwordx4 v[172:173], off
	s_waitcnt lgkmcnt(8)
	s_barrier
	s_waitcnt lgkmcnt(0)
	s_waitcnt lgkmcnt(0)
	v_mfma_f32_16x16x32_bf16 v[124:127], v[176:179], v[192:195], v[124:127]
	v_mfma_f32_16x16x32_bf16 v[120:123], v[184:187], v[192:195], v[120:123]
	v_mfma_f32_16x16x32_bf16 v[116:119], v[176:179], v[200:203], v[116:119]
	v_mfma_f32_16x16x32_bf16 v[112:115], v[184:187], v[200:203], v[112:115]
	v_mfma_f32_16x16x32_bf16 v[108:111], v[176:179], v[208:211], v[108:111]
	v_mfma_f32_16x16x32_bf16 v[104:107], v[184:187], v[208:211], v[104:107]
	v_mfma_f32_16x16x32_bf16 v[100:103], v[176:179], v[216:219], v[100:103]
	v_mfma_f32_16x16x32_bf16 v[96:99], v[184:187], v[216:219], v[96:99]
	v_mfma_f32_16x16x32_bf16 v[124:127], v[180:183], v[196:199], v[124:127]
	v_mfma_f32_16x16x32_bf16 v[120:123], v[188:191], v[196:199], v[120:123]
	v_mfma_f32_16x16x32_bf16 v[116:119], v[180:183], v[204:207], v[116:119]
	v_mfma_f32_16x16x32_bf16 v[112:115], v[188:191], v[204:207], v[112:115]
	v_mfma_f32_16x16x32_bf16 v[108:111], v[180:183], v[212:215], v[108:111]
	v_mfma_f32_16x16x32_bf16 v[104:107], v[188:191], v[212:215], v[104:107]
	v_mfma_f32_16x16x32_bf16 v[100:103], v[180:183], v[220:223], v[100:103]
	v_mfma_f32_16x16x32_bf16 v[96:99], v[188:191], v[220:223], v[96:99]
	s_barrier
	v_add_u32_e32 v171, v152, v153
	v_add_u32_e32 v173, v152, v155
	v_mov_b32_e32 v240, v141
	v_mov_b32_e32 v128, v139
	v_add_u32_e32 v172, v152, v154
	ds_read_b128 v[224:227], v171
	ds_read_b128 v[228:231], v172
	v_add_u32_e32 v174, v152, v156
	ds_read_b128 v[232:235], v173
	ds_read_b128 v[236:239], v174
	v_readfirstlane_b32 s53, v142
	v_lshl_add_u64 v[242:243], s[44:45], 0, v[128:129]
	v_mov_b32_e32 v241, v129
	v_lshl_add_u64 v[242:243], v[242:243], 0, s[20:21]
	s_mov_b32 m0, s53
	v_lshl_add_u64 v[240:241], s[44:45], 0, v[240:241]
	v_readfirstlane_b32 s53, v143
	global_load_lds_dwordx4 v[242:243], off
	v_lshl_add_u64 v[240:241], v[240:241], 0, s[20:21]
	s_mov_b32 m0, s53
	s_nop 0
	global_load_lds_dwordx4 v[240:241], off
	s_barrier
; #define LDA(dst, b, h) for (int m = 0; m < 4; ++m) for (int k = 0; k < 2; ++k) \
;     dst[m][k] = *reinterpret_cast<const bf16x8*>((char*)SA(b, h) + lds_byte(wr * 64 + m * 16 + fr, k * 32 + fq * 8))
; #define LDB(dst, b, h) for (int n = 0; n < 2; ++n) for (int k = 0; k < 2; ++k) \
;     dst[n][k] = *reinterpret_cast<const bf16x8*>((char*)SB(b, h) + lds_byte(wc * 32 + n * 16 + fr, k * 32 + fq * 8))
; #define MMA(ai, bj, At_, Bt_) do { __builtin_amdgcn_s_setprio(1); \
;     for (int m = 0; m < 4; ++m) for (int n = 0; n < 2; ++n) for (int k = 0; k < 2; ++k) \
;       acc[ai][bj][m][n] = MFMA16(Bt_[n][k], At_[m][k], acc[ai][bj][m][n]); \
;     __builtin_amdgcn_s_setprio(0); } while (0)
; #define WAIT_V(n) asm volatile("s_waitcnt vmcnt(" #n ")" ::: "memory")
; #define WAIT_L(n) asm volatile("s_waitcnt lgkmcnt(" #n ")" ::: "memory")
; #define BAR __builtin_amdgcn_s_barrier()
; #define SCHED __builtin_amdgcn_sched_barrier(0)
; template <int PART  , bool SYNC_FIRST = true>
; __device__ __forceinline__ void kloop_t(const u16* __restrict__ A, int lda, const u16* __restrict__ Bt, int ldb, int K, Acc& acc, const int wv) {
;     ...
;     BAR; WAIT_L(0); MMA(0, 1, At, B1); BAR;
;     LDA(At, 1, 1); STAGE(SA(1, 0), A, lda, 0, t + 3);
;     BAR; WAIT_L(0); MMA(1, 0, At, B0); BAR; SCHED;
;     STAGE(SB(1, 1), Bt, ldb, HALF, t + 3);
;     WAIT_V(6); BAR; MMA(1, 1, At, B1); BAR;
;   }
;   { LDB(B0, 0, 0); LDA(At, 0, 0); STAGE(SA(1, 1), A, lda, HALF, nt - 1);
	s_waitcnt lgkmcnt(0)
	s_waitcnt lgkmcnt(0)
	v_mfma_f32_16x16x32_bf16 v[92:95], v[224:227], v[192:195], v[92:95]
	v_mfma_f32_16x16x32_bf16 v[88:91], v[232:235], v[192:195], v[88:91]
	v_mfma_f32_16x16x32_bf16 v[84:87], v[224:227], v[200:203], v[84:87]
	v_mfma_f32_16x16x32_bf16 v[80:83], v[232:235], v[200:203], v[80:83]
	v_mfma_f32_16x16x32_bf16 v[76:79], v[224:227], v[208:211], v[76:79]
	v_mfma_f32_16x16x32_bf16 v[72:75], v[232:235], v[208:211], v[72:75]
	v_mfma_f32_16x16x32_bf16 v[68:71], v[224:227], v[216:219], v[68:71]
	v_mfma_f32_16x16x32_bf16 v[64:67], v[232:235], v[216:219], v[64:67]
	v_mfma_f32_16x16x32_bf16 v[92:95], v[228:231], v[196:199], v[92:95]
	v_mfma_f32_16x16x32_bf16 v[88:91], v[236:239], v[196:199], v[88:91]
	v_mfma_f32_16x16x32_bf16 v[84:87], v[228:231], v[204:207], v[84:87]
	v_mfma_f32_16x16x32_bf16 v[80:83], v[236:239], v[204:207], v[80:83]
	v_mfma_f32_16x16x32_bf16 v[76:79], v[228:231], v[212:215], v[76:79]
	v_mfma_f32_16x16x32_bf16 v[72:75], v[236:239], v[212:215], v[72:75]
	v_mfma_f32_16x16x32_bf16 v[68:71], v[228:231], v[220:223], v[68:71]
	v_mfma_f32_16x16x32_bf16 v[64:67], v[236:239], v[220:223], v[64:67]
	v_mov_b32_e32 v240, v141
	v_mov_b32_e32 v128, v139
	s_barrier
	ds_read_b128 v[192:195], v130 offset:49152
	ds_read_b128 v[196:199], v131 offset:49152
	ds_read_b128 v[200:203], v132 offset:49152
	ds_read_b128 v[204:207], v133 offset:49152
	ds_read_b128 v[208:211], v134 offset:49152
	ds_read_b128 v[212:215], v135 offset:49152
	ds_read_b128 v[216:219], v137 offset:49152
	ds_read_b128 v[220:223], v138 offset:49152
	v_readfirstlane_b32 s53, v145
	v_lshl_add_u64 v[242:243], s[42:43], 0, v[128:129]
	v_mov_b32_e32 v241, v129
	v_lshl_add_u64 v[242:243], v[242:243], 0, s[20:21]
	s_mov_b32 m0, s53
	v_lshl_add_u64 v[240:241], s[42:43], 0, v[240:241]
	v_readfirstlane_b32 s42, v146
	global_load_lds_dwordx4 v[242:243], off
	v_lshl_add_u64 v[240:241], v[240:241], 0, s[20:21]
	s_mov_b32 m0, s42
	s_nop 0
	global_load_lds_dwordx4 v[240:241], off
	s_barrier
	s_waitcnt lgkmcnt(0)
	s_waitcnt lgkmcnt(0)
	v_mfma_f32_16x16x32_bf16 v[60:63], v[176:179], v[192:195], v[60:63]
	v_mfma_f32_16x16x32_bf16 v[56:59], v[184:187], v[192:195], v[56:59]
	v_mfma_f32_16x16x32_bf16 v[52:55], v[176:179], v[200:203], v[52:55]
	v_mfma_f32_16x16x32_bf16 v[48:51], v[184:187], v[200:203], v[48:51]
	v_mfma_f32_16x16x32_bf16 v[44:47], v[176:179], v[208:211], v[44:47]
	v_mfma_f32_16x16x32_bf16 v[40:43], v[184:187], v[208:211], v[40:43]
	v_mfma_f32_16x16x32_bf16 v[36:39], v[176:179], v[216:219], v[36:39]
	v_mfma_f32_16x16x32_bf16 v[32:35], v[184:187], v[216:219], v[32:35]
	v_mfma_f32_16x16x32_bf16 v[60:63], v[180:183], v[196:199], v[60:63]
	v_mfma_f32_16x16x32_bf16 v[56:59], v[188:191], v[196:199], v[56:59]
	v_mfma_f32_16x16x32_bf16 v[52:55], v[180:183], v[204:207], v[52:55]
	v_mfma_f32_16x16x32_bf16 v[48:51], v[188:191], v[204:207], v[48:51]
	v_mfma_f32_16x16x32_bf16 v[44:47], v[180:183], v[212:215], v[44:47]
	v_mfma_f32_16x16x32_bf16 v[40:43], v[188:191], v[212:215], v[40:43]
	v_mfma_f32_16x16x32_bf16 v[36:39], v[180:183], v[220:223], v[36:39]
	v_mfma_f32_16x16x32_bf16 v[32:35], v[188:191], v[220:223], v[32:35]
	s_barrier
	v_mov_b32_e32 v176, v141
	v_mov_b32_e32 v128, v139
	v_readfirstlane_b32 s42, v147
	v_lshl_add_u64 v[178:179], s[44:45], 0, v[128:129]
	v_mov_b32_e32 v177, v129
	v_lshl_add_u64 v[178:179], v[178:179], 0, s[22:23]
	s_mov_b32 m0, s42
	v_lshl_add_u64 v[176:177], s[44:45], 0, v[176:177]
	v_readfirstlane_b32 s42, v148
	global_load_lds_dwordx4 v[178:179], off
	v_lshl_add_u64 v[176:177], v[176:177], 0, s[22:23]
	s_mov_b32 m0, s42
	s_nop 0
	global_load_lds_dwordx4 v[176:177], off
	s_waitcnt vmcnt(6)
	s_barrier
	v_mfma_f32_16x16x32_bf16 v[28:31], v[224:227], v[192:195], v[28:31]
	v_mfma_f32_16x16x32_bf16 v[24:27], v[232:235], v[192:195], v[24:27]
	v_mfma_f32_16x16x32_bf16 v[20:23], v[224:227], v[200:203], v[20:23]
	v_mfma_f32_16x16x32_bf16 v[16:19], v[232:235], v[200:203], v[16:19]
	v_mfma_f32_16x16x32_bf16 v[12:15], v[224:227], v[208:211], v[12:15]
	v_mfma_f32_16x16x32_bf16 v[8:11], v[232:235], v[208:211], v[8:11]
	v_mfma_f32_16x16x32_bf16 v[4:7], v[224:227], v[216:219], v[4:7]
	v_mfma_f32_16x16x32_bf16 v[0:3], v[232:235], v[216:219], v[0:3]
	v_mfma_f32_16x16x32_bf16 v[28:31], v[228:231], v[196:199], v[28:31]
	v_mfma_f32_16x16x32_bf16 v[24:27], v[236:239], v[196:199], v[24:27]
	v_mfma_f32_16x16x32_bf16 v[20:23], v[228:231], v[204:207], v[20:23]
	v_mfma_f32_16x16x32_bf16 v[16:19], v[236:239], v[204:207], v[16:19]
	v_mfma_f32_16x16x32_bf16 v[12:15], v[228:231], v[212:215], v[12:15]
	v_mfma_f32_16x16x32_bf16 v[8:11], v[236:239], v[212:215], v[8:11]
	v_mfma_f32_16x16x32_bf16 v[4:7], v[228:231], v[220:223], v[4:7]
	v_mfma_f32_16x16x32_bf16 v[0:3], v[236:239], v[220:223], v[0:3]
	s_add_i32 s39, s39, 2
	s_add_u32 s40, s40, 0x100
	s_addc_u32 s41, s41, 0
	s_cmp_lt_u32 s39, 12
	s_barrier
	s_cbranch_scc1 .LBB0_193
	s_add_u32 s4, s4, 0x40780
	v_readfirstlane_b32 s36, v161
	s_addc_u32 s5, s5, 0
	s_mov_b32 m0, s36
	v_readfirstlane_b32 s36, v162
	ds_read_b128 v[142:145], v157
	ds_read_b128 v[146:149], v158
	ds_read_b128 v[150:153], v159
	ds_read_b128 v[154:157], v160
	ds_read_b128 v[176:179], v130
	ds_read_b128 v[180:183], v131
	ds_read_b128 v[184:187], v132
	ds_read_b128 v[188:191], v133
	ds_read_b128 v[192:195], v134
	ds_read_b128 v[196:199], v135
	ds_read_b128 v[200:203], v137
	ds_read_b128 v[204:207], v138
	s_nop 0
	global_load_lds_dwordx4 v139, s[4:5]
	s_mov_b32 m0, s36
	s_nop 0
	global_load_lds_dwordx4 v141, s[4:5]
	s_barrier
; #define LDA(dst, b, h) for (int m = 0; m < 4; ++m) for (int k = 0; k < 2; ++k) \
;     dst[m][k] = *reinterpret_cast<const bf16x8*>((char*)SA(b, h) + lds_byte(wr * 64 + m * 16 + fr, k * 32 + fq * 8))
; #define LDB(dst, b, h) for (int n = 0; n < 2; ++n) for (int k = 0; k < 2; ++k) \
;     dst[n][k] = *reinterpret_cast<const bf16x8*>((char*)SB(b, h) + lds_byte(wc * 32 + n * 16 + fr, k * 32 + fq * 8))
; #define MMA(ai, bj, At_, Bt_) do { __builtin_amdgcn_s_setprio(1); \
;     for (int m = 0; m < 4; ++m) for (int n = 0; n < 2; ++n) for (int k = 0; k < 2; ++k) \
;       acc[ai][bj][m][n] = MFMA16(Bt_[n][k], At_[m][k], acc[ai][bj][m][n]); \
;     __builtin_amdgcn_s_setprio(0); } while (0)
; #define WAIT_V(n) asm volatile("s_waitcnt vmcnt(" #n ")" ::: "memory")
; #define WAIT_L(n) asm volatile("s_waitcnt lgkmcnt(" #n ")" ::: "memory")
; #define BAR __builtin_amdgcn_s_barrier()
; template <int PART  , bool SYNC_FIRST = true>
; __device__ __forceinline__ void kloop_t(const u16* __restrict__ A, int lda, const u16* __restrict__ Bt, int ldb, int K, Acc& acc, const int wv) {
;     ...
;   { LDB(B0, 0, 0); LDA(At, 0, 0); STAGE(SA(1, 1), A, lda, HALF, nt - 1);
;     BAR; WAIT_L(0); MMA(0, 0, At, B0); BAR;
;     LDB(B1, 0, 1); BAR; WAIT_L(0); MMA(0, 1, At, B1); BAR;
;     LDA(At, 0, 1); WAIT_V(4); BAR; WAIT_L(0); MMA(1, 0, At, B0); MMA(1, 1, At, B1); BAR; }
;   { LDB(B0, 1, 0); LDA(At, 1, 0); WAIT_V(2); BAR; WAIT_L(0); MMA(0, 0, At, B0); BAR;
	s_waitcnt lgkmcnt(0)
	s_waitcnt lgkmcnt(0)
	v_mfma_f32_16x16x32_bf16 v[124:127], v[142:145], v[176:179], v[124:127]
	v_mfma_f32_16x16x32_bf16 v[120:123], v[150:153], v[176:179], v[120:123]
	v_mfma_f32_16x16x32_bf16 v[116:119], v[142:145], v[184:187], v[116:119]
	v_mfma_f32_16x16x32_bf16 v[112:115], v[150:153], v[184:187], v[112:115]
	v_mfma_f32_16x16x32_bf16 v[100:103], v[142:145], v[200:203], v[100:103]
	v_mfma_f32_16x16x32_bf16 v[96:99], v[150:153], v[200:203], v[96:99]
	v_mfma_f32_16x16x32_bf16 v[124:127], v[146:149], v[180:183], v[124:127]
	v_mfma_f32_16x16x32_bf16 v[120:123], v[154:157], v[180:183], v[120:123]
	v_mfma_f32_16x16x32_bf16 v[116:119], v[146:149], v[188:191], v[116:119]
	v_mfma_f32_16x16x32_bf16 v[112:115], v[154:157], v[188:191], v[112:115]
	v_mfma_f32_16x16x32_bf16 v[108:111], v[142:145], v[192:195], v[108:111]
	v_mfma_f32_16x16x32_bf16 v[104:107], v[150:153], v[192:195], v[104:107]
	v_mfma_f32_16x16x32_bf16 v[100:103], v[146:149], v[204:207], v[100:103]
	v_mfma_f32_16x16x32_bf16 v[96:99], v[154:157], v[204:207], v[96:99]
	v_mfma_f32_16x16x32_bf16 v[158:161], v[146:149], v[196:199], v[108:111]
	v_mfma_f32_16x16x32_bf16 v[208:211], v[154:157], v[196:199], v[104:107]
	s_barrier
	s_nop 1
	ds_read_b128 v[104:107], v163
	ds_read_b128 v[108:111], v164
	ds_read_b128 v[162:165], v165
	ds_read_b128 v[212:215], v166
	s_barrier
	s_waitcnt lgkmcnt(0)
	s_waitcnt lgkmcnt(0)
	v_mfma_f32_16x16x32_bf16 v[84:87], v[104:107], v[184:187], v[84:87]
	v_mfma_f32_16x16x32_bf16 v[80:83], v[162:165], v[184:187], v[80:83]
	v_mfma_f32_16x16x32_bf16 v[68:71], v[104:107], v[200:203], v[68:71]
	v_mfma_f32_16x16x32_bf16 v[64:67], v[162:165], v[200:203], v[64:67]
	v_mfma_f32_16x16x32_bf16 v[92:95], v[104:107], v[176:179], v[92:95]
	v_mfma_f32_16x16x32_bf16 v[88:91], v[162:165], v[176:179], v[88:91]
	v_mfma_f32_16x16x32_bf16 v[84:87], v[108:111], v[188:191], v[84:87]
	v_mfma_f32_16x16x32_bf16 v[80:83], v[212:215], v[188:191], v[80:83]
	v_mfma_f32_16x16x32_bf16 v[76:79], v[104:107], v[192:195], v[76:79]
	v_mfma_f32_16x16x32_bf16 v[72:75], v[162:165], v[192:195], v[72:75]
	v_mfma_f32_16x16x32_bf16 v[68:71], v[108:111], v[204:207], v[68:71]
	v_mfma_f32_16x16x32_bf16 v[64:67], v[212:215], v[204:207], v[64:67]
	v_mfma_f32_16x16x32_bf16 v[216:219], v[108:111], v[180:183], v[92:95]
	v_mfma_f32_16x16x32_bf16 v[176:179], v[212:215], v[180:183], v[88:91]
	v_mfma_f32_16x16x32_bf16 v[180:183], v[108:111], v[196:199], v[76:79]
	v_mfma_f32_16x16x32_bf16 v[184:187], v[212:215], v[196:199], v[72:75]
	s_barrier
	s_nop 0
	ds_read_b128 v[72:75], v130 offset:16384
	ds_read_b128 v[76:79], v131 offset:16384
	ds_read_b128 v[88:91], v132 offset:16384
	ds_read_b128 v[92:95], v133 offset:16384
	ds_read_b128 v[188:191], v134 offset:16384
	ds_read_b128 v[192:195], v135 offset:16384
	ds_read_b128 v[196:199], v137 offset:16384
	ds_read_b128 v[200:203], v138 offset:16384
	s_waitcnt vmcnt(4)
	s_barrier
	s_waitcnt lgkmcnt(0)
	s_waitcnt lgkmcnt(0)
	v_mfma_f32_16x16x32_bf16 v[60:63], v[142:145], v[72:75], v[60:63]
	v_mfma_f32_16x16x32_bf16 v[56:59], v[150:153], v[72:75], v[56:59]
	v_mfma_f32_16x16x32_bf16 v[52:55], v[142:145], v[88:91], v[52:55]
	v_mfma_f32_16x16x32_bf16 v[48:51], v[150:153], v[88:91], v[48:51]
	v_mfma_f32_16x16x32_bf16 v[36:39], v[142:145], v[196:199], v[36:39]
	v_mfma_f32_16x16x32_bf16 v[32:35], v[150:153], v[196:199], v[32:35]
	v_mfma_f32_16x16x32_bf16 v[60:63], v[146:149], v[76:79], v[60:63]
	v_mfma_f32_16x16x32_bf16 v[56:59], v[154:157], v[76:79], v[56:59]
	v_mfma_f32_16x16x32_bf16 v[52:55], v[146:149], v[92:95], v[52:55]
	v_mfma_f32_16x16x32_bf16 v[48:51], v[154:157], v[92:95], v[48:51]
	v_mfma_f32_16x16x32_bf16 v[44:47], v[142:145], v[188:191], v[44:47]
	v_mfma_f32_16x16x32_bf16 v[40:43], v[150:153], v[188:191], v[40:43]
	v_mfma_f32_16x16x32_bf16 v[36:39], v[146:149], v[200:203], v[36:39]
	v_mfma_f32_16x16x32_bf16 v[32:35], v[154:157], v[200:203], v[32:35]
	v_mfma_f32_16x16x32_bf16 v[204:207], v[146:149], v[192:195], v[44:47]
	v_mfma_f32_16x16x32_bf16 v[220:223], v[154:157], v[192:195], v[40:43]
	v_mfma_f32_16x16x32_bf16 v[20:23], v[104:107], v[88:91], v[20:23]
	v_mfma_f32_16x16x32_bf16 v[16:19], v[162:165], v[88:91], v[16:19]
	v_mfma_f32_16x16x32_bf16 v[4:7], v[104:107], v[196:199], v[4:7]
	v_mfma_f32_16x16x32_bf16 v[0:3], v[162:165], v[196:199], v[0:3]
	v_mfma_f32_16x16x32_bf16 v[28:31], v[104:107], v[72:75], v[28:31]
	v_mfma_f32_16x16x32_bf16 v[24:27], v[162:165], v[72:75], v[24:27]
	v_mfma_f32_16x16x32_bf16 v[20:23], v[108:111], v[92:95], v[20:23]
	v_mfma_f32_16x16x32_bf16 v[16:19], v[212:215], v[92:95], v[16:19]
	v_mfma_f32_16x16x32_bf16 v[12:15], v[104:107], v[188:191], v[12:15]
	v_mfma_f32_16x16x32_bf16 v[8:11], v[162:165], v[188:191], v[8:11]
	v_mfma_f32_16x16x32_bf16 v[4:7], v[108:111], v[200:203], v[4:7]
	v_mfma_f32_16x16x32_bf16 v[0:3], v[212:215], v[200:203], v[0:3]
	v_mfma_f32_16x16x32_bf16 v[140:143], v[108:111], v[76:79], v[28:31]
	v_mfma_f32_16x16x32_bf16 v[144:147], v[212:215], v[76:79], v[24:27]
	v_mfma_f32_16x16x32_bf16 v[148:151], v[108:111], v[192:195], v[12:15]
	v_mfma_f32_16x16x32_bf16 v[152:155], v[212:215], v[192:195], v[8:11]
	s_barrier
; #define LDA(dst, b, h) for (int m = 0; m < 4; ++m) for (int k = 0; k < 2; ++k) \
;     dst[m][k] = *reinterpret_cast<const bf16x8*>((char*)SA(b, h) + lds_byte(wr * 64 + m * 16 + fr, k * 32 + fq * 8))
; #define LDB(dst, b, h) for (int n = 0; n < 2; ++n) for (int k = 0; k < 2; ++k) \
;     dst[n][k] = *reinterpret_cast<const bf16x8*>((char*)SB(b, h) + lds_byte(wc * 32 + n * 16 + fr, k * 32 + fq * 8))
; #define MMA(ai, bj, At_, Bt_) do { __builtin_amdgcn_s_setprio(1); \
;     for (int m = 0; m < 4; ++m) for (int n = 0; n < 2; ++n) for (int k = 0; k < 2; ++k) \
;       acc[ai][bj][m][n] = MFMA16(Bt_[n][k], At_[m][k], acc[ai][bj][m][n]); \
;     __builtin_amdgcn_s_setprio(0); } while (0)
; #define WAIT_V(n) asm volatile("s_waitcnt vmcnt(" #n ")" ::: "memory")
; #define WAIT_L(n) asm volatile("s_waitcnt lgkmcnt(" #n ")" ::: "memory")
; #define BAR __builtin_amdgcn_s_barrier()
; template <int PART  , bool SYNC_FIRST = true>
; __device__ __forceinline__ void kloop_t(const u16* __restrict__ A, int lda, const u16* __restrict__ Bt, int ldb, int K, Acc& acc, const int wv) {
;     ...
;   { LDB(B0, 1, 0); LDA(At, 1, 0); WAIT_V(2); BAR; WAIT_L(0); MMA(0, 0, At, B0); BAR;
;     LDB(B1, 1, 1); WAIT_V(0); BAR; WAIT_L(0); MMA(0, 1, At, B1); BAR;
;     LDA(At, 1, 1); BAR; WAIT_L(0); MMA(1, 0, At, B0); MMA(1, 1, At, B1); BAR; }
;   if (wr == 0) BAR;
	s_nop 0
	ds_read_b128 v[8:11], v167
	ds_read_b128 v[12:15], v168
	ds_read_b128 v[162:165], v169
	ds_read_b128 v[166:169], v170
	ds_read_b128 v[24:27], v130 offset:32768
	ds_read_b128 v[28:31], v131 offset:32768
	ds_read_b128 v[40:43], v132 offset:32768
	ds_read_b128 v[44:47], v133 offset:32768
	ds_read_b128 v[188:191], v134 offset:32768
	ds_read_b128 v[192:195], v135 offset:32768
	ds_read_b128 v[196:199], v137 offset:32768
	ds_read_b128 v[200:203], v138 offset:32768
	s_waitcnt vmcnt(2)
	s_barrier
	s_waitcnt lgkmcnt(0)
	s_waitcnt lgkmcnt(0)
	v_mfma_f32_16x16x32_bf16 v[72:75], v[8:11], v[24:27], v[124:127]
	v_mfma_f32_16x16x32_bf16 v[124:127], v[12:15], v[28:31], v[72:75]
	v_mfma_f32_16x16x32_bf16 v[72:75], v[162:165], v[24:27], v[120:123]
	v_mfma_f32_16x16x32_bf16 v[120:123], v[166:169], v[28:31], v[72:75]
	v_mfma_f32_16x16x32_bf16 v[72:75], v[8:11], v[40:43], v[116:119]
	v_mfma_f32_16x16x32_bf16 v[108:111], v[12:15], v[44:47], v[72:75]
	v_mfma_f32_16x16x32_bf16 v[72:75], v[162:165], v[40:43], v[112:115]
	v_mfma_f32_16x16x32_bf16 v[104:107], v[166:169], v[44:47], v[72:75]
	v_mfma_f32_16x16x32_bf16 v[72:75], v[8:11], v[188:191], v[158:161]
	v_mfma_f32_16x16x32_bf16 v[92:95], v[12:15], v[192:195], v[72:75]
	v_mfma_f32_16x16x32_bf16 v[72:75], v[162:165], v[188:191], v[208:211]
	v_mfma_f32_16x16x32_bf16 v[88:91], v[166:169], v[192:195], v[72:75]
	v_mfma_f32_16x16x32_bf16 v[72:75], v[8:11], v[196:199], v[100:103]
	v_mfma_f32_16x16x32_bf16 v[76:79], v[12:15], v[200:203], v[72:75]
	v_mfma_f32_16x16x32_bf16 v[72:75], v[162:165], v[196:199], v[96:99]
	v_mfma_f32_16x16x32_bf16 v[72:75], v[166:169], v[200:203], v[72:75]
	s_barrier
	ds_read_b128 v[156:159], v171
	ds_read_b128 v[208:211], v172
	ds_read_b128 v[170:173], v173
	ds_read_b128 v[212:215], v174
	s_waitcnt vmcnt(0)
	s_barrier
	s_waitcnt lgkmcnt(0)
	s_waitcnt lgkmcnt(0)
	v_mfma_f32_16x16x32_bf16 v[96:99], v[156:159], v[24:27], v[216:219]
	v_mfma_f32_16x16x32_bf16 v[24:27], v[170:173], v[24:27], v[176:179]
	v_mfma_f32_16x16x32_bf16 v[112:115], v[212:215], v[28:31], v[24:27]
	v_mfma_f32_16x16x32_bf16 v[24:27], v[156:159], v[40:43], v[84:87]
	v_mfma_f32_16x16x32_bf16 v[100:103], v[208:211], v[44:47], v[24:27]
	v_mfma_f32_16x16x32_bf16 v[24:27], v[170:173], v[40:43], v[80:83]
	v_mfma_f32_16x16x32_bf16 v[116:119], v[208:211], v[28:31], v[96:99]
	v_mfma_f32_16x16x32_bf16 v[96:99], v[212:215], v[44:47], v[24:27]
	v_mfma_f32_16x16x32_bf16 v[24:27], v[156:159], v[188:191], v[180:183]
	v_mfma_f32_16x16x32_bf16 v[84:87], v[208:211], v[192:195], v[24:27]
	v_mfma_f32_16x16x32_bf16 v[24:27], v[170:173], v[188:191], v[184:187]
	v_mfma_f32_16x16x32_bf16 v[80:83], v[212:215], v[192:195], v[24:27]
	v_mfma_f32_16x16x32_bf16 v[24:27], v[156:159], v[196:199], v[68:71]
	v_mfma_f32_16x16x32_bf16 v[68:71], v[208:211], v[200:203], v[24:27]
	v_mfma_f32_16x16x32_bf16 v[24:27], v[170:173], v[196:199], v[64:67]
	v_mfma_f32_16x16x32_bf16 v[64:67], v[212:215], v[200:203], v[24:27]
	s_barrier
	ds_read_b128 v[174:177], v130 offset:49152
	ds_read_b128 v[178:181], v131 offset:49152
	ds_read_b128 v[182:185], v132 offset:49152
	ds_read_b128 v[130:133], v133 offset:49152
	ds_read_b128 v[186:189], v134 offset:49152
	ds_read_b128 v[190:193], v135 offset:49152
	ds_read_b128 v[194:197], v137 offset:49152
	ds_read_b128 v[198:201], v138 offset:49152
	s_barrier
	s_waitcnt lgkmcnt(0)
	s_waitcnt lgkmcnt(0)
	v_mfma_f32_16x16x32_bf16 v[24:27], v[8:11], v[174:177], v[60:63]
	v_mfma_f32_16x16x32_bf16 v[60:63], v[12:15], v[178:181], v[24:27]
	v_mfma_f32_16x16x32_bf16 v[24:27], v[162:165], v[174:177], v[56:59]
	v_mfma_f32_16x16x32_bf16 v[56:59], v[166:169], v[178:181], v[24:27]
	v_mfma_f32_16x16x32_bf16 v[24:27], v[8:11], v[182:185], v[52:55]
	v_mfma_f32_16x16x32_bf16 v[44:47], v[12:15], v[130:133], v[24:27]
	v_mfma_f32_16x16x32_bf16 v[24:27], v[162:165], v[182:185], v[48:51]
	v_mfma_f32_16x16x32_bf16 v[40:43], v[166:169], v[130:133], v[24:27]
	v_mfma_f32_16x16x32_bf16 v[24:27], v[8:11], v[186:189], v[204:207]
	v_mfma_f32_16x16x32_bf16 v[8:11], v[8:11], v[194:197], v[36:39]
	v_mfma_f32_16x16x32_bf16 v[28:31], v[12:15], v[190:193], v[24:27]
	v_mfma_f32_16x16x32_bf16 v[24:27], v[162:165], v[186:189], v[220:223]
	v_mfma_f32_16x16x32_bf16 v[12:15], v[12:15], v[198:201], v[8:11]
	v_mfma_f32_16x16x32_bf16 v[8:11], v[162:165], v[194:197], v[32:35]
	v_mfma_f32_16x16x32_bf16 v[24:27], v[166:169], v[190:193], v[24:27]
	v_mfma_f32_16x16x32_bf16 v[8:11], v[166:169], v[198:201], v[8:11]
	v_mfma_f32_16x16x32_bf16 v[32:35], v[156:159], v[174:177], v[140:143]
	v_mfma_f32_16x16x32_bf16 v[52:55], v[208:211], v[178:181], v[32:35]
	v_mfma_f32_16x16x32_bf16 v[32:35], v[170:173], v[174:177], v[144:147]
	v_mfma_f32_16x16x32_bf16 v[16:19], v[170:173], v[182:185], v[16:19]
	v_mfma_f32_16x16x32_bf16 v[48:51], v[212:215], v[178:181], v[32:35]
	v_mfma_f32_16x16x32_bf16 v[20:23], v[156:159], v[182:185], v[20:23]
	v_mfma_f32_16x16x32_bf16 v[32:35], v[212:215], v[130:133], v[16:19]
	v_mfma_f32_16x16x32_bf16 v[16:19], v[156:159], v[186:189], v[148:151]
	v_mfma_f32_16x16x32_bf16 v[36:39], v[208:211], v[130:133], v[20:23]
	v_mfma_f32_16x16x32_bf16 v[20:23], v[208:211], v[190:193], v[16:19]
	v_mfma_f32_16x16x32_bf16 v[16:19], v[170:173], v[186:189], v[152:155]
	v_mfma_f32_16x16x32_bf16 v[4:7], v[156:159], v[194:197], v[4:7]
	v_mfma_f32_16x16x32_bf16 v[0:3], v[170:173], v[194:197], v[0:3]
	v_mfma_f32_16x16x32_bf16 v[16:19], v[212:215], v[190:193], v[16:19]
	v_mfma_f32_16x16x32_bf16 v[4:7], v[208:211], v[198:201], v[4:7]
	v_mfma_f32_16x16x32_bf16 v[0:3], v[212:215], v[198:201], v[0:3]
	s_andn2_b64 vcc, exec, s[0:1]
	s_barrier
	s_cbranch_vccnz .LBB0_196
	s_barrier

; #define LDA(dst, b, h) for (int m = 0; m < 4; ++m) for (int k = 0; k < 2; ++k) \
;     dst[m][k] = *reinterpret_cast<const bf16x8*>((char*)SA(b, h) + lds_byte(wr * 64 + m * 16 + fr, k * 32 + fq * 8))
; #define LDB(dst, b, h) for (int n = 0; n < 2; ++n) for (int k = 0; k < 2; ++k) \
;     dst[n][k] = *reinterpret_cast<const bf16x8*>((char*)SB(b, h) + lds_byte(wc * 32 + n * 16 + fr, k * 32 + fq * 8))
; #define MMA(ai, bj, At_, Bt_) do { __builtin_amdgcn_s_setprio(1); \
;     for (int m = 0; m < 4; ++m) for (int n = 0; n < 2; ++n) for (int k = 0; k < 2; ++k) \
;       acc[ai][bj][m][n] = MFMA16(Bt_[n][k], At_[m][k], acc[ai][bj][m][n]); \
;     __builtin_amdgcn_s_setprio(0); } while (0)
; #define WAIT_L(n) asm volatile("s_waitcnt lgkmcnt(" #n ")" ::: "memory")
; #define BAR __builtin_amdgcn_s_barrier()
; #define SCHED __builtin_amdgcn_sched_barrier(0)
; template <int PART  , bool SYNC_FIRST = true>
; __device__ __forceinline__ void kloop_t(const u16* __restrict__ A, int lda, const u16* __restrict__ Bt, int ldb, int K, Acc& acc, const int wv) {
;     ...
;   for (int t = 0; t < nt - 2; t += 2) {
;     LDB(B0, 0, 0); SCHED; LDA(At, 0, 0); STAGE(SA(1, 1), A, lda, HALF, t + 1);
;     WAIT_L(8); BAR; WAIT_L(0); MMA(0, 0, At, B0); BAR; SCHED;
;     LDB(B1, 0, 1); STAGE(SB(0, 0), Bt, ldb, 0, t + 2);
;     BAR; WAIT_L(0); MMA(0, 1, At, B1); BAR;
;     LDA(At, 0, 1); STAGE(SA(0, 0), A, lda, 0, t + 2);
.LBB0_318:
	v_add_u32_e32 v164, v156, v160
	v_add_u32_e32 v166, v156, v162
	v_add_u32_e32 v165, v156, v161
	ds_read_b128 v[174:177], v164
	ds_read_b128 v[178:181], v165
	v_add_u32_e32 v167, v156, v163
	ds_read_b128 v[182:185], v166
	ds_read_b128 v[186:189], v167
	s_add_u32 s44, s6, s4
	v_mov_b32_e32 v170, v131
	v_mov_b32_e32 v128, v130
	s_addc_u32 s45, s7, s5
	ds_read_b128 v[190:193], v132
	ds_read_b128 v[194:197], v133
	ds_read_b128 v[198:201], v134
	ds_read_b128 v[202:205], v135
	ds_read_b128 v[206:209], v136
	ds_read_b128 v[210:213], v137
	ds_read_b128 v[214:217], v138
	ds_read_b128 v[218:221], v139
	v_mov_b32_e32 v171, v129
	v_lshl_add_u64 v[168:169], s[44:45], 0, v[128:129]
	v_lshl_add_u64 v[172:173], v[168:169], 0, s[24:25]
	v_add_u32_e32 v168, 0xc000, v142
	v_add_u32_e32 v169, 0xe000, v142
	v_readfirstlane_b32 s52, v168
	s_mov_b32 m0, s52
	v_lshl_add_u64 v[170:171], s[44:45], 0, v[170:171]
	v_readfirstlane_b32 s52, v169
	global_load_lds_dwordx4 v[172:173], off
	v_lshl_add_u64 v[170:171], v[170:171], 0, s[24:25]
	s_mov_b32 m0, s52
	s_nop 0
	global_load_lds_dwordx4 v[170:171], off
	s_waitcnt lgkmcnt(8)
	s_barrier
	s_waitcnt lgkmcnt(0)
	s_waitcnt lgkmcnt(0)
	v_mfma_f32_16x16x32_bf16 v[124:127], v[174:177], v[190:193], v[124:127]
	v_mfma_f32_16x16x32_bf16 v[120:123], v[182:185], v[190:193], v[120:123]
	v_mfma_f32_16x16x32_bf16 v[116:119], v[174:177], v[198:201], v[116:119]
	v_mfma_f32_16x16x32_bf16 v[112:115], v[182:185], v[198:201], v[112:115]
	v_mfma_f32_16x16x32_bf16 v[108:111], v[174:177], v[206:209], v[108:111]
	v_mfma_f32_16x16x32_bf16 v[104:107], v[182:185], v[206:209], v[104:107]
	v_mfma_f32_16x16x32_bf16 v[100:103], v[174:177], v[214:217], v[100:103]
	v_mfma_f32_16x16x32_bf16 v[96:99], v[182:185], v[214:217], v[96:99]
	v_mfma_f32_16x16x32_bf16 v[124:127], v[178:181], v[194:197], v[124:127]
	v_mfma_f32_16x16x32_bf16 v[120:123], v[186:189], v[194:197], v[120:123]
	v_mfma_f32_16x16x32_bf16 v[116:119], v[178:181], v[202:205], v[116:119]
	v_mfma_f32_16x16x32_bf16 v[112:115], v[186:189], v[202:205], v[112:115]
	v_mfma_f32_16x16x32_bf16 v[108:111], v[178:181], v[210:213], v[108:111]
	v_mfma_f32_16x16x32_bf16 v[104:107], v[186:189], v[210:213], v[104:107]
	v_mfma_f32_16x16x32_bf16 v[100:103], v[178:181], v[218:221], v[100:103]
	v_mfma_f32_16x16x32_bf16 v[96:99], v[186:189], v[218:221], v[96:99]
	s_barrier
	s_add_u32 s52, s6, s43
	v_add_u32_e32 v170, v157, v160
	v_add_u32_e32 v172, v157, v162
	v_mov_b32_e32 v238, v131
	v_mov_b32_e32 v128, v130
	s_addc_u32 s53, s7, 0
	v_add_u32_e32 v171, v157, v161
	ds_read_b128 v[222:225], v170
	ds_read_b128 v[226:229], v171
	v_add_u32_e32 v173, v157, v163
	ds_read_b128 v[230:233], v172
	ds_read_b128 v[234:237], v173
	v_readfirstlane_b32 s91, v140
	v_lshl_add_u64 v[240:241], s[52:53], 0, v[128:129]
	v_mov_b32_e32 v239, v129
	v_lshl_add_u64 v[240:241], v[240:241], 0, s[26:27]
	s_mov_b32 m0, s91
	v_lshl_add_u64 v[238:239], s[52:53], 0, v[238:239]
	v_readfirstlane_b32 s91, v141
	global_load_lds_dwordx4 v[240:241], off
	v_lshl_add_u64 v[238:239], v[238:239], 0, s[26:27]
	s_mov_b32 m0, s91
	s_nop 0
	global_load_lds_dwordx4 v[238:239], off
	s_barrier
	s_waitcnt lgkmcnt(0)
	s_waitcnt lgkmcnt(0)
	v_mfma_f32_16x16x32_bf16 v[92:95], v[222:225], v[190:193], v[92:95]
	v_mfma_f32_16x16x32_bf16 v[88:91], v[230:233], v[190:193], v[88:91]
	v_mfma_f32_16x16x32_bf16 v[84:87], v[222:225], v[198:201], v[84:87]
	v_mfma_f32_16x16x32_bf16 v[80:83], v[230:233], v[198:201], v[80:83]
	v_mfma_f32_16x16x32_bf16 v[76:79], v[222:225], v[206:209], v[76:79]
	v_mfma_f32_16x16x32_bf16 v[72:75], v[230:233], v[206:209], v[72:75]
	v_mfma_f32_16x16x32_bf16 v[68:71], v[222:225], v[214:217], v[68:71]
	v_mfma_f32_16x16x32_bf16 v[64:67], v[230:233], v[214:217], v[64:67]
	v_mfma_f32_16x16x32_bf16 v[92:95], v[226:229], v[194:197], v[92:95]
	v_mfma_f32_16x16x32_bf16 v[88:91], v[234:237], v[194:197], v[88:91]
	v_mfma_f32_16x16x32_bf16 v[84:87], v[226:229], v[202:205], v[84:87]
	v_mfma_f32_16x16x32_bf16 v[80:83], v[234:237], v[202:205], v[80:83]
	v_mfma_f32_16x16x32_bf16 v[76:79], v[226:229], v[210:213], v[76:79]
	v_mfma_f32_16x16x32_bf16 v[72:75], v[234:237], v[210:213], v[72:75]
	v_mfma_f32_16x16x32_bf16 v[68:71], v[226:229], v[218:221], v[68:71]
	v_mfma_f32_16x16x32_bf16 v[64:67], v[234:237], v[218:221], v[64:67]
	v_mov_b32_e32 v238, v131
	v_mov_b32_e32 v128, v130
	s_barrier
	ds_read_b128 v[190:193], v132 offset:16384
	ds_read_b128 v[194:197], v133 offset:16384
	ds_read_b128 v[198:201], v134 offset:16384
	ds_read_b128 v[202:205], v135 offset:16384
	ds_read_b128 v[206:209], v136 offset:16384
	ds_read_b128 v[210:213], v137 offset:16384
	ds_read_b128 v[214:217], v138 offset:16384
	ds_read_b128 v[218:221], v139 offset:16384
	v_readfirstlane_b32 s91, v142
	v_lshl_add_u64 v[240:241], s[44:45], 0, v[128:129]
	v_mov_b32_e32 v239, v129
	v_lshl_add_u64 v[240:241], v[240:241], 0, s[28:29]
	s_mov_b32 m0, s91
	v_lshl_add_u64 v[238:239], s[44:45], 0, v[238:239]
	v_readfirstlane_b32 s91, v143
	global_load_lds_dwordx4 v[240:241], off
	v_lshl_add_u64 v[238:239], v[238:239], 0, s[28:29]
	s_mov_b32 m0, s91
	s_nop 0
	global_load_lds_dwordx4 v[238:239], off
	s_barrier
; #define LDA(dst, b, h) for (int m = 0; m < 4; ++m) for (int k = 0; k < 2; ++k) \
;     dst[m][k] = *reinterpret_cast<const bf16x8*>((char*)SA(b, h) + lds_byte(wr * 64 + m * 16 + fr, k * 32 + fq * 8))
; #define LDB(dst, b, h) for (int n = 0; n < 2; ++n) for (int k = 0; k < 2; ++k) \
;     dst[n][k] = *reinterpret_cast<const bf16x8*>((char*)SB(b, h) + lds_byte(wc * 32 + n * 16 + fr, k * 32 + fq * 8))
; #define MMA(ai, bj, At_, Bt_) do { __builtin_amdgcn_s_setprio(1); \
;     for (int m = 0; m < 4; ++m) for (int n = 0; n < 2; ++n) for (int k = 0; k < 2; ++k) \
;       acc[ai][bj][m][n] = MFMA16(Bt_[n][k], At_[m][k], acc[ai][bj][m][n]); \
;     __builtin_amdgcn_s_setprio(0); } while (0)
; #define WAIT_V(n) asm volatile("s_waitcnt vmcnt(" #n ")" ::: "memory")
; #define WAIT_L(n) asm volatile("s_waitcnt lgkmcnt(" #n ")" ::: "memory")
; #define BAR __builtin_amdgcn_s_barrier()
; #define SCHED __builtin_amdgcn_sched_barrier(0)
; template <int PART  , bool SYNC_FIRST = true>
; __device__ __forceinline__ void kloop_t(const u16* __restrict__ A, int lda, const u16* __restrict__ Bt, int ldb, int K, Acc& acc, const int wv) {
;     ...
;     BAR; WAIT_L(0); MMA(1, 0, At, B0); BAR; SCHED;
;     STAGE(SB(0, 1), Bt, ldb, HALF, t + 2);
;     WAIT_V(6); BAR; MMA(1, 1, At, B1); BAR;
;     LDB(B0, 1, 0); SCHED; LDA(At, 1, 0); STAGE(SA(0, 1), A, lda, HALF, t + 2);
;     WAIT_L(8); BAR; WAIT_L(0); MMA(0, 0, At, B0); BAR; SCHED;
;     LDB(B1, 1, 1); STAGE(SB(1, 0), Bt, ldb, 0, t + 3);
	s_waitcnt lgkmcnt(0)
	s_waitcnt lgkmcnt(0)
	v_mfma_f32_16x16x32_bf16 v[60:63], v[174:177], v[190:193], v[60:63]
	v_mfma_f32_16x16x32_bf16 v[56:59], v[182:185], v[190:193], v[56:59]
	v_mfma_f32_16x16x32_bf16 v[52:55], v[174:177], v[198:201], v[52:55]
	v_mfma_f32_16x16x32_bf16 v[48:51], v[182:185], v[198:201], v[48:51]
	v_mfma_f32_16x16x32_bf16 v[44:47], v[174:177], v[206:209], v[44:47]
	v_mfma_f32_16x16x32_bf16 v[40:43], v[182:185], v[206:209], v[40:43]
	v_mfma_f32_16x16x32_bf16 v[36:39], v[174:177], v[214:217], v[36:39]
	v_mfma_f32_16x16x32_bf16 v[32:35], v[182:185], v[214:217], v[32:35]
	v_mfma_f32_16x16x32_bf16 v[60:63], v[178:181], v[194:197], v[60:63]
	v_mfma_f32_16x16x32_bf16 v[56:59], v[186:189], v[194:197], v[56:59]
	v_mfma_f32_16x16x32_bf16 v[52:55], v[178:181], v[202:205], v[52:55]
	v_mfma_f32_16x16x32_bf16 v[48:51], v[186:189], v[202:205], v[48:51]
	v_mfma_f32_16x16x32_bf16 v[44:47], v[178:181], v[210:213], v[44:47]
	v_mfma_f32_16x16x32_bf16 v[40:43], v[186:189], v[210:213], v[40:43]
	v_mfma_f32_16x16x32_bf16 v[36:39], v[178:181], v[218:221], v[36:39]
	v_mfma_f32_16x16x32_bf16 v[32:35], v[186:189], v[218:221], v[32:35]
	s_barrier
	v_mov_b32_e32 v174, v131
	v_mov_b32_e32 v128, v130
	v_readfirstlane_b32 s91, v144
	v_lshl_add_u64 v[176:177], s[52:53], 0, v[128:129]
	v_mov_b32_e32 v175, v129
	v_lshl_add_u64 v[176:177], v[176:177], 0, s[30:31]
	s_mov_b32 m0, s91
	v_lshl_add_u64 v[174:175], s[52:53], 0, v[174:175]
	v_readfirstlane_b32 s91, v145
	global_load_lds_dwordx4 v[176:177], off
	v_lshl_add_u64 v[174:175], v[174:175], 0, s[30:31]
	s_mov_b32 m0, s91
	s_nop 0
	global_load_lds_dwordx4 v[174:175], off
	s_waitcnt vmcnt(6)
	s_barrier
	v_mfma_f32_16x16x32_bf16 v[28:31], v[222:225], v[190:193], v[28:31]
	v_mfma_f32_16x16x32_bf16 v[24:27], v[230:233], v[190:193], v[24:27]
	v_mfma_f32_16x16x32_bf16 v[20:23], v[222:225], v[198:201], v[20:23]
	v_mfma_f32_16x16x32_bf16 v[16:19], v[230:233], v[198:201], v[16:19]
	v_mfma_f32_16x16x32_bf16 v[12:15], v[222:225], v[206:209], v[12:15]
	v_mfma_f32_16x16x32_bf16 v[8:11], v[230:233], v[206:209], v[8:11]
	v_mfma_f32_16x16x32_bf16 v[4:7], v[222:225], v[214:217], v[4:7]
	v_mfma_f32_16x16x32_bf16 v[0:3], v[230:233], v[214:217], v[0:3]
	v_mfma_f32_16x16x32_bf16 v[28:31], v[226:229], v[194:197], v[28:31]
	v_mfma_f32_16x16x32_bf16 v[24:27], v[234:237], v[194:197], v[24:27]
	v_mfma_f32_16x16x32_bf16 v[20:23], v[226:229], v[202:205], v[20:23]
	v_mfma_f32_16x16x32_bf16 v[16:19], v[234:237], v[202:205], v[16:19]
	v_mfma_f32_16x16x32_bf16 v[12:15], v[226:229], v[210:213], v[12:15]
	v_mfma_f32_16x16x32_bf16 v[8:11], v[234:237], v[210:213], v[8:11]
	v_mfma_f32_16x16x32_bf16 v[4:7], v[226:229], v[218:221], v[4:7]
	v_mfma_f32_16x16x32_bf16 v[0:3], v[234:237], v[218:221], v[0:3]
	v_add_u32_e32 v174, v158, v160
	v_add_u32_e32 v176, v158, v162
	s_barrier
	v_add_u32_e32 v175, v158, v161
	ds_read_b128 v[182:185], v174
	ds_read_b128 v[186:189], v175
	v_add_u32_e32 v177, v158, v163
	ds_read_b128 v[190:193], v176
	ds_read_b128 v[194:197], v177
	v_mov_b32_e32 v178, v131
	v_mov_b32_e32 v128, v130
	ds_read_b128 v[198:201], v132 offset:32768
	ds_read_b128 v[202:205], v133 offset:32768
	ds_read_b128 v[206:209], v134 offset:32768
	ds_read_b128 v[210:213], v135 offset:32768
	ds_read_b128 v[214:217], v136 offset:32768
	ds_read_b128 v[218:221], v137 offset:32768
	ds_read_b128 v[222:225], v138 offset:32768
	ds_read_b128 v[226:229], v139 offset:32768
	v_readfirstlane_b32 s91, v148
	v_lshl_add_u64 v[180:181], s[44:45], 0, v[128:129]
	v_mov_b32_e32 v179, v129
	v_lshl_add_u64 v[180:181], v[180:181], 0, s[34:35]
	s_mov_b32 m0, s91
	v_lshl_add_u64 v[178:179], s[44:45], 0, v[178:179]
	v_readfirstlane_b32 s91, v149
	global_load_lds_dwordx4 v[180:181], off
	v_lshl_add_u64 v[178:179], v[178:179], 0, s[34:35]
	s_mov_b32 m0, s91
	s_nop 0
	global_load_lds_dwordx4 v[178:179], off
	s_waitcnt lgkmcnt(8)
	s_barrier
	s_waitcnt lgkmcnt(0)
	s_waitcnt lgkmcnt(0)
	v_mfma_f32_16x16x32_bf16 v[124:127], v[182:185], v[198:201], v[124:127]
	v_mfma_f32_16x16x32_bf16 v[120:123], v[190:193], v[198:201], v[120:123]
	v_mfma_f32_16x16x32_bf16 v[116:119], v[182:185], v[206:209], v[116:119]
	v_mfma_f32_16x16x32_bf16 v[112:115], v[190:193], v[206:209], v[112:115]
	v_mfma_f32_16x16x32_bf16 v[108:111], v[182:185], v[214:217], v[108:111]
	v_mfma_f32_16x16x32_bf16 v[104:107], v[190:193], v[214:217], v[104:107]
	v_mfma_f32_16x16x32_bf16 v[100:103], v[182:185], v[222:225], v[100:103]
	v_mfma_f32_16x16x32_bf16 v[96:99], v[190:193], v[222:225], v[96:99]
	v_mfma_f32_16x16x32_bf16 v[124:127], v[186:189], v[202:205], v[124:127]
	v_mfma_f32_16x16x32_bf16 v[120:123], v[194:197], v[202:205], v[120:123]
	v_mfma_f32_16x16x32_bf16 v[116:119], v[186:189], v[210:213], v[116:119]
	v_mfma_f32_16x16x32_bf16 v[112:115], v[194:197], v[210:213], v[112:115]
	v_mfma_f32_16x16x32_bf16 v[108:111], v[186:189], v[218:221], v[108:111]
	v_mfma_f32_16x16x32_bf16 v[104:107], v[194:197], v[218:221], v[104:107]
	v_mfma_f32_16x16x32_bf16 v[100:103], v[186:189], v[226:229], v[100:103]
	v_mfma_f32_16x16x32_bf16 v[96:99], v[194:197], v[226:229], v[96:99]
	s_barrier
	v_add_u32_e32 v178, v159, v160
	v_add_u32_e32 v180, v159, v162
	v_mov_b32_e32 v246, v131
	v_mov_b32_e32 v128, v130
	v_add_u32_e32 v179, v159, v161
	ds_read_b128 v[230:233], v178
	ds_read_b128 v[234:237], v179
	v_add_u32_e32 v181, v159, v163
	ds_read_b128 v[238:241], v180
	ds_read_b128 v[242:245], v181
	v_readfirstlane_b32 s91, v150
	v_lshl_add_u64 v[248:249], s[52:53], 0, v[128:129]
	v_mov_b32_e32 v247, v129
	v_lshl_add_u64 v[248:249], v[248:249], 0, s[36:37]
	s_mov_b32 m0, s91
	v_lshl_add_u64 v[246:247], s[52:53], 0, v[246:247]
	v_readfirstlane_b32 s91, v151
	global_load_lds_dwordx4 v[248:249], off
	v_lshl_add_u64 v[246:247], v[246:247], 0, s[36:37]
	s_mov_b32 m0, s91
	s_nop 0
	global_load_lds_dwordx4 v[246:247], off
	s_barrier
; #define LDA(dst, b, h) for (int m = 0; m < 4; ++m) for (int k = 0; k < 2; ++k) \
;     dst[m][k] = *reinterpret_cast<const bf16x8*>((char*)SA(b, h) + lds_byte(wr * 64 + m * 16 + fr, k * 32 + fq * 8))
; #define LDB(dst, b, h) for (int n = 0; n < 2; ++n) for (int k = 0; k < 2; ++k) \
;     dst[n][k] = *reinterpret_cast<const bf16x8*>((char*)SB(b, h) + lds_byte(wc * 32 + n * 16 + fr, k * 32 + fq * 8))
; #define MMA(ai, bj, At_, Bt_) do { __builtin_amdgcn_s_setprio(1); \
;     for (int m = 0; m < 4; ++m) for (int n = 0; n < 2; ++n) for (int k = 0; k < 2; ++k) \
;       acc[ai][bj][m][n] = MFMA16(Bt_[n][k], At_[m][k], acc[ai][bj][m][n]); \
;     __builtin_amdgcn_s_setprio(0); } while (0)
; #define WAIT_V(n) asm volatile("s_waitcnt vmcnt(" #n ")" ::: "memory")
; #define WAIT_L(n) asm volatile("s_waitcnt lgkmcnt(" #n ")" ::: "memory")
; #define BAR __builtin_amdgcn_s_barrier()
; #define SCHED __builtin_amdgcn_sched_barrier(0)
; template <int PART  , bool SYNC_FIRST = true>
; __device__ __forceinline__ void kloop_t(const u16* __restrict__ A, int lda, const u16* __restrict__ Bt, int ldb, int K, Acc& acc, const int wv) {
;     ...
;     BAR; WAIT_L(0); MMA(0, 1, At, B1); BAR;
;     LDA(At, 1, 1); STAGE(SA(1, 0), A, lda, 0, t + 3);
;     BAR; WAIT_L(0); MMA(1, 0, At, B0); BAR; SCHED;
;     STAGE(SB(1, 1), Bt, ldb, HALF, t + 3);
;     WAIT_V(6); BAR; MMA(1, 1, At, B1); BAR;
;   }
;   { LDB(B0, 0, 0); LDA(At, 0, 0); STAGE(SA(1, 1), A, lda, HALF, nt - 1);
	s_waitcnt lgkmcnt(0)
	s_waitcnt lgkmcnt(0)
	v_mfma_f32_16x16x32_bf16 v[92:95], v[230:233], v[198:201], v[92:95]
	v_mfma_f32_16x16x32_bf16 v[88:91], v[238:241], v[198:201], v[88:91]
	v_mfma_f32_16x16x32_bf16 v[84:87], v[230:233], v[206:209], v[84:87]
	v_mfma_f32_16x16x32_bf16 v[80:83], v[238:241], v[206:209], v[80:83]
	v_mfma_f32_16x16x32_bf16 v[76:79], v[230:233], v[214:217], v[76:79]
	v_mfma_f32_16x16x32_bf16 v[72:75], v[238:241], v[214:217], v[72:75]
	v_mfma_f32_16x16x32_bf16 v[68:71], v[230:233], v[222:225], v[68:71]
	v_mfma_f32_16x16x32_bf16 v[64:67], v[238:241], v[222:225], v[64:67]
	v_mfma_f32_16x16x32_bf16 v[92:95], v[234:237], v[202:205], v[92:95]
	v_mfma_f32_16x16x32_bf16 v[88:91], v[242:245], v[202:205], v[88:91]
	v_mfma_f32_16x16x32_bf16 v[84:87], v[234:237], v[210:213], v[84:87]
	v_mfma_f32_16x16x32_bf16 v[80:83], v[242:245], v[210:213], v[80:83]
	v_mfma_f32_16x16x32_bf16 v[76:79], v[234:237], v[218:221], v[76:79]
	v_mfma_f32_16x16x32_bf16 v[72:75], v[242:245], v[218:221], v[72:75]
	v_mfma_f32_16x16x32_bf16 v[68:71], v[234:237], v[226:229], v[68:71]
	v_mfma_f32_16x16x32_bf16 v[64:67], v[242:245], v[226:229], v[64:67]
	v_mov_b32_e32 v246, v131
	v_mov_b32_e32 v128, v130
	s_barrier
	ds_read_b128 v[198:201], v132 offset:49152
	ds_read_b128 v[202:205], v133 offset:49152
	ds_read_b128 v[206:209], v134 offset:49152
	ds_read_b128 v[210:213], v135 offset:49152
	ds_read_b128 v[214:217], v136 offset:49152
	ds_read_b128 v[218:221], v137 offset:49152
	ds_read_b128 v[222:225], v138 offset:49152
	ds_read_b128 v[226:229], v139 offset:49152
	v_readfirstlane_b32 s91, v152
	v_lshl_add_u64 v[248:249], s[44:45], 0, v[128:129]
	v_mov_b32_e32 v247, v129
	v_lshl_add_u64 v[248:249], v[248:249], 0, s[38:39]
	s_mov_b32 m0, s91
	v_lshl_add_u64 v[246:247], s[44:45], 0, v[246:247]
	v_readfirstlane_b32 s44, v153
	global_load_lds_dwordx4 v[248:249], off
	v_lshl_add_u64 v[246:247], v[246:247], 0, s[38:39]
	s_mov_b32 m0, s44
	s_nop 0
	global_load_lds_dwordx4 v[246:247], off
	s_barrier
	s_waitcnt lgkmcnt(0)
	s_waitcnt lgkmcnt(0)
	v_mfma_f32_16x16x32_bf16 v[60:63], v[182:185], v[198:201], v[60:63]
	v_mfma_f32_16x16x32_bf16 v[56:59], v[190:193], v[198:201], v[56:59]
	v_mfma_f32_16x16x32_bf16 v[52:55], v[182:185], v[206:209], v[52:55]
	v_mfma_f32_16x16x32_bf16 v[48:51], v[190:193], v[206:209], v[48:51]
	v_mfma_f32_16x16x32_bf16 v[44:47], v[182:185], v[214:217], v[44:47]
	v_mfma_f32_16x16x32_bf16 v[40:43], v[190:193], v[214:217], v[40:43]
	v_mfma_f32_16x16x32_bf16 v[36:39], v[182:185], v[222:225], v[36:39]
	v_mfma_f32_16x16x32_bf16 v[32:35], v[190:193], v[222:225], v[32:35]
	v_mfma_f32_16x16x32_bf16 v[60:63], v[186:189], v[202:205], v[60:63]
	v_mfma_f32_16x16x32_bf16 v[56:59], v[194:197], v[202:205], v[56:59]
	v_mfma_f32_16x16x32_bf16 v[52:55], v[186:189], v[210:213], v[52:55]
	v_mfma_f32_16x16x32_bf16 v[48:51], v[194:197], v[210:213], v[48:51]
	v_mfma_f32_16x16x32_bf16 v[44:47], v[186:189], v[218:221], v[44:47]
	v_mfma_f32_16x16x32_bf16 v[40:43], v[194:197], v[218:221], v[40:43]
	v_mfma_f32_16x16x32_bf16 v[36:39], v[186:189], v[226:229], v[36:39]
	v_mfma_f32_16x16x32_bf16 v[32:35], v[194:197], v[226:229], v[32:35]
	s_barrier
	v_mov_b32_e32 v182, v131
	v_mov_b32_e32 v128, v130
	v_readfirstlane_b32 s44, v154
	v_lshl_add_u64 v[184:185], s[52:53], 0, v[128:129]
	v_mov_b32_e32 v183, v129
	v_lshl_add_u64 v[184:185], v[184:185], 0, s[40:41]
	s_mov_b32 m0, s44
	v_lshl_add_u64 v[182:183], s[52:53], 0, v[182:183]
	v_readfirstlane_b32 s44, v155
	global_load_lds_dwordx4 v[184:185], off
	v_lshl_add_u64 v[182:183], v[182:183], 0, s[40:41]
	s_mov_b32 m0, s44
	s_nop 0
	global_load_lds_dwordx4 v[182:183], off
	s_waitcnt vmcnt(6)
	s_barrier
	v_mfma_f32_16x16x32_bf16 v[28:31], v[230:233], v[198:201], v[28:31]
	v_mfma_f32_16x16x32_bf16 v[24:27], v[238:241], v[198:201], v[24:27]
	v_mfma_f32_16x16x32_bf16 v[20:23], v[230:233], v[206:209], v[20:23]
	v_mfma_f32_16x16x32_bf16 v[16:19], v[238:241], v[206:209], v[16:19]
	v_mfma_f32_16x16x32_bf16 v[12:15], v[230:233], v[214:217], v[12:15]
	v_mfma_f32_16x16x32_bf16 v[8:11], v[238:241], v[214:217], v[8:11]
	v_mfma_f32_16x16x32_bf16 v[4:7], v[230:233], v[222:225], v[4:7]
	v_mfma_f32_16x16x32_bf16 v[0:3], v[238:241], v[222:225], v[0:3]
	v_mfma_f32_16x16x32_bf16 v[28:31], v[234:237], v[202:205], v[28:31]
	v_mfma_f32_16x16x32_bf16 v[24:27], v[242:245], v[202:205], v[24:27]
	v_mfma_f32_16x16x32_bf16 v[20:23], v[234:237], v[210:213], v[20:23]
	v_mfma_f32_16x16x32_bf16 v[16:19], v[242:245], v[210:213], v[16:19]
	v_mfma_f32_16x16x32_bf16 v[12:15], v[234:237], v[218:221], v[12:15]
	v_mfma_f32_16x16x32_bf16 v[8:11], v[242:245], v[218:221], v[8:11]
	v_mfma_f32_16x16x32_bf16 v[4:7], v[234:237], v[226:229], v[4:7]
	v_mfma_f32_16x16x32_bf16 v[0:3], v[242:245], v[226:229], v[0:3]
	s_add_i32 s90, s90, 2
	s_add_u32 s6, s6, 0x100
	s_addc_u32 s7, s7, 0
	s_cmp_lt_u32 s90, 12
	s_barrier
	s_cbranch_scc1 .LBB0_318
	s_add_u32 s0, s0, 0x40780
	v_readfirstlane_b32 s4, v168
	s_addc_u32 s1, s1, 0
	s_mov_b32 m0, s4
	v_readfirstlane_b32 s4, v169
	ds_read_b128 v[140:143], v164
	ds_read_b128 v[148:151], v165
	ds_read_b128 v[152:155], v166
	ds_read_b128 v[156:159], v167
	ds_read_b128 v[160:163], v132
	ds_read_b128 v[164:167], v133
	ds_read_b128 v[182:185], v134
	ds_read_b128 v[186:189], v135
	ds_read_b128 v[190:193], v136
	ds_read_b128 v[194:197], v137
	ds_read_b128 v[198:201], v138
	ds_read_b128 v[202:205], v139
	s_nop 0
	global_load_lds_dwordx4 v130, s[0:1]
	s_mov_b32 m0, s4
	s_nop 0
	global_load_lds_dwordx4 v131, s[0:1]
	s_barrier
; #define LDA(dst, b, h) for (int m = 0; m < 4; ++m) for (int k = 0; k < 2; ++k) \
;     dst[m][k] = *reinterpret_cast<const bf16x8*>((char*)SA(b, h) + lds_byte(wr * 64 + m * 16 + fr, k * 32 + fq * 8))
; #define LDB(dst, b, h) for (int n = 0; n < 2; ++n) for (int k = 0; k < 2; ++k) \
;     dst[n][k] = *reinterpret_cast<const bf16x8*>((char*)SB(b, h) + lds_byte(wc * 32 + n * 16 + fr, k * 32 + fq * 8))
; #define MMA(ai, bj, At_, Bt_) do { __builtin_amdgcn_s_setprio(1); \
;     for (int m = 0; m < 4; ++m) for (int n = 0; n < 2; ++n) for (int k = 0; k < 2; ++k) \
;       acc[ai][bj][m][n] = MFMA16(Bt_[n][k], At_[m][k], acc[ai][bj][m][n]); \
;     __builtin_amdgcn_s_setprio(0); } while (0)
; #define WAIT_V(n) asm volatile("s_waitcnt vmcnt(" #n ")" ::: "memory")
; #define WAIT_L(n) asm volatile("s_waitcnt lgkmcnt(" #n ")" ::: "memory")
; #define BAR __builtin_amdgcn_s_barrier()
; template <int PART  , bool SYNC_FIRST = true>
; __device__ __forceinline__ void kloop_t(const u16* __restrict__ A, int lda, const u16* __restrict__ Bt, int ldb, int K, Acc& acc, const int wv) {
;     ...
;   { LDB(B0, 0, 0); LDA(At, 0, 0); STAGE(SA(1, 1), A, lda, HALF, nt - 1);
;     BAR; WAIT_L(0); MMA(0, 0, At, B0); BAR;
;     LDB(B1, 0, 1); BAR; WAIT_L(0); MMA(0, 1, At, B1); BAR;
;     LDA(At, 0, 1); WAIT_V(4); BAR; WAIT_L(0); MMA(1, 0, At, B0); MMA(1, 1, At, B1); BAR; }
	s_waitcnt lgkmcnt(0)
	s_waitcnt lgkmcnt(0)
	v_mfma_f32_16x16x32_bf16 v[124:127], v[140:143], v[160:163], v[124:127]
	v_mfma_f32_16x16x32_bf16 v[120:123], v[152:155], v[160:163], v[120:123]
	v_mfma_f32_16x16x32_bf16 v[116:119], v[140:143], v[182:185], v[116:119]
	v_mfma_f32_16x16x32_bf16 v[112:115], v[152:155], v[182:185], v[112:115]
	v_mfma_f32_16x16x32_bf16 v[100:103], v[140:143], v[198:201], v[100:103]
	v_mfma_f32_16x16x32_bf16 v[96:99], v[152:155], v[198:201], v[96:99]
	v_mfma_f32_16x16x32_bf16 v[124:127], v[148:151], v[164:167], v[124:127]
	v_mfma_f32_16x16x32_bf16 v[120:123], v[156:159], v[164:167], v[120:123]
	v_mfma_f32_16x16x32_bf16 v[116:119], v[148:151], v[186:189], v[116:119]
	v_mfma_f32_16x16x32_bf16 v[112:115], v[156:159], v[186:189], v[112:115]
	v_mfma_f32_16x16x32_bf16 v[108:111], v[140:143], v[190:193], v[108:111]
	v_mfma_f32_16x16x32_bf16 v[104:107], v[152:155], v[190:193], v[104:107]
	v_mfma_f32_16x16x32_bf16 v[100:103], v[148:151], v[202:205], v[100:103]
	v_mfma_f32_16x16x32_bf16 v[96:99], v[156:159], v[202:205], v[96:99]
	v_mfma_f32_16x16x32_bf16 v[206:209], v[148:151], v[194:197], v[108:111]
	v_mfma_f32_16x16x32_bf16 v[210:213], v[156:159], v[194:197], v[104:107]
	s_barrier
	s_nop 1
	ds_read_b128 v[104:107], v170
	ds_read_b128 v[108:111], v171
	ds_read_b128 v[168:171], v172
	ds_read_b128 v[214:217], v173
	s_barrier
	s_waitcnt lgkmcnt(0)
	s_waitcnt lgkmcnt(0)
	v_mfma_f32_16x16x32_bf16 v[84:87], v[104:107], v[182:185], v[84:87]
	v_mfma_f32_16x16x32_bf16 v[80:83], v[168:171], v[182:185], v[80:83]
	v_mfma_f32_16x16x32_bf16 v[68:71], v[104:107], v[198:201], v[68:71]
	v_mfma_f32_16x16x32_bf16 v[64:67], v[168:171], v[198:201], v[64:67]
	v_mfma_f32_16x16x32_bf16 v[92:95], v[104:107], v[160:163], v[92:95]
	v_mfma_f32_16x16x32_bf16 v[88:91], v[168:171], v[160:163], v[88:91]
	v_mfma_f32_16x16x32_bf16 v[84:87], v[108:111], v[186:189], v[84:87]
	v_mfma_f32_16x16x32_bf16 v[80:83], v[214:217], v[186:189], v[80:83]
	v_mfma_f32_16x16x32_bf16 v[76:79], v[104:107], v[190:193], v[76:79]
	v_mfma_f32_16x16x32_bf16 v[72:75], v[168:171], v[190:193], v[72:75]
	v_mfma_f32_16x16x32_bf16 v[68:71], v[108:111], v[202:205], v[68:71]
	v_mfma_f32_16x16x32_bf16 v[64:67], v[214:217], v[202:205], v[64:67]
	v_mfma_f32_16x16x32_bf16 v[218:221], v[108:111], v[164:167], v[92:95]
	v_mfma_f32_16x16x32_bf16 v[160:163], v[214:217], v[164:167], v[88:91]
	v_mfma_f32_16x16x32_bf16 v[164:167], v[108:111], v[194:197], v[76:79]
	v_mfma_f32_16x16x32_bf16 v[182:185], v[214:217], v[194:197], v[72:75]
	s_barrier
	s_nop 0
	ds_read_b128 v[72:75], v132 offset:16384
	ds_read_b128 v[76:79], v133 offset:16384
	ds_read_b128 v[88:91], v134 offset:16384
	ds_read_b128 v[92:95], v135 offset:16384
	ds_read_b128 v[186:189], v136 offset:16384
	ds_read_b128 v[190:193], v137 offset:16384
	ds_read_b128 v[194:197], v138 offset:16384
	ds_read_b128 v[198:201], v139 offset:16384
	s_waitcnt vmcnt(4)
	s_barrier
	s_waitcnt lgkmcnt(0)
	s_waitcnt lgkmcnt(0)
	v_mfma_f32_16x16x32_bf16 v[60:63], v[140:143], v[72:75], v[60:63]
	v_mfma_f32_16x16x32_bf16 v[56:59], v[152:155], v[72:75], v[56:59]
	v_mfma_f32_16x16x32_bf16 v[52:55], v[140:143], v[88:91], v[52:55]
	v_mfma_f32_16x16x32_bf16 v[48:51], v[152:155], v[88:91], v[48:51]
	v_mfma_f32_16x16x32_bf16 v[36:39], v[140:143], v[194:197], v[36:39]
	v_mfma_f32_16x16x32_bf16 v[32:35], v[152:155], v[194:197], v[32:35]
	v_mfma_f32_16x16x32_bf16 v[60:63], v[148:151], v[76:79], v[60:63]
	v_mfma_f32_16x16x32_bf16 v[56:59], v[156:159], v[76:79], v[56:59]
	v_mfma_f32_16x16x32_bf16 v[52:55], v[148:151], v[92:95], v[52:55]
	v_mfma_f32_16x16x32_bf16 v[48:51], v[156:159], v[92:95], v[48:51]
	v_mfma_f32_16x16x32_bf16 v[44:47], v[140:143], v[186:189], v[44:47]
	v_mfma_f32_16x16x32_bf16 v[40:43], v[152:155], v[186:189], v[40:43]
	v_mfma_f32_16x16x32_bf16 v[36:39], v[148:151], v[198:201], v[36:39]
	v_mfma_f32_16x16x32_bf16 v[32:35], v[156:159], v[198:201], v[32:35]
	v_mfma_f32_16x16x32_bf16 v[202:205], v[148:151], v[190:193], v[44:47]
	v_mfma_f32_16x16x32_bf16 v[222:225], v[156:159], v[190:193], v[40:43]
	v_mfma_f32_16x16x32_bf16 v[20:23], v[104:107], v[88:91], v[20:23]
	v_mfma_f32_16x16x32_bf16 v[16:19], v[168:171], v[88:91], v[16:19]
	v_mfma_f32_16x16x32_bf16 v[4:7], v[104:107], v[194:197], v[4:7]
	v_mfma_f32_16x16x32_bf16 v[0:3], v[168:171], v[194:197], v[0:3]
	v_mfma_f32_16x16x32_bf16 v[28:31], v[104:107], v[72:75], v[28:31]
	v_mfma_f32_16x16x32_bf16 v[24:27], v[168:171], v[72:75], v[24:27]
	v_mfma_f32_16x16x32_bf16 v[20:23], v[108:111], v[92:95], v[20:23]
	v_mfma_f32_16x16x32_bf16 v[16:19], v[214:217], v[92:95], v[16:19]
	v_mfma_f32_16x16x32_bf16 v[12:15], v[104:107], v[186:189], v[12:15]
	v_mfma_f32_16x16x32_bf16 v[8:11], v[168:171], v[186:189], v[8:11]
	v_mfma_f32_16x16x32_bf16 v[4:7], v[108:111], v[198:201], v[4:7]
	v_mfma_f32_16x16x32_bf16 v[0:3], v[214:217], v[198:201], v[0:3]
	v_mfma_f32_16x16x32_bf16 v[140:143], v[108:111], v[76:79], v[28:31]
	v_mfma_f32_16x16x32_bf16 v[148:151], v[214:217], v[76:79], v[24:27]
	v_mfma_f32_16x16x32_bf16 v[152:155], v[108:111], v[190:193], v[12:15]
	v_mfma_f32_16x16x32_bf16 v[156:159], v[214:217], v[190:193], v[8:11]
	s_barrier
; #define LDA(dst, b, h) for (int m = 0; m < 4; ++m) for (int k = 0; k < 2; ++k) \
;     dst[m][k] = *reinterpret_cast<const bf16x8*>((char*)SA(b, h) + lds_byte(wr * 64 + m * 16 + fr, k * 32 + fq * 8))
; #define LDB(dst, b, h) for (int n = 0; n < 2; ++n) for (int k = 0; k < 2; ++k) \
;     dst[n][k] = *reinterpret_cast<const bf16x8*>((char*)SB(b, h) + lds_byte(wc * 32 + n * 16 + fr, k * 32 + fq * 8))
; #define MMA(ai, bj, At_, Bt_) do { __builtin_amdgcn_s_setprio(1); \
;     for (int m = 0; m < 4; ++m) for (int n = 0; n < 2; ++n) for (int k = 0; k < 2; ++k) \
;       acc[ai][bj][m][n] = MFMA16(Bt_[n][k], At_[m][k], acc[ai][bj][m][n]); \
;     __builtin_amdgcn_s_setprio(0); } while (0)
; #define WAIT_V(n) asm volatile("s_waitcnt vmcnt(" #n ")" ::: "memory")
; #define WAIT_L(n) asm volatile("s_waitcnt lgkmcnt(" #n ")" ::: "memory")
; #define BAR __builtin_amdgcn_s_barrier()
; template <int PART  , bool SYNC_FIRST = true>
; __device__ __forceinline__ void kloop_t(const u16* __restrict__ A, int lda, const u16* __restrict__ Bt, int ldb, int K, Acc& acc, const int wv) {
;     ...
;   { LDB(B0, 1, 0); LDA(At, 1, 0); WAIT_V(2); BAR; WAIT_L(0); MMA(0, 0, At, B0); BAR;
;     LDB(B1, 1, 1); WAIT_V(0); BAR; WAIT_L(0); MMA(0, 1, At, B1); BAR;
;     LDA(At, 1, 1); BAR; WAIT_L(0); MMA(1, 0, At, B0); MMA(1, 1, At, B1); BAR; }
;   if (wr == 0) BAR;
	s_nop 0
	ds_read_b128 v[8:11], v174
	ds_read_b128 v[12:15], v175
	ds_read_b128 v[168:171], v176
	ds_read_b128 v[172:175], v177
	ds_read_b128 v[24:27], v132 offset:32768
	ds_read_b128 v[28:31], v133 offset:32768
	ds_read_b128 v[40:43], v134 offset:32768
	ds_read_b128 v[44:47], v135 offset:32768
	ds_read_b128 v[186:189], v136 offset:32768
	ds_read_b128 v[190:193], v137 offset:32768
	ds_read_b128 v[194:197], v138 offset:32768
	ds_read_b128 v[198:201], v139 offset:32768
	s_waitcnt vmcnt(2)
	s_barrier
	s_waitcnt lgkmcnt(0)
	s_waitcnt lgkmcnt(0)
	v_mfma_f32_16x16x32_bf16 v[72:75], v[8:11], v[24:27], v[124:127]
	v_mfma_f32_16x16x32_bf16 v[124:127], v[12:15], v[28:31], v[72:75]
	v_mfma_f32_16x16x32_bf16 v[72:75], v[168:171], v[24:27], v[120:123]
	v_mfma_f32_16x16x32_bf16 v[120:123], v[172:175], v[28:31], v[72:75]
	v_mfma_f32_16x16x32_bf16 v[72:75], v[8:11], v[40:43], v[116:119]
	v_mfma_f32_16x16x32_bf16 v[108:111], v[12:15], v[44:47], v[72:75]
	v_mfma_f32_16x16x32_bf16 v[72:75], v[168:171], v[40:43], v[112:115]
	v_mfma_f32_16x16x32_bf16 v[104:107], v[172:175], v[44:47], v[72:75]
	v_mfma_f32_16x16x32_bf16 v[72:75], v[8:11], v[186:189], v[206:209]
	v_mfma_f32_16x16x32_bf16 v[92:95], v[12:15], v[190:193], v[72:75]
	v_mfma_f32_16x16x32_bf16 v[72:75], v[168:171], v[186:189], v[210:213]
	v_mfma_f32_16x16x32_bf16 v[88:91], v[172:175], v[190:193], v[72:75]
	v_mfma_f32_16x16x32_bf16 v[72:75], v[8:11], v[194:197], v[100:103]
	v_mfma_f32_16x16x32_bf16 v[76:79], v[12:15], v[198:201], v[72:75]
	v_mfma_f32_16x16x32_bf16 v[72:75], v[168:171], v[194:197], v[96:99]
	v_mfma_f32_16x16x32_bf16 v[72:75], v[172:175], v[198:201], v[72:75]
	s_barrier
	ds_read_b128 v[206:209], v178
	ds_read_b128 v[176:179], v179
	ds_read_b128 v[210:213], v180
	ds_read_b128 v[214:217], v181
	s_waitcnt vmcnt(0)
	s_barrier
	s_waitcnt lgkmcnt(0)
	s_waitcnt lgkmcnt(0)
	v_mfma_f32_16x16x32_bf16 v[96:99], v[206:209], v[24:27], v[218:221]
	v_mfma_f32_16x16x32_bf16 v[24:27], v[210:213], v[24:27], v[160:163]
	v_mfma_f32_16x16x32_bf16 v[112:115], v[214:217], v[28:31], v[24:27]
	v_mfma_f32_16x16x32_bf16 v[24:27], v[206:209], v[40:43], v[84:87]
	v_mfma_f32_16x16x32_bf16 v[100:103], v[176:179], v[44:47], v[24:27]
	v_mfma_f32_16x16x32_bf16 v[24:27], v[210:213], v[40:43], v[80:83]
	v_mfma_f32_16x16x32_bf16 v[116:119], v[176:179], v[28:31], v[96:99]
	v_mfma_f32_16x16x32_bf16 v[96:99], v[214:217], v[44:47], v[24:27]
	v_mfma_f32_16x16x32_bf16 v[24:27], v[206:209], v[186:189], v[164:167]
	v_mfma_f32_16x16x32_bf16 v[84:87], v[176:179], v[190:193], v[24:27]
	v_mfma_f32_16x16x32_bf16 v[24:27], v[210:213], v[186:189], v[182:185]
	v_mfma_f32_16x16x32_bf16 v[80:83], v[214:217], v[190:193], v[24:27]
	v_mfma_f32_16x16x32_bf16 v[24:27], v[206:209], v[194:197], v[68:71]
	v_mfma_f32_16x16x32_bf16 v[68:71], v[176:179], v[198:201], v[24:27]
	v_mfma_f32_16x16x32_bf16 v[24:27], v[210:213], v[194:197], v[64:67]
	v_mfma_f32_16x16x32_bf16 v[64:67], v[214:217], v[198:201], v[24:27]
	s_barrier
	ds_read_b128 v[160:163], v132 offset:49152
	ds_read_b128 v[130:133], v133 offset:49152
	ds_read_b128 v[164:167], v134 offset:49152
	ds_read_b128 v[180:183], v135 offset:49152
	ds_read_b128 v[184:187], v136 offset:49152
	ds_read_b128 v[134:137], v137 offset:49152
	ds_read_b128 v[188:191], v138 offset:49152
	ds_read_b128 v[192:195], v139 offset:49152
	s_barrier
	s_waitcnt lgkmcnt(0)
	s_waitcnt lgkmcnt(0)
	v_mfma_f32_16x16x32_bf16 v[24:27], v[8:11], v[160:163], v[60:63]
	v_mfma_f32_16x16x32_bf16 v[60:63], v[12:15], v[130:133], v[24:27]
	v_mfma_f32_16x16x32_bf16 v[24:27], v[168:171], v[160:163], v[56:59]
	v_mfma_f32_16x16x32_bf16 v[56:59], v[172:175], v[130:133], v[24:27]
	v_mfma_f32_16x16x32_bf16 v[24:27], v[8:11], v[164:167], v[52:55]
	v_mfma_f32_16x16x32_bf16 v[44:47], v[12:15], v[180:183], v[24:27]
	v_mfma_f32_16x16x32_bf16 v[24:27], v[168:171], v[164:167], v[48:51]
	v_mfma_f32_16x16x32_bf16 v[40:43], v[172:175], v[180:183], v[24:27]
	v_mfma_f32_16x16x32_bf16 v[24:27], v[8:11], v[184:187], v[202:205]
	v_mfma_f32_16x16x32_bf16 v[8:11], v[8:11], v[188:191], v[36:39]
	v_mfma_f32_16x16x32_bf16 v[28:31], v[12:15], v[134:137], v[24:27]
	v_mfma_f32_16x16x32_bf16 v[24:27], v[168:171], v[184:187], v[222:225]
	v_mfma_f32_16x16x32_bf16 v[12:15], v[12:15], v[192:195], v[8:11]
	v_mfma_f32_16x16x32_bf16 v[8:11], v[168:171], v[188:191], v[32:35]
	v_mfma_f32_16x16x32_bf16 v[24:27], v[172:175], v[134:137], v[24:27]
	v_mfma_f32_16x16x32_bf16 v[8:11], v[172:175], v[192:195], v[8:11]
	v_mfma_f32_16x16x32_bf16 v[32:35], v[206:209], v[160:163], v[140:143]
	v_mfma_f32_16x16x32_bf16 v[52:55], v[176:179], v[130:133], v[32:35]
	v_mfma_f32_16x16x32_bf16 v[32:35], v[210:213], v[160:163], v[148:151]
	v_mfma_f32_16x16x32_bf16 v[16:19], v[210:213], v[164:167], v[16:19]
	v_mfma_f32_16x16x32_bf16 v[48:51], v[214:217], v[130:133], v[32:35]
	v_mfma_f32_16x16x32_bf16 v[20:23], v[206:209], v[164:167], v[20:23]
	v_mfma_f32_16x16x32_bf16 v[32:35], v[214:217], v[180:183], v[16:19]
	v_mfma_f32_16x16x32_bf16 v[16:19], v[206:209], v[184:187], v[152:155]
	v_mfma_f32_16x16x32_bf16 v[36:39], v[176:179], v[180:183], v[20:23]
	v_mfma_f32_16x16x32_bf16 v[20:23], v[176:179], v[134:137], v[16:19]
	v_mfma_f32_16x16x32_bf16 v[16:19], v[210:213], v[184:187], v[156:159]
	v_mfma_f32_16x16x32_bf16 v[4:7], v[206:209], v[188:191], v[4:7]
	v_mfma_f32_16x16x32_bf16 v[0:3], v[210:213], v[188:191], v[0:3]
	v_mfma_f32_16x16x32_bf16 v[16:19], v[214:217], v[134:137], v[16:19]
	v_mfma_f32_16x16x32_bf16 v[4:7], v[176:179], v[192:195], v[4:7]
	v_mfma_f32_16x16x32_bf16 v[0:3], v[214:217], v[192:195], v[0:3]
	s_andn2_b64 vcc, exec, s[12:13]
	s_barrier
	s_cbranch_vccnz .LBB0_321
	s_barrier

; #define LDA(dst, b, h) for (int m = 0; m < 4; ++m) for (int k = 0; k < 2; ++k) \
;     dst[m][k] = *reinterpret_cast<const bf16x8*>((char*)SA(b, h) + lds_byte(wr * 64 + m * 16 + fr, k * 32 + fq * 8))
; #define LDB(dst, b, h) for (int n = 0; n < 2; ++n) for (int k = 0; k < 2; ++k) \
;     dst[n][k] = *reinterpret_cast<const bf16x8*>((char*)SB(b, h) + lds_byte(wc * 32 + n * 16 + fr, k * 32 + fq * 8))
; #define MMA(ai, bj, At_, Bt_) do { __builtin_amdgcn_s_setprio(1); \
;     for (int m = 0; m < 4; ++m) for (int n = 0; n < 2; ++n) for (int k = 0; k < 2; ++k) \
;       acc[ai][bj][m][n] = MFMA16(Bt_[n][k], At_[m][k], acc[ai][bj][m][n]); \
;     __builtin_amdgcn_s_setprio(0); } while (0)
; #define WAIT_L(n) asm volatile("s_waitcnt lgkmcnt(" #n ")" ::: "memory")
; #define BAR __builtin_amdgcn_s_barrier()
; #define SCHED __builtin_amdgcn_sched_barrier(0)
; template <int PART  , bool SYNC_FIRST = true>
; __device__ __forceinline__ void kloop_t(const u16* __restrict__ A, int lda, const u16* __restrict__ Bt, int ldb, int K, Acc& acc, const int wv) {
;     ...
;   for (int t = 0; t < nt - 2; t += 2) {
;     LDB(B0, 0, 0); SCHED; LDA(At, 0, 0); STAGE(SA(1, 1), A, lda, HALF, t + 1);
;     WAIT_L(8); BAR; WAIT_L(0); MMA(0, 0, At, B0); BAR; SCHED;
;     LDB(B1, 0, 1); STAGE(SB(0, 0), Bt, ldb, 0, t + 2);
;     BAR; WAIT_L(0); MMA(0, 1, At, B1); BAR;
;     LDA(At, 0, 1); STAGE(SA(0, 0), A, lda, 0, t + 2);
.LBB0_704:
	v_add_u32_e32 v156, v148, v152
	v_add_u32_e32 v158, v148, v154
	v_add_u32_e32 v157, v148, v153
	ds_read_b128 v[166:169], v156
	ds_read_b128 v[170:173], v157
	v_add_u32_e32 v159, v148, v155
	ds_read_b128 v[174:177], v158
	ds_read_b128 v[178:181], v159
	s_add_u32 s58, s18, s56
	v_mov_b32_e32 v0, v130
	v_mov_b32_e32 v162, v132
	s_addc_u32 s59, vcc_lo, s57
	ds_read_b128 v[182:185], v134
	ds_read_b128 v[188:191], v135
	ds_read_b128 v[192:195], v136
	ds_read_b128 v[196:199], v137
	ds_read_b128 v[200:203], v138
	ds_read_b128 v[204:207], v139
	ds_read_b128 v[208:211], v140
	ds_read_b128 v[212:215], v141
	v_mov_b32_e32 v163, v1
	v_lshl_add_u64 v[160:161], s[58:59], 0, v[0:1]
	v_lshl_add_u64 v[164:165], v[160:161], 0, s[20:21]
	v_add_u32_e32 v160, 0xc000, v143
	v_add_u32_e32 v161, 0xe000, v143
	v_readfirstlane_b32 s60, v160
	s_mov_b32 m0, s60
	v_lshl_add_u64 v[162:163], s[58:59], 0, v[162:163]
	v_readfirstlane_b32 s60, v161
	global_load_lds_dwordx4 v[164:165], off
	v_lshl_add_u64 v[162:163], v[162:163], 0, s[20:21]
	s_mov_b32 m0, s60
	s_nop 0
	global_load_lds_dwordx4 v[162:163], off
	s_waitcnt lgkmcnt(8)
	s_barrier
	s_waitcnt lgkmcnt(0)
	s_waitcnt lgkmcnt(0)
	v_mfma_f32_16x16x32_bf16 v[30:33], v[166:169], v[182:185], v[30:33]
	v_mfma_f32_16x16x32_bf16 v[38:41], v[174:177], v[182:185], v[38:41]
	v_mfma_f32_16x16x32_bf16 v[70:73], v[166:169], v[192:195], v[70:73]
	v_mfma_f32_16x16x32_bf16 v[78:81], v[174:177], v[192:195], v[78:81]
	v_mfma_f32_16x16x32_bf16 v[106:109], v[166:169], v[200:203], v[106:109]
	v_mfma_f32_16x16x32_bf16 v[114:117], v[174:177], v[200:203], v[114:117]
	v_mfma_f32_16x16x32_bf16 v[122:125], v[166:169], v[208:211], v[122:125]
	v_mfma_f32_16x16x32_bf16 v[110:113], v[174:177], v[208:211], v[110:113]
	v_mfma_f32_16x16x32_bf16 v[30:33], v[170:173], v[188:191], v[30:33]
	v_mfma_f32_16x16x32_bf16 v[38:41], v[178:181], v[188:191], v[38:41]
	v_mfma_f32_16x16x32_bf16 v[70:73], v[170:173], v[196:199], v[70:73]
	v_mfma_f32_16x16x32_bf16 v[78:81], v[178:181], v[196:199], v[78:81]
	v_mfma_f32_16x16x32_bf16 v[106:109], v[170:173], v[204:207], v[106:109]
	v_mfma_f32_16x16x32_bf16 v[114:117], v[178:181], v[204:207], v[114:117]
	v_mfma_f32_16x16x32_bf16 v[122:125], v[170:173], v[212:215], v[122:125]
	v_mfma_f32_16x16x32_bf16 v[110:113], v[178:181], v[212:215], v[110:113]
	s_barrier
	v_add_u32_e32 v162, v149, v152
	v_add_u32_e32 v164, v149, v154
	v_mov_b32_e32 v0, v130
	v_mov_b32_e32 v232, v132
	s_add_u32 s60, s4, s56
	v_add_u32_e32 v163, v149, v153
	ds_read_b128 v[216:219], v162
	ds_read_b128 v[220:223], v163
	v_add_u32_e32 v165, v149, v155
	ds_read_b128 v[224:227], v164
	ds_read_b128 v[228:231], v165
	s_addc_u32 s61, s5, s57
	v_lshl_add_u64 v[234:235], s[60:61], 0, v[0:1]
	v_add_u32_e32 v0, s94, v131
	v_mov_b32_e32 v233, v1
	v_readfirstlane_b32 s62, v0
	v_add_u32_e32 v0, 0x2000, v0
	v_lshl_add_u64 v[234:235], v[234:235], 0, s[22:23]
	s_mov_b32 m0, s62
	v_lshl_add_u64 v[232:233], s[60:61], 0, v[232:233]
	v_readfirstlane_b32 s62, v0
	global_load_lds_dwordx4 v[234:235], off
	v_lshl_add_u64 v[232:233], v[232:233], 0, s[22:23]
	s_mov_b32 m0, s62
	s_nop 0
	global_load_lds_dwordx4 v[232:233], off
	s_barrier
	s_waitcnt lgkmcnt(0)
	s_waitcnt lgkmcnt(0)
	v_mfma_f32_16x16x32_bf16 v[42:45], v[216:219], v[182:185], v[42:45]
	v_mfma_f32_16x16x32_bf16 v[46:49], v[224:227], v[182:185], v[46:49]
	v_mfma_f32_16x16x32_bf16 v[82:85], v[216:219], v[192:195], v[82:85]
	v_mfma_f32_16x16x32_bf16 v[90:93], v[224:227], v[192:195], v[90:93]
	v_mfma_f32_16x16x32_bf16 v[118:121], v[216:219], v[200:203], v[118:121]
	v_mfma_f32_16x16x32_bf16 v[126:129], v[224:227], v[200:203], v[126:129]
	v_mfma_f32_16x16x32_bf16 v[102:105], v[216:219], v[208:211], v[102:105]
	v_mfma_f32_16x16x32_bf16 v[98:101], v[224:227], v[208:211], v[98:101]
	v_mfma_f32_16x16x32_bf16 v[42:45], v[220:223], v[188:191], v[42:45]
	v_mfma_f32_16x16x32_bf16 v[46:49], v[228:231], v[188:191], v[46:49]
	v_mfma_f32_16x16x32_bf16 v[82:85], v[220:223], v[196:199], v[82:85]
	v_mfma_f32_16x16x32_bf16 v[90:93], v[228:231], v[196:199], v[90:93]
	v_mfma_f32_16x16x32_bf16 v[118:121], v[220:223], v[204:207], v[118:121]
	v_mfma_f32_16x16x32_bf16 v[126:129], v[228:231], v[204:207], v[126:129]
	v_mfma_f32_16x16x32_bf16 v[102:105], v[220:223], v[212:215], v[102:105]
	v_mfma_f32_16x16x32_bf16 v[98:101], v[228:231], v[212:215], v[98:101]
	v_mov_b32_e32 v0, v130
	v_mov_b32_e32 v232, v132
	s_add_u32 s62, s0, s56
	s_barrier
	ds_read_b128 v[182:185], v134 offset:16384
	ds_read_b128 v[188:191], v135 offset:16384
	ds_read_b128 v[192:195], v136 offset:16384
	ds_read_b128 v[196:199], v137 offset:16384
	ds_read_b128 v[200:203], v138 offset:16384
	ds_read_b128 v[204:207], v139 offset:16384
	ds_read_b128 v[208:211], v140 offset:16384
	ds_read_b128 v[212:215], v141 offset:16384
	s_addc_u32 s63, s1, s57
	v_lshl_add_u64 v[234:235], s[62:63], 0, v[0:1]
	v_readfirstlane_b32 s64, v143
	v_mov_b32_e32 v233, v1
	v_add_u32_e32 v0, 0x2000, v143
	v_lshl_add_u64 v[234:235], v[234:235], 0, s[22:23]
	s_mov_b32 m0, s64
	v_lshl_add_u64 v[232:233], s[62:63], 0, v[232:233]
	v_readfirstlane_b32 s64, v0
	global_load_lds_dwordx4 v[234:235], off
	v_lshl_add_u64 v[232:233], v[232:233], 0, s[22:23]
	s_mov_b32 m0, s64
	s_nop 0
	global_load_lds_dwordx4 v[232:233], off
	s_barrier
; #define LDA(dst, b, h) for (int m = 0; m < 4; ++m) for (int k = 0; k < 2; ++k) \
;     dst[m][k] = *reinterpret_cast<const bf16x8*>((char*)SA(b, h) + lds_byte(wr * 64 + m * 16 + fr, k * 32 + fq * 8))
; #define LDB(dst, b, h) for (int n = 0; n < 2; ++n) for (int k = 0; k < 2; ++k) \
;     dst[n][k] = *reinterpret_cast<const bf16x8*>((char*)SB(b, h) + lds_byte(wc * 32 + n * 16 + fr, k * 32 + fq * 8))
; #define MMA(ai, bj, At_, Bt_) do { __builtin_amdgcn_s_setprio(1); \
;     for (int m = 0; m < 4; ++m) for (int n = 0; n < 2; ++n) for (int k = 0; k < 2; ++k) \
;       acc[ai][bj][m][n] = MFMA16(Bt_[n][k], At_[m][k], acc[ai][bj][m][n]); \
;     __builtin_amdgcn_s_setprio(0); } while (0)
; #define WAIT_V(n) asm volatile("s_waitcnt vmcnt(" #n ")" ::: "memory")
; #define WAIT_L(n) asm volatile("s_waitcnt lgkmcnt(" #n ")" ::: "memory")
; #define BAR __builtin_amdgcn_s_barrier()
; #define SCHED __builtin_amdgcn_sched_barrier(0)
; template <int PART  , bool SYNC_FIRST = true>
; __device__ __forceinline__ void kloop_t(const u16* __restrict__ A, int lda, const u16* __restrict__ Bt, int ldb, int K, Acc& acc, const int wv) {
;     ...
;     BAR; WAIT_L(0); MMA(1, 0, At, B0); BAR; SCHED;
;     STAGE(SB(0, 1), Bt, ldb, HALF, t + 2);
;     WAIT_V(6); BAR; MMA(1, 1, At, B1); BAR;
;     LDB(B0, 1, 0); SCHED; LDA(At, 1, 0); STAGE(SA(0, 1), A, lda, HALF, t + 2);
;     WAIT_L(8); BAR; WAIT_L(0); MMA(0, 0, At, B0); BAR; SCHED;
;     LDB(B1, 1, 1); STAGE(SB(1, 0), Bt, ldb, 0, t + 3);
	s_waitcnt lgkmcnt(0)
	s_waitcnt lgkmcnt(0)
	v_mfma_f32_16x16x32_bf16 v[94:97], v[166:169], v[182:185], v[94:97]
	v_mfma_f32_16x16x32_bf16 v[86:89], v[174:177], v[182:185], v[86:89]
	v_mfma_f32_16x16x32_bf16 v[62:65], v[166:169], v[192:195], v[62:65]
	v_mfma_f32_16x16x32_bf16 v[58:61], v[174:177], v[192:195], v[58:61]
	v_mfma_f32_16x16x32_bf16 v[34:37], v[166:169], v[200:203], v[34:37]
	v_mfma_f32_16x16x32_bf16 v[26:29], v[174:177], v[200:203], v[26:29]
	v_mfma_f32_16x16x32_bf16 v[14:17], v[166:169], v[208:211], v[14:17]
	v_mfma_f32_16x16x32_bf16 v[10:13], v[174:177], v[208:211], v[10:13]
	v_mfma_f32_16x16x32_bf16 v[94:97], v[170:173], v[188:191], v[94:97]
	v_mfma_f32_16x16x32_bf16 v[86:89], v[178:181], v[188:191], v[86:89]
	v_mfma_f32_16x16x32_bf16 v[62:65], v[170:173], v[196:199], v[62:65]
	v_mfma_f32_16x16x32_bf16 v[58:61], v[178:181], v[196:199], v[58:61]
	v_mfma_f32_16x16x32_bf16 v[34:37], v[170:173], v[204:207], v[34:37]
	v_mfma_f32_16x16x32_bf16 v[26:29], v[178:181], v[204:207], v[26:29]
	v_mfma_f32_16x16x32_bf16 v[14:17], v[170:173], v[212:215], v[14:17]
	v_mfma_f32_16x16x32_bf16 v[10:13], v[178:181], v[212:215], v[10:13]
	s_barrier
	v_mov_b32_e32 v0, v130
	v_mov_b32_e32 v166, v132
	s_add_u32 s64, s8, s56
	s_addc_u32 s65, s9, s57
	v_lshl_add_u64 v[168:169], s[64:65], 0, v[0:1]
	v_add_u32_e32 v0, s95, v131
	v_mov_b32_e32 v167, v1
	v_readfirstlane_b32 s12, v0
	v_add_u32_e32 v0, 0x2000, v0
	v_lshl_add_u64 v[168:169], v[168:169], 0, s[22:23]
	s_mov_b32 m0, s12
	v_lshl_add_u64 v[166:167], s[64:65], 0, v[166:167]
	v_readfirstlane_b32 s12, v0
	global_load_lds_dwordx4 v[168:169], off
	v_lshl_add_u64 v[166:167], v[166:167], 0, s[22:23]
	s_mov_b32 m0, s12
	s_nop 0
	global_load_lds_dwordx4 v[166:167], off
	s_waitcnt vmcnt(6)
	s_barrier
	v_mfma_f32_16x16x32_bf16 v[74:77], v[216:219], v[182:185], v[74:77]
	v_mfma_f32_16x16x32_bf16 v[66:69], v[224:227], v[182:185], v[66:69]
	v_mfma_f32_16x16x32_bf16 v[54:57], v[216:219], v[192:195], v[54:57]
	v_mfma_f32_16x16x32_bf16 v[50:53], v[224:227], v[192:195], v[50:53]
	v_mfma_f32_16x16x32_bf16 v[22:25], v[216:219], v[200:203], v[22:25]
	v_mfma_f32_16x16x32_bf16 v[18:21], v[224:227], v[200:203], v[18:21]
	v_mfma_f32_16x16x32_bf16 v[6:9], v[216:219], v[208:211], v[6:9]
	v_mfma_f32_16x16x32_bf16 v[2:5], v[224:227], v[208:211], v[2:5]
	v_mfma_f32_16x16x32_bf16 v[74:77], v[220:223], v[188:191], v[74:77]
	v_mfma_f32_16x16x32_bf16 v[66:69], v[228:231], v[188:191], v[66:69]
	v_mfma_f32_16x16x32_bf16 v[54:57], v[220:223], v[196:199], v[54:57]
	v_mfma_f32_16x16x32_bf16 v[50:53], v[228:231], v[196:199], v[50:53]
	v_mfma_f32_16x16x32_bf16 v[22:25], v[220:223], v[204:207], v[22:25]
	v_mfma_f32_16x16x32_bf16 v[18:21], v[228:231], v[204:207], v[18:21]
	v_mfma_f32_16x16x32_bf16 v[6:9], v[220:223], v[212:215], v[6:9]
	v_mfma_f32_16x16x32_bf16 v[2:5], v[228:231], v[212:215], v[2:5]
	v_add_u32_e32 v166, v150, v152
	v_add_u32_e32 v168, v150, v154
	s_barrier
	v_add_u32_e32 v167, v150, v153
	ds_read_b128 v[174:177], v166
	ds_read_b128 v[178:181], v167
	v_add_u32_e32 v169, v150, v155
	ds_read_b128 v[182:185], v168
	ds_read_b128 v[188:191], v169
	v_mov_b32_e32 v0, v130
	v_mov_b32_e32 v170, v132
	ds_read_b128 v[192:195], v134 offset:32768
	ds_read_b128 v[196:199], v135 offset:32768
	ds_read_b128 v[200:203], v136 offset:32768
	ds_read_b128 v[204:207], v137 offset:32768
	ds_read_b128 v[208:211], v138 offset:32768
	ds_read_b128 v[212:215], v139 offset:32768
	ds_read_b128 v[216:219], v140 offset:32768
	ds_read_b128 v[220:223], v141 offset:32768
	v_mov_b32_e32 v171, v1
	v_lshl_add_u64 v[172:173], s[58:59], 0, v[0:1]
	v_add_u32_e32 v0, 0x4000, v143
	v_lshl_add_u64 v[172:173], v[172:173], 0, s[22:23]
	v_readfirstlane_b32 s12, v0
	v_add_u32_e32 v0, 0x6000, v143
	s_mov_b32 m0, s12
	v_lshl_add_u64 v[170:171], s[58:59], 0, v[170:171]
	v_readfirstlane_b32 s12, v0
	global_load_lds_dwordx4 v[172:173], off
	v_lshl_add_u64 v[170:171], v[170:171], 0, s[22:23]
	s_mov_b32 m0, s12
	s_nop 0
	global_load_lds_dwordx4 v[170:171], off
	s_waitcnt lgkmcnt(8)
	s_barrier
	s_waitcnt lgkmcnt(0)
	s_waitcnt lgkmcnt(0)
	v_mfma_f32_16x16x32_bf16 v[30:33], v[174:177], v[192:195], v[30:33]
	v_mfma_f32_16x16x32_bf16 v[38:41], v[182:185], v[192:195], v[38:41]
	v_mfma_f32_16x16x32_bf16 v[70:73], v[174:177], v[200:203], v[70:73]
	v_mfma_f32_16x16x32_bf16 v[78:81], v[182:185], v[200:203], v[78:81]
	v_mfma_f32_16x16x32_bf16 v[106:109], v[174:177], v[208:211], v[106:109]
	v_mfma_f32_16x16x32_bf16 v[114:117], v[182:185], v[208:211], v[114:117]
	v_mfma_f32_16x16x32_bf16 v[122:125], v[174:177], v[216:219], v[122:125]
	v_mfma_f32_16x16x32_bf16 v[110:113], v[182:185], v[216:219], v[110:113]
	v_mfma_f32_16x16x32_bf16 v[30:33], v[178:181], v[196:199], v[30:33]
	v_mfma_f32_16x16x32_bf16 v[38:41], v[188:191], v[196:199], v[38:41]
	v_mfma_f32_16x16x32_bf16 v[70:73], v[178:181], v[204:207], v[70:73]
	v_mfma_f32_16x16x32_bf16 v[78:81], v[188:191], v[204:207], v[78:81]
	v_mfma_f32_16x16x32_bf16 v[106:109], v[178:181], v[212:215], v[106:109]
	v_mfma_f32_16x16x32_bf16 v[114:117], v[188:191], v[212:215], v[114:117]
	v_mfma_f32_16x16x32_bf16 v[122:125], v[178:181], v[220:223], v[122:125]
	v_mfma_f32_16x16x32_bf16 v[110:113], v[188:191], v[220:223], v[110:113]
	s_barrier
	v_add_u32_e32 v170, v151, v152
	v_add_u32_e32 v172, v151, v154
	v_mov_b32_e32 v0, v130
	v_mov_b32_e32 v240, v132
	v_add_u32_e32 v171, v151, v153
	ds_read_b128 v[224:227], v170
	ds_read_b128 v[228:231], v171
	v_add_u32_e32 v173, v151, v155
	ds_read_b128 v[232:235], v172
	ds_read_b128 v[236:239], v173
	v_readfirstlane_b32 s12, v133
	v_lshl_add_u64 v[242:243], s[60:61], 0, v[0:1]
	v_mov_b32_e32 v241, v1
	v_lshl_add_u64 v[242:243], v[242:243], 0, s[24:25]
	s_mov_b32 m0, s12
	v_lshl_add_u64 v[240:241], s[60:61], 0, v[240:241]
	v_readfirstlane_b32 s12, v142
	global_load_lds_dwordx4 v[242:243], off
	v_lshl_add_u64 v[240:241], v[240:241], 0, s[24:25]
	s_mov_b32 m0, s12
	s_nop 0
	global_load_lds_dwordx4 v[240:241], off
	s_barrier
; #define LDA(dst, b, h) for (int m = 0; m < 4; ++m) for (int k = 0; k < 2; ++k) \
;     dst[m][k] = *reinterpret_cast<const bf16x8*>((char*)SA(b, h) + lds_byte(wr * 64 + m * 16 + fr, k * 32 + fq * 8))
; #define LDB(dst, b, h) for (int n = 0; n < 2; ++n) for (int k = 0; k < 2; ++k) \
;     dst[n][k] = *reinterpret_cast<const bf16x8*>((char*)SB(b, h) + lds_byte(wc * 32 + n * 16 + fr, k * 32 + fq * 8))
; #define MMA(ai, bj, At_, Bt_) do { __builtin_amdgcn_s_setprio(1); \
;     for (int m = 0; m < 4; ++m) for (int n = 0; n < 2; ++n) for (int k = 0; k < 2; ++k) \
;       acc[ai][bj][m][n] = MFMA16(Bt_[n][k], At_[m][k], acc[ai][bj][m][n]); \
;     __builtin_amdgcn_s_setprio(0); } while (0)
; #define WAIT_V(n) asm volatile("s_waitcnt vmcnt(" #n ")" ::: "memory")
; #define WAIT_L(n) asm volatile("s_waitcnt lgkmcnt(" #n ")" ::: "memory")
; #define BAR __builtin_amdgcn_s_barrier()
; #define SCHED __builtin_amdgcn_sched_barrier(0)
; template <int PART  , bool SYNC_FIRST = true>
; __device__ __forceinline__ void kloop_t(const u16* __restrict__ A, int lda, const u16* __restrict__ Bt, int ldb, int K, Acc& acc, const int wv) {
;     ...
;     BAR; WAIT_L(0); MMA(0, 1, At, B1); BAR;
;     LDA(At, 1, 1); STAGE(SA(1, 0), A, lda, 0, t + 3);
;     BAR; WAIT_L(0); MMA(1, 0, At, B0); BAR; SCHED;
;     STAGE(SB(1, 1), Bt, ldb, HALF, t + 3);
;     WAIT_V(6); BAR; MMA(1, 1, At, B1); BAR;
;   }
;   { LDB(B0, 0, 0); LDA(At, 0, 0); STAGE(SA(1, 1), A, lda, HALF, nt - 1);
	s_waitcnt lgkmcnt(0)
	s_waitcnt lgkmcnt(0)
	v_mfma_f32_16x16x32_bf16 v[42:45], v[224:227], v[192:195], v[42:45]
	v_mfma_f32_16x16x32_bf16 v[46:49], v[232:235], v[192:195], v[46:49]
	v_mfma_f32_16x16x32_bf16 v[82:85], v[224:227], v[200:203], v[82:85]
	v_mfma_f32_16x16x32_bf16 v[90:93], v[232:235], v[200:203], v[90:93]
	v_mfma_f32_16x16x32_bf16 v[118:121], v[224:227], v[208:211], v[118:121]
	v_mfma_f32_16x16x32_bf16 v[126:129], v[232:235], v[208:211], v[126:129]
	v_mfma_f32_16x16x32_bf16 v[102:105], v[224:227], v[216:219], v[102:105]
	v_mfma_f32_16x16x32_bf16 v[98:101], v[232:235], v[216:219], v[98:101]
	v_mfma_f32_16x16x32_bf16 v[42:45], v[228:231], v[196:199], v[42:45]
	v_mfma_f32_16x16x32_bf16 v[46:49], v[236:239], v[196:199], v[46:49]
	v_mfma_f32_16x16x32_bf16 v[82:85], v[228:231], v[204:207], v[82:85]
	v_mfma_f32_16x16x32_bf16 v[90:93], v[236:239], v[204:207], v[90:93]
	v_mfma_f32_16x16x32_bf16 v[118:121], v[228:231], v[212:215], v[118:121]
	v_mfma_f32_16x16x32_bf16 v[126:129], v[236:239], v[212:215], v[126:129]
	v_mfma_f32_16x16x32_bf16 v[102:105], v[228:231], v[220:223], v[102:105]
	v_mfma_f32_16x16x32_bf16 v[98:101], v[236:239], v[220:223], v[98:101]
	v_mov_b32_e32 v0, v130
	v_mov_b32_e32 v240, v132
	s_barrier
	ds_read_b128 v[192:195], v134 offset:49152
	ds_read_b128 v[196:199], v135 offset:49152
	ds_read_b128 v[200:203], v136 offset:49152
	ds_read_b128 v[204:207], v137 offset:49152
	ds_read_b128 v[208:211], v138 offset:49152
	ds_read_b128 v[212:215], v139 offset:49152
	ds_read_b128 v[216:219], v140 offset:49152
	ds_read_b128 v[220:223], v141 offset:49152
	v_readfirstlane_b32 s12, v144
	v_lshl_add_u64 v[242:243], s[62:63], 0, v[0:1]
	v_mov_b32_e32 v241, v1
	v_lshl_add_u64 v[242:243], v[242:243], 0, s[24:25]
	s_mov_b32 m0, s12
	v_lshl_add_u64 v[240:241], s[62:63], 0, v[240:241]
	v_readfirstlane_b32 s12, v145
	global_load_lds_dwordx4 v[242:243], off
	v_lshl_add_u64 v[240:241], v[240:241], 0, s[24:25]
	s_mov_b32 m0, s12
	s_nop 0
	global_load_lds_dwordx4 v[240:241], off
	s_barrier
	s_waitcnt lgkmcnt(0)
	s_waitcnt lgkmcnt(0)
	v_mfma_f32_16x16x32_bf16 v[94:97], v[174:177], v[192:195], v[94:97]
	v_mfma_f32_16x16x32_bf16 v[86:89], v[182:185], v[192:195], v[86:89]
	v_mfma_f32_16x16x32_bf16 v[62:65], v[174:177], v[200:203], v[62:65]
	v_mfma_f32_16x16x32_bf16 v[58:61], v[182:185], v[200:203], v[58:61]
	v_mfma_f32_16x16x32_bf16 v[34:37], v[174:177], v[208:211], v[34:37]
	v_mfma_f32_16x16x32_bf16 v[26:29], v[182:185], v[208:211], v[26:29]
	v_mfma_f32_16x16x32_bf16 v[14:17], v[174:177], v[216:219], v[14:17]
	v_mfma_f32_16x16x32_bf16 v[10:13], v[182:185], v[216:219], v[10:13]
	v_mfma_f32_16x16x32_bf16 v[94:97], v[178:181], v[196:199], v[94:97]
	v_mfma_f32_16x16x32_bf16 v[86:89], v[188:191], v[196:199], v[86:89]
	v_mfma_f32_16x16x32_bf16 v[62:65], v[178:181], v[204:207], v[62:65]
	v_mfma_f32_16x16x32_bf16 v[58:61], v[188:191], v[204:207], v[58:61]
	v_mfma_f32_16x16x32_bf16 v[34:37], v[178:181], v[212:215], v[34:37]
	v_mfma_f32_16x16x32_bf16 v[26:29], v[188:191], v[212:215], v[26:29]
	v_mfma_f32_16x16x32_bf16 v[14:17], v[178:181], v[220:223], v[14:17]
	v_mfma_f32_16x16x32_bf16 v[10:13], v[188:191], v[220:223], v[10:13]
	s_barrier
	v_mov_b32_e32 v0, v130
	v_mov_b32_e32 v174, v132
	v_readfirstlane_b32 s12, v146
	v_lshl_add_u64 v[176:177], s[64:65], 0, v[0:1]
	v_mov_b32_e32 v175, v1
	v_lshl_add_u64 v[176:177], v[176:177], 0, s[24:25]
	s_mov_b32 m0, s12
	v_lshl_add_u64 v[174:175], s[64:65], 0, v[174:175]
	v_readfirstlane_b32 s12, v147
	global_load_lds_dwordx4 v[176:177], off
	v_lshl_add_u64 v[174:175], v[174:175], 0, s[24:25]
	s_mov_b32 m0, s12
	s_nop 0
	global_load_lds_dwordx4 v[174:175], off
	s_waitcnt vmcnt(6)
	s_barrier
	v_mfma_f32_16x16x32_bf16 v[74:77], v[224:227], v[192:195], v[74:77]
	v_mfma_f32_16x16x32_bf16 v[66:69], v[232:235], v[192:195], v[66:69]
	v_mfma_f32_16x16x32_bf16 v[54:57], v[224:227], v[200:203], v[54:57]
	v_mfma_f32_16x16x32_bf16 v[50:53], v[232:235], v[200:203], v[50:53]
	v_mfma_f32_16x16x32_bf16 v[22:25], v[224:227], v[208:211], v[22:25]
	v_mfma_f32_16x16x32_bf16 v[18:21], v[232:235], v[208:211], v[18:21]
	v_mfma_f32_16x16x32_bf16 v[6:9], v[224:227], v[216:219], v[6:9]
	v_mfma_f32_16x16x32_bf16 v[2:5], v[232:235], v[216:219], v[2:5]
	v_mfma_f32_16x16x32_bf16 v[74:77], v[228:231], v[196:199], v[74:77]
	v_mfma_f32_16x16x32_bf16 v[66:69], v[236:239], v[196:199], v[66:69]
	v_mfma_f32_16x16x32_bf16 v[54:57], v[228:231], v[204:207], v[54:57]
	v_mfma_f32_16x16x32_bf16 v[50:53], v[236:239], v[204:207], v[50:53]
	v_mfma_f32_16x16x32_bf16 v[22:25], v[228:231], v[212:215], v[22:25]
	v_mfma_f32_16x16x32_bf16 v[18:21], v[236:239], v[212:215], v[18:21]
	v_mfma_f32_16x16x32_bf16 v[6:9], v[228:231], v[220:223], v[6:9]
	v_mfma_f32_16x16x32_bf16 v[2:5], v[236:239], v[220:223], v[2:5]
	s_add_i32 vcc_hi, vcc_hi, 2
	s_add_u32 s56, s56, 0x100
	s_addc_u32 s57, s57, 0
	s_cmp_lt_u32 vcc_hi, 4
	s_barrier
	s_cbranch_scc1 .LBB0_704
	s_add_u32 s0, s0, s6
	ds_read_b128 v[142:145], v156
	ds_read_b128 v[146:149], v157
	ds_read_b128 v[150:153], v158
	ds_read_b128 v[154:157], v159
	ds_read_b128 v[174:177], v134
	ds_read_b128 v[178:181], v135
	ds_read_b128 v[182:185], v136
	ds_read_b128 v[188:191], v137
	ds_read_b128 v[192:195], v138
	ds_read_b128 v[196:199], v139
	ds_read_b128 v[200:203], v140
	ds_read_b128 v[204:207], v141
	s_addc_u32 s1, s1, s7
	v_mov_b32_e32 v131, v1
	v_lshl_add_u64 v[130:131], s[0:1], 0, v[130:131]
	v_readfirstlane_b32 s4, v160
	v_lshl_add_u64 v[130:131], v[130:131], 0, s[26:27]
	s_mov_b32 m0, s4
	v_mov_b32_e32 v133, v1
	global_load_lds_dwordx4 v[130:131], off
	v_lshl_add_u64 v[130:131], s[0:1], 0, v[132:133]
	v_readfirstlane_b32 s0, v161
	v_lshl_add_u64 v[130:131], v[130:131], 0, s[26:27]
	s_mov_b32 m0, s0
	s_nop 0
	global_load_lds_dwordx4 v[130:131], off
	s_barrier
; #define LDA(dst, b, h) for (int m = 0; m < 4; ++m) for (int k = 0; k < 2; ++k) \
;     dst[m][k] = *reinterpret_cast<const bf16x8*>((char*)SA(b, h) + lds_byte(wr * 64 + m * 16 + fr, k * 32 + fq * 8))
; #define LDB(dst, b, h) for (int n = 0; n < 2; ++n) for (int k = 0; k < 2; ++k) \
;     dst[n][k] = *reinterpret_cast<const bf16x8*>((char*)SB(b, h) + lds_byte(wc * 32 + n * 16 + fr, k * 32 + fq * 8))
; #define MMA(ai, bj, At_, Bt_) do { __builtin_amdgcn_s_setprio(1); \
;     for (int m = 0; m < 4; ++m) for (int n = 0; n < 2; ++n) for (int k = 0; k < 2; ++k) \
;       acc[ai][bj][m][n] = MFMA16(Bt_[n][k], At_[m][k], acc[ai][bj][m][n]); \
;     __builtin_amdgcn_s_setprio(0); } while (0)
; #define WAIT_V(n) asm volatile("s_waitcnt vmcnt(" #n ")" ::: "memory")
; #define WAIT_L(n) asm volatile("s_waitcnt lgkmcnt(" #n ")" ::: "memory")
; #define BAR __builtin_amdgcn_s_barrier()
; template <int PART  , bool SYNC_FIRST = true>
; __device__ __forceinline__ void kloop_t(const u16* __restrict__ A, int lda, const u16* __restrict__ Bt, int ldb, int K, Acc& acc, const int wv) {
;     ...
;   { LDB(B0, 0, 0); LDA(At, 0, 0); STAGE(SA(1, 1), A, lda, HALF, nt - 1);
;     BAR; WAIT_L(0); MMA(0, 0, At, B0); BAR;
;     LDB(B1, 0, 1); BAR; WAIT_L(0); MMA(0, 1, At, B1); BAR;
;     LDA(At, 0, 1); WAIT_V(4); BAR; WAIT_L(0); MMA(1, 0, At, B0); MMA(1, 1, At, B1); BAR; }
;   { LDB(B0, 1, 0); LDA(At, 1, 0); WAIT_V(2); BAR; WAIT_L(0); MMA(0, 0, At, B0); BAR;
	s_waitcnt lgkmcnt(0)
	s_waitcnt lgkmcnt(0)
	v_mfma_f32_16x16x32_bf16 v[30:33], v[142:145], v[174:177], v[30:33]
	v_mfma_f32_16x16x32_bf16 v[38:41], v[150:153], v[174:177], v[38:41]
	v_mfma_f32_16x16x32_bf16 v[70:73], v[142:145], v[182:185], v[70:73]
	v_mfma_f32_16x16x32_bf16 v[78:81], v[150:153], v[182:185], v[78:81]
	v_mfma_f32_16x16x32_bf16 v[106:109], v[142:145], v[192:195], v[106:109]
	v_mfma_f32_16x16x32_bf16 v[114:117], v[150:153], v[192:195], v[114:117]
	v_mfma_f32_16x16x32_bf16 v[122:125], v[142:145], v[200:203], v[122:125]
	v_mfma_f32_16x16x32_bf16 v[110:113], v[150:153], v[200:203], v[110:113]
	v_mfma_f32_16x16x32_bf16 v[30:33], v[146:149], v[178:181], v[30:33]
	v_mfma_f32_16x16x32_bf16 v[38:41], v[154:157], v[178:181], v[38:41]
	v_mfma_f32_16x16x32_bf16 v[70:73], v[146:149], v[188:191], v[70:73]
	v_mfma_f32_16x16x32_bf16 v[78:81], v[154:157], v[188:191], v[78:81]
	v_mfma_f32_16x16x32_bf16 v[106:109], v[146:149], v[196:199], v[106:109]
	v_mfma_f32_16x16x32_bf16 v[114:117], v[154:157], v[196:199], v[114:117]
	v_mfma_f32_16x16x32_bf16 v[122:125], v[146:149], v[204:207], v[122:125]
	v_mfma_f32_16x16x32_bf16 v[110:113], v[154:157], v[204:207], v[110:113]
	s_barrier
	ds_read_b128 v[130:133], v162
	ds_read_b128 v[158:161], v163
	ds_read_b128 v[208:211], v164
	ds_read_b128 v[162:165], v165
	s_barrier
	s_waitcnt lgkmcnt(0)
	s_waitcnt lgkmcnt(0)
	v_mfma_f32_16x16x32_bf16 v[42:45], v[130:133], v[174:177], v[42:45]
	v_mfma_f32_16x16x32_bf16 v[46:49], v[208:211], v[174:177], v[46:49]
	v_mfma_f32_16x16x32_bf16 v[82:85], v[130:133], v[182:185], v[82:85]
	v_mfma_f32_16x16x32_bf16 v[90:93], v[208:211], v[182:185], v[90:93]
	v_mfma_f32_16x16x32_bf16 v[118:121], v[130:133], v[192:195], v[118:121]
	v_mfma_f32_16x16x32_bf16 v[126:129], v[208:211], v[192:195], v[126:129]
	v_mfma_f32_16x16x32_bf16 v[102:105], v[130:133], v[200:203], v[102:105]
	v_mfma_f32_16x16x32_bf16 v[98:101], v[208:211], v[200:203], v[98:101]
	v_mfma_f32_16x16x32_bf16 v[42:45], v[158:161], v[178:181], v[42:45]
	v_mfma_f32_16x16x32_bf16 v[46:49], v[162:165], v[178:181], v[46:49]
	v_mfma_f32_16x16x32_bf16 v[82:85], v[158:161], v[188:191], v[82:85]
	v_mfma_f32_16x16x32_bf16 v[90:93], v[162:165], v[188:191], v[90:93]
	v_mfma_f32_16x16x32_bf16 v[118:121], v[158:161], v[196:199], v[118:121]
	v_mfma_f32_16x16x32_bf16 v[126:129], v[162:165], v[196:199], v[126:129]
	v_mfma_f32_16x16x32_bf16 v[102:105], v[158:161], v[204:207], v[102:105]
	v_mfma_f32_16x16x32_bf16 v[98:101], v[162:165], v[204:207], v[98:101]
	s_barrier
	ds_read_b128 v[174:177], v134 offset:16384
	ds_read_b128 v[178:181], v135 offset:16384
	ds_read_b128 v[182:185], v136 offset:16384
	ds_read_b128 v[188:191], v137 offset:16384
	ds_read_b128 v[192:195], v138 offset:16384
	ds_read_b128 v[196:199], v139 offset:16384
	ds_read_b128 v[200:203], v140 offset:16384
	ds_read_b128 v[204:207], v141 offset:16384
	s_waitcnt vmcnt(4)
	s_barrier
	s_waitcnt lgkmcnt(0)
	s_waitcnt lgkmcnt(0)
	v_mfma_f32_16x16x32_bf16 v[94:97], v[142:145], v[174:177], v[94:97]
	v_mfma_f32_16x16x32_bf16 v[86:89], v[150:153], v[174:177], v[86:89]
	v_mfma_f32_16x16x32_bf16 v[62:65], v[142:145], v[182:185], v[62:65]
	v_mfma_f32_16x16x32_bf16 v[58:61], v[150:153], v[182:185], v[58:61]
	v_mfma_f32_16x16x32_bf16 v[34:37], v[142:145], v[192:195], v[34:37]
	v_mfma_f32_16x16x32_bf16 v[26:29], v[150:153], v[192:195], v[26:29]
	v_mfma_f32_16x16x32_bf16 v[14:17], v[142:145], v[200:203], v[14:17]
	v_mfma_f32_16x16x32_bf16 v[10:13], v[150:153], v[200:203], v[10:13]
	v_mfma_f32_16x16x32_bf16 v[94:97], v[146:149], v[178:181], v[94:97]
	v_mfma_f32_16x16x32_bf16 v[86:89], v[154:157], v[178:181], v[86:89]
	v_mfma_f32_16x16x32_bf16 v[62:65], v[146:149], v[188:191], v[62:65]
	v_mfma_f32_16x16x32_bf16 v[58:61], v[154:157], v[188:191], v[58:61]
	v_mfma_f32_16x16x32_bf16 v[34:37], v[146:149], v[196:199], v[34:37]
	v_mfma_f32_16x16x32_bf16 v[26:29], v[154:157], v[196:199], v[26:29]
	v_mfma_f32_16x16x32_bf16 v[14:17], v[146:149], v[204:207], v[14:17]
	v_mfma_f32_16x16x32_bf16 v[10:13], v[154:157], v[204:207], v[10:13]
	v_mfma_f32_16x16x32_bf16 v[74:77], v[130:133], v[174:177], v[74:77]
	v_mfma_f32_16x16x32_bf16 v[66:69], v[208:211], v[174:177], v[66:69]
	v_mfma_f32_16x16x32_bf16 v[54:57], v[130:133], v[182:185], v[54:57]
	v_mfma_f32_16x16x32_bf16 v[50:53], v[208:211], v[182:185], v[50:53]
	v_mfma_f32_16x16x32_bf16 v[22:25], v[130:133], v[192:195], v[22:25]
	v_mfma_f32_16x16x32_bf16 v[18:21], v[208:211], v[192:195], v[18:21]
	v_mfma_f32_16x16x32_bf16 v[6:9], v[130:133], v[200:203], v[6:9]
	v_mfma_f32_16x16x32_bf16 v[2:5], v[208:211], v[200:203], v[2:5]
	v_mfma_f32_16x16x32_bf16 v[74:77], v[158:161], v[178:181], v[74:77]
	v_mfma_f32_16x16x32_bf16 v[66:69], v[162:165], v[178:181], v[66:69]
	v_mfma_f32_16x16x32_bf16 v[54:57], v[158:161], v[188:191], v[54:57]
	v_mfma_f32_16x16x32_bf16 v[50:53], v[162:165], v[188:191], v[50:53]
	v_mfma_f32_16x16x32_bf16 v[22:25], v[158:161], v[196:199], v[22:25]
	v_mfma_f32_16x16x32_bf16 v[18:21], v[162:165], v[196:199], v[18:21]
	v_mfma_f32_16x16x32_bf16 v[6:9], v[158:161], v[204:207], v[6:9]
	v_mfma_f32_16x16x32_bf16 v[2:5], v[162:165], v[204:207], v[2:5]
	s_barrier
	ds_read_b128 v[130:133], v166
	ds_read_b128 v[142:145], v167
	ds_read_b128 v[146:149], v168
	ds_read_b128 v[150:153], v169
	ds_read_b128 v[154:157], v134 offset:32768
	ds_read_b128 v[158:161], v135 offset:32768
	ds_read_b128 v[162:165], v136 offset:32768
	ds_read_b128 v[166:169], v137 offset:32768
	ds_read_b128 v[174:177], v138 offset:32768
	ds_read_b128 v[178:181], v139 offset:32768
	ds_read_b128 v[182:185], v140 offset:32768
	ds_read_b128 v[188:191], v141 offset:32768
	s_waitcnt vmcnt(2)
	s_barrier
; #define LDA(dst, b, h) for (int m = 0; m < 4; ++m) for (int k = 0; k < 2; ++k) \
;     dst[m][k] = *reinterpret_cast<const bf16x8*>((char*)SA(b, h) + lds_byte(wr * 64 + m * 16 + fr, k * 32 + fq * 8))
; #define LDB(dst, b, h) for (int n = 0; n < 2; ++n) for (int k = 0; k < 2; ++k) \
;     dst[n][k] = *reinterpret_cast<const bf16x8*>((char*)SB(b, h) + lds_byte(wc * 32 + n * 16 + fr, k * 32 + fq * 8))
; #define MMA(ai, bj, At_, Bt_) do { __builtin_amdgcn_s_setprio(1); \
;     for (int m = 0; m < 4; ++m) for (int n = 0; n < 2; ++n) for (int k = 0; k < 2; ++k) \
;       acc[ai][bj][m][n] = MFMA16(Bt_[n][k], At_[m][k], acc[ai][bj][m][n]); \
;     __builtin_amdgcn_s_setprio(0); } while (0)
; #define WAIT_V(n) asm volatile("s_waitcnt vmcnt(" #n ")" ::: "memory")
; #define WAIT_L(n) asm volatile("s_waitcnt lgkmcnt(" #n ")" ::: "memory")
; #define BAR __builtin_amdgcn_s_barrier()
; template <int PART  , bool SYNC_FIRST = true>
; __device__ __forceinline__ void kloop_t(const u16* __restrict__ A, int lda, const u16* __restrict__ Bt, int ldb, int K, Acc& acc, const int wv) {
;     ...
;   { LDB(B0, 1, 0); LDA(At, 1, 0); WAIT_V(2); BAR; WAIT_L(0); MMA(0, 0, At, B0); BAR;
;     LDB(B1, 1, 1); WAIT_V(0); BAR; WAIT_L(0); MMA(0, 1, At, B1); BAR;
;     LDA(At, 1, 1); BAR; WAIT_L(0); MMA(1, 0, At, B0); MMA(1, 1, At, B1); BAR; }
;   if (wr == 0) BAR;
	s_waitcnt lgkmcnt(0)
	s_waitcnt lgkmcnt(0)
	v_mfma_f32_16x16x32_bf16 v[30:33], v[130:133], v[154:157], v[30:33]
	v_mfma_f32_16x16x32_bf16 v[38:41], v[146:149], v[154:157], v[38:41]
	v_mfma_f32_16x16x32_bf16 v[70:73], v[130:133], v[162:165], v[70:73]
	v_mfma_f32_16x16x32_bf16 v[78:81], v[146:149], v[162:165], v[78:81]
	v_mfma_f32_16x16x32_bf16 v[106:109], v[130:133], v[174:177], v[106:109]
	v_mfma_f32_16x16x32_bf16 v[114:117], v[146:149], v[174:177], v[114:117]
	v_mfma_f32_16x16x32_bf16 v[122:125], v[130:133], v[182:185], v[122:125]
	v_mfma_f32_16x16x32_bf16 v[110:113], v[146:149], v[182:185], v[110:113]
	v_mfma_f32_16x16x32_bf16 v[30:33], v[142:145], v[158:161], v[30:33]
	v_mfma_f32_16x16x32_bf16 v[38:41], v[150:153], v[158:161], v[38:41]
	v_mfma_f32_16x16x32_bf16 v[70:73], v[142:145], v[166:169], v[70:73]
	v_mfma_f32_16x16x32_bf16 v[78:81], v[150:153], v[166:169], v[78:81]
	v_mfma_f32_16x16x32_bf16 v[106:109], v[142:145], v[178:181], v[106:109]
	v_mfma_f32_16x16x32_bf16 v[114:117], v[150:153], v[178:181], v[114:117]
	v_mfma_f32_16x16x32_bf16 v[122:125], v[142:145], v[188:191], v[122:125]
	v_mfma_f32_16x16x32_bf16 v[110:113], v[150:153], v[188:191], v[110:113]
	s_barrier
	ds_read_b128 v[192:195], v170
	ds_read_b128 v[196:199], v171
	ds_read_b128 v[200:203], v172
	ds_read_b128 v[170:173], v173
	s_waitcnt vmcnt(0)
	s_barrier
	s_waitcnt lgkmcnt(0)
	s_waitcnt lgkmcnt(0)
	v_mfma_f32_16x16x32_bf16 v[42:45], v[192:195], v[154:157], v[42:45]
	v_mfma_f32_16x16x32_bf16 v[46:49], v[200:203], v[154:157], v[46:49]
	v_mfma_f32_16x16x32_bf16 v[82:85], v[192:195], v[162:165], v[82:85]
	v_mfma_f32_16x16x32_bf16 v[90:93], v[200:203], v[162:165], v[90:93]
	v_mfma_f32_16x16x32_bf16 v[118:121], v[192:195], v[174:177], v[118:121]
	v_mfma_f32_16x16x32_bf16 v[126:129], v[200:203], v[174:177], v[126:129]
	v_mfma_f32_16x16x32_bf16 v[102:105], v[192:195], v[182:185], v[102:105]
	v_mfma_f32_16x16x32_bf16 v[98:101], v[200:203], v[182:185], v[98:101]
	v_mfma_f32_16x16x32_bf16 v[42:45], v[196:199], v[158:161], v[42:45]
	v_mfma_f32_16x16x32_bf16 v[46:49], v[170:173], v[158:161], v[46:49]
	v_mfma_f32_16x16x32_bf16 v[82:85], v[196:199], v[166:169], v[82:85]
	v_mfma_f32_16x16x32_bf16 v[90:93], v[170:173], v[166:169], v[90:93]
	v_mfma_f32_16x16x32_bf16 v[118:121], v[196:199], v[178:181], v[118:121]
	v_mfma_f32_16x16x32_bf16 v[126:129], v[170:173], v[178:181], v[126:129]
	v_mfma_f32_16x16x32_bf16 v[102:105], v[196:199], v[188:191], v[102:105]
	v_mfma_f32_16x16x32_bf16 v[98:101], v[170:173], v[188:191], v[98:101]
	s_barrier
	ds_read_b128 v[154:157], v134 offset:49152
	ds_read_b128 v[158:161], v135 offset:49152
	ds_read_b128 v[162:165], v136 offset:49152
	ds_read_b128 v[134:137], v137 offset:49152
	ds_read_b128 v[166:169], v138 offset:49152
	ds_read_b128 v[174:177], v139 offset:49152
	ds_read_b128 v[178:181], v140 offset:49152
	ds_read_b128 v[138:141], v141 offset:49152
	s_barrier
	s_waitcnt lgkmcnt(0)
	s_waitcnt lgkmcnt(0)
	v_mfma_f32_16x16x32_bf16 v[94:97], v[130:133], v[154:157], v[94:97]
	v_mfma_f32_16x16x32_bf16 v[86:89], v[146:149], v[154:157], v[86:89]
	v_mfma_f32_16x16x32_bf16 v[62:65], v[130:133], v[162:165], v[62:65]
	v_mfma_f32_16x16x32_bf16 v[58:61], v[146:149], v[162:165], v[58:61]
	v_mfma_f32_16x16x32_bf16 v[34:37], v[130:133], v[166:169], v[34:37]
	v_mfma_f32_16x16x32_bf16 v[26:29], v[146:149], v[166:169], v[26:29]
	v_mfma_f32_16x16x32_bf16 v[14:17], v[130:133], v[178:181], v[14:17]
	v_mfma_f32_16x16x32_bf16 v[10:13], v[146:149], v[178:181], v[10:13]
	v_mfma_f32_16x16x32_bf16 v[94:97], v[142:145], v[158:161], v[94:97]
	v_mfma_f32_16x16x32_bf16 v[86:89], v[150:153], v[158:161], v[86:89]
	v_mfma_f32_16x16x32_bf16 v[62:65], v[142:145], v[134:137], v[62:65]
	v_mfma_f32_16x16x32_bf16 v[58:61], v[150:153], v[134:137], v[58:61]
	v_mfma_f32_16x16x32_bf16 v[34:37], v[142:145], v[174:177], v[34:37]
	v_mfma_f32_16x16x32_bf16 v[26:29], v[150:153], v[174:177], v[26:29]
	v_mfma_f32_16x16x32_bf16 v[14:17], v[142:145], v[138:141], v[14:17]
	v_mfma_f32_16x16x32_bf16 v[10:13], v[150:153], v[138:141], v[10:13]
	v_mfma_f32_16x16x32_bf16 v[74:77], v[192:195], v[154:157], v[74:77]
	v_mfma_f32_16x16x32_bf16 v[66:69], v[200:203], v[154:157], v[66:69]
	v_mfma_f32_16x16x32_bf16 v[54:57], v[192:195], v[162:165], v[54:57]
	v_mfma_f32_16x16x32_bf16 v[50:53], v[200:203], v[162:165], v[50:53]
	v_mfma_f32_16x16x32_bf16 v[22:25], v[192:195], v[166:169], v[22:25]
	v_mfma_f32_16x16x32_bf16 v[18:21], v[200:203], v[166:169], v[18:21]
	v_mfma_f32_16x16x32_bf16 v[6:9], v[192:195], v[178:181], v[6:9]
	v_mfma_f32_16x16x32_bf16 v[2:5], v[200:203], v[178:181], v[2:5]
	v_mfma_f32_16x16x32_bf16 v[74:77], v[196:199], v[158:161], v[74:77]
	v_mfma_f32_16x16x32_bf16 v[66:69], v[170:173], v[158:161], v[66:69]
	v_mfma_f32_16x16x32_bf16 v[54:57], v[196:199], v[134:137], v[54:57]
	v_mfma_f32_16x16x32_bf16 v[50:53], v[170:173], v[134:137], v[50:53]
	v_mfma_f32_16x16x32_bf16 v[22:25], v[196:199], v[174:177], v[22:25]
	v_mfma_f32_16x16x32_bf16 v[18:21], v[170:173], v[174:177], v[18:21]
	v_mfma_f32_16x16x32_bf16 v[6:9], v[196:199], v[138:141], v[6:9]
	v_mfma_f32_16x16x32_bf16 v[2:5], v[170:173], v[138:141], v[2:5]
	s_andn2_b64 vcc, exec, s[16:17]
	s_barrier
	s_cbranch_vccnz .LBB0_707
	s_barrier

; #define LDA(dst, b, h) for (int m = 0; m < 4; ++m) for (int k = 0; k < 2; ++k) \
;     dst[m][k] = *reinterpret_cast<const bf16x8*>((char*)SA(b, h) + lds_byte(wr * 64 + m * 16 + fr, k * 32 + fq * 8))
; #define LDB(dst, b, h) for (int n = 0; n < 2; ++n) for (int k = 0; k < 2; ++k) \
;     dst[n][k] = *reinterpret_cast<const bf16x8*>((char*)SB(b, h) + lds_byte(wc * 32 + n * 16 + fr, k * 32 + fq * 8))
; #define MMA(ai, bj, At_, Bt_) do { __builtin_amdgcn_s_setprio(1); \
;     for (int m = 0; m < 4; ++m) for (int n = 0; n < 2; ++n) for (int k = 0; k < 2; ++k) \
;       acc[ai][bj][m][n] = MFMA16(Bt_[n][k], At_[m][k], acc[ai][bj][m][n]); \
;     __builtin_amdgcn_s_setprio(0); } while (0)
; #define WAIT_L(n) asm volatile("s_waitcnt lgkmcnt(" #n ")" ::: "memory")
; #define BAR __builtin_amdgcn_s_barrier()
; #define SCHED __builtin_amdgcn_sched_barrier(0)
; template <int PART  , bool SYNC_FIRST = true>
; __device__ __forceinline__ void kloop_t(const u16* __restrict__ A, int lda, const u16* __restrict__ Bt, int ldb, int K, Acc& acc, const int wv) {
;     ...
;   for (int t = 0; t < nt - 2; t += 2) {
;     LDB(B0, 0, 0); SCHED; LDA(At, 0, 0); STAGE(SA(1, 1), A, lda, HALF, t + 1);
;     WAIT_L(8); BAR; WAIT_L(0); MMA(0, 0, At, B0); BAR; SCHED;
;     LDB(B1, 0, 1); STAGE(SB(0, 0), Bt, ldb, 0, t + 2);
;     BAR; WAIT_L(0); MMA(0, 1, At, B1); BAR;
;     LDA(At, 0, 1); STAGE(SA(0, 0), A, lda, 0, t + 2);
.LBB0_980:
	v_add_u32_e32 v163, v155, v159
	v_add_u32_e32 v165, v155, v161
	v_add_u32_e32 v164, v155, v160
	ds_read_b128 v[174:177], v163
	ds_read_b128 v[178:181], v164
	v_add_u32_e32 v166, v155, v162
	ds_read_b128 v[182:185], v165
	ds_read_b128 v[186:189], v166
	s_add_u32 s36, s34, s72
	v_mov_b32_e32 v128, v130
	v_mov_b32_e32 v168, v131
	s_addc_u32 s37, s35, 0
	v_add_u32_e32 v167, 0xc000, v143
	ds_read_b128 v[190:193], v132
	ds_read_b128 v[194:197], v133
	ds_read_b128 v[198:201], v135
	ds_read_b128 v[202:205], v136
	ds_read_b128 v[206:209], v137
	ds_read_b128 v[210:213], v138
	ds_read_b128 v[214:217], v139
	ds_read_b128 v[218:221], v140
	v_readfirstlane_b32 s38, v167
	v_lshl_add_u64 v[170:171], s[36:37], 0, v[128:129]
	v_mov_b32_e32 v169, v129
	v_lshl_add_u64 v[170:171], v[170:171], 0, s[14:15]
	s_mov_b32 m0, s38
	v_lshl_add_u64 v[168:169], s[36:37], 0, v[168:169]
	global_load_lds_dwordx4 v[170:171], off
	v_lshl_add_u64 v[170:171], v[168:169], 0, s[14:15]
	v_add_u32_e32 v168, 0xe000, v143
	s_nop 0
	v_readfirstlane_b32 s38, v168
	s_mov_b32 m0, s38
	s_nop 0
	global_load_lds_dwordx4 v[170:171], off
	s_waitcnt lgkmcnt(8)
	s_barrier
	s_waitcnt lgkmcnt(0)
	s_waitcnt lgkmcnt(0)
	v_mfma_f32_16x16x32_bf16 v[124:127], v[174:177], v[190:193], v[124:127]
	v_mfma_f32_16x16x32_bf16 v[120:123], v[182:185], v[190:193], v[120:123]
	v_mfma_f32_16x16x32_bf16 v[116:119], v[174:177], v[198:201], v[116:119]
	v_mfma_f32_16x16x32_bf16 v[112:115], v[182:185], v[198:201], v[112:115]
	v_mfma_f32_16x16x32_bf16 v[108:111], v[174:177], v[206:209], v[108:111]
	v_mfma_f32_16x16x32_bf16 v[104:107], v[182:185], v[206:209], v[104:107]
	v_mfma_f32_16x16x32_bf16 v[100:103], v[174:177], v[214:217], v[100:103]
	v_mfma_f32_16x16x32_bf16 v[96:99], v[182:185], v[214:217], v[96:99]
	v_mfma_f32_16x16x32_bf16 v[124:127], v[178:181], v[194:197], v[124:127]
	v_mfma_f32_16x16x32_bf16 v[120:123], v[186:189], v[194:197], v[120:123]
	v_mfma_f32_16x16x32_bf16 v[116:119], v[178:181], v[202:205], v[116:119]
	v_mfma_f32_16x16x32_bf16 v[112:115], v[186:189], v[202:205], v[112:115]
	v_mfma_f32_16x16x32_bf16 v[108:111], v[178:181], v[210:213], v[108:111]
	v_mfma_f32_16x16x32_bf16 v[104:107], v[186:189], v[210:213], v[104:107]
	v_mfma_f32_16x16x32_bf16 v[100:103], v[178:181], v[218:221], v[100:103]
	v_mfma_f32_16x16x32_bf16 v[96:99], v[186:189], v[218:221], v[96:99]
	s_barrier
	s_add_u32 s38, s34, s73
	v_add_u32_e32 v169, v156, v159
	v_add_u32_e32 v171, v156, v161
	v_mov_b32_e32 v128, v130
	v_mov_b32_e32 v238, v131
	s_addc_u32 s39, s35, 0
	v_add_u32_e32 v170, v156, v160
	ds_read_b128 v[222:225], v169
	ds_read_b128 v[226:229], v170
	v_add_u32_e32 v172, v156, v162
	ds_read_b128 v[230:233], v171
	ds_read_b128 v[234:237], v172
	v_readfirstlane_b32 s75, v141
	v_lshl_add_u64 v[240:241], s[38:39], 0, v[128:129]
	v_mov_b32_e32 v239, v129
	v_lshl_add_u64 v[240:241], v[240:241], 0, s[16:17]
	s_mov_b32 m0, s75
	v_lshl_add_u64 v[238:239], s[38:39], 0, v[238:239]
	v_readfirstlane_b32 s75, v142
	global_load_lds_dwordx4 v[240:241], off
	v_lshl_add_u64 v[238:239], v[238:239], 0, s[16:17]
	s_mov_b32 m0, s75
	s_nop 0
	global_load_lds_dwordx4 v[238:239], off
	s_barrier
	s_waitcnt lgkmcnt(0)
	s_waitcnt lgkmcnt(0)
	v_mfma_f32_16x16x32_bf16 v[92:95], v[222:225], v[190:193], v[92:95]
	v_mfma_f32_16x16x32_bf16 v[88:91], v[230:233], v[190:193], v[88:91]
	v_mfma_f32_16x16x32_bf16 v[84:87], v[222:225], v[198:201], v[84:87]
	v_mfma_f32_16x16x32_bf16 v[80:83], v[230:233], v[198:201], v[80:83]
	v_mfma_f32_16x16x32_bf16 v[76:79], v[222:225], v[206:209], v[76:79]
	v_mfma_f32_16x16x32_bf16 v[72:75], v[230:233], v[206:209], v[72:75]
	v_mfma_f32_16x16x32_bf16 v[68:71], v[222:225], v[214:217], v[68:71]
	v_mfma_f32_16x16x32_bf16 v[64:67], v[230:233], v[214:217], v[64:67]
	v_mfma_f32_16x16x32_bf16 v[92:95], v[226:229], v[194:197], v[92:95]
	v_mfma_f32_16x16x32_bf16 v[88:91], v[234:237], v[194:197], v[88:91]
	v_mfma_f32_16x16x32_bf16 v[84:87], v[226:229], v[202:205], v[84:87]
	v_mfma_f32_16x16x32_bf16 v[80:83], v[234:237], v[202:205], v[80:83]
	v_mfma_f32_16x16x32_bf16 v[76:79], v[226:229], v[210:213], v[76:79]
	v_mfma_f32_16x16x32_bf16 v[72:75], v[234:237], v[210:213], v[72:75]
	v_mfma_f32_16x16x32_bf16 v[68:71], v[226:229], v[218:221], v[68:71]
	v_mfma_f32_16x16x32_bf16 v[64:67], v[234:237], v[218:221], v[64:67]
	v_mov_b32_e32 v128, v130
	v_mov_b32_e32 v238, v131
	s_barrier
	ds_read_b128 v[190:193], v132 offset:16384
	ds_read_b128 v[194:197], v133 offset:16384
	ds_read_b128 v[198:201], v135 offset:16384
	ds_read_b128 v[202:205], v136 offset:16384
	ds_read_b128 v[206:209], v137 offset:16384
	ds_read_b128 v[210:213], v138 offset:16384
	ds_read_b128 v[214:217], v139 offset:16384
	ds_read_b128 v[218:221], v140 offset:16384
	v_readfirstlane_b32 s75, v143
	v_lshl_add_u64 v[240:241], s[36:37], 0, v[128:129]
	v_mov_b32_e32 v239, v129
	v_lshl_add_u64 v[240:241], v[240:241], 0, s[18:19]
	s_mov_b32 m0, s75
	v_lshl_add_u64 v[238:239], s[36:37], 0, v[238:239]
	v_readfirstlane_b32 s75, v144
	global_load_lds_dwordx4 v[240:241], off
	v_lshl_add_u64 v[238:239], v[238:239], 0, s[18:19]
	s_mov_b32 m0, s75
	s_nop 0
	global_load_lds_dwordx4 v[238:239], off
	s_barrier
; #define LDA(dst, b, h) for (int m = 0; m < 4; ++m) for (int k = 0; k < 2; ++k) \
;     dst[m][k] = *reinterpret_cast<const bf16x8*>((char*)SA(b, h) + lds_byte(wr * 64 + m * 16 + fr, k * 32 + fq * 8))
; #define LDB(dst, b, h) for (int n = 0; n < 2; ++n) for (int k = 0; k < 2; ++k) \
;     dst[n][k] = *reinterpret_cast<const bf16x8*>((char*)SB(b, h) + lds_byte(wc * 32 + n * 16 + fr, k * 32 + fq * 8))
; #define MMA(ai, bj, At_, Bt_) do { __builtin_amdgcn_s_setprio(1); \
;     for (int m = 0; m < 4; ++m) for (int n = 0; n < 2; ++n) for (int k = 0; k < 2; ++k) \
;       acc[ai][bj][m][n] = MFMA16(Bt_[n][k], At_[m][k], acc[ai][bj][m][n]); \
;     __builtin_amdgcn_s_setprio(0); } while (0)
; #define WAIT_V(n) asm volatile("s_waitcnt vmcnt(" #n ")" ::: "memory")
; #define WAIT_L(n) asm volatile("s_waitcnt lgkmcnt(" #n ")" ::: "memory")
; #define BAR __builtin_amdgcn_s_barrier()
; #define SCHED __builtin_amdgcn_sched_barrier(0)
; template <int PART  , bool SYNC_FIRST = true>
; __device__ __forceinline__ void kloop_t(const u16* __restrict__ A, int lda, const u16* __restrict__ Bt, int ldb, int K, Acc& acc, const int wv) {
;     ...
;     BAR; WAIT_L(0); MMA(1, 0, At, B0); BAR; SCHED;
;     STAGE(SB(0, 1), Bt, ldb, HALF, t + 2);
;     WAIT_V(6); BAR; MMA(1, 1, At, B1); BAR;
;     LDB(B0, 1, 0); SCHED; LDA(At, 1, 0); STAGE(SA(0, 1), A, lda, HALF, t + 2);
;     WAIT_L(8); BAR; WAIT_L(0); MMA(0, 0, At, B0); BAR; SCHED;
;     LDB(B1, 1, 1); STAGE(SB(1, 0), Bt, ldb, 0, t + 3);
	s_waitcnt lgkmcnt(0)
	s_waitcnt lgkmcnt(0)
	v_mfma_f32_16x16x32_bf16 v[60:63], v[174:177], v[190:193], v[60:63]
	v_mfma_f32_16x16x32_bf16 v[56:59], v[182:185], v[190:193], v[56:59]
	v_mfma_f32_16x16x32_bf16 v[52:55], v[174:177], v[198:201], v[52:55]
	v_mfma_f32_16x16x32_bf16 v[48:51], v[182:185], v[198:201], v[48:51]
	v_mfma_f32_16x16x32_bf16 v[44:47], v[174:177], v[206:209], v[44:47]
	v_mfma_f32_16x16x32_bf16 v[40:43], v[182:185], v[206:209], v[40:43]
	v_mfma_f32_16x16x32_bf16 v[36:39], v[174:177], v[214:217], v[36:39]
	v_mfma_f32_16x16x32_bf16 v[32:35], v[182:185], v[214:217], v[32:35]
	v_mfma_f32_16x16x32_bf16 v[60:63], v[178:181], v[194:197], v[60:63]
	v_mfma_f32_16x16x32_bf16 v[56:59], v[186:189], v[194:197], v[56:59]
	v_mfma_f32_16x16x32_bf16 v[52:55], v[178:181], v[202:205], v[52:55]
	v_mfma_f32_16x16x32_bf16 v[48:51], v[186:189], v[202:205], v[48:51]
	v_mfma_f32_16x16x32_bf16 v[44:47], v[178:181], v[210:213], v[44:47]
	v_mfma_f32_16x16x32_bf16 v[40:43], v[186:189], v[210:213], v[40:43]
	v_mfma_f32_16x16x32_bf16 v[36:39], v[178:181], v[218:221], v[36:39]
	v_mfma_f32_16x16x32_bf16 v[32:35], v[186:189], v[218:221], v[32:35]
	s_barrier
	v_mov_b32_e32 v128, v130
	v_mov_b32_e32 v174, v131
	v_readfirstlane_b32 s75, v145
	v_lshl_add_u64 v[176:177], s[38:39], 0, v[128:129]
	v_mov_b32_e32 v175, v129
	v_lshl_add_u64 v[176:177], v[176:177], 0, s[20:21]
	s_mov_b32 m0, s75
	v_lshl_add_u64 v[174:175], s[38:39], 0, v[174:175]
	v_readfirstlane_b32 s75, v146
	global_load_lds_dwordx4 v[176:177], off
	v_lshl_add_u64 v[174:175], v[174:175], 0, s[20:21]
	s_mov_b32 m0, s75
	s_nop 0
	global_load_lds_dwordx4 v[174:175], off
	s_waitcnt vmcnt(6)
	s_barrier
	v_mfma_f32_16x16x32_bf16 v[28:31], v[222:225], v[190:193], v[28:31]
	v_mfma_f32_16x16x32_bf16 v[24:27], v[230:233], v[190:193], v[24:27]
	v_mfma_f32_16x16x32_bf16 v[20:23], v[222:225], v[198:201], v[20:23]
	v_mfma_f32_16x16x32_bf16 v[16:19], v[230:233], v[198:201], v[16:19]
	v_mfma_f32_16x16x32_bf16 v[12:15], v[222:225], v[206:209], v[12:15]
	v_mfma_f32_16x16x32_bf16 v[8:11], v[230:233], v[206:209], v[8:11]
	v_mfma_f32_16x16x32_bf16 v[4:7], v[222:225], v[214:217], v[4:7]
	v_mfma_f32_16x16x32_bf16 v[0:3], v[230:233], v[214:217], v[0:3]
	v_mfma_f32_16x16x32_bf16 v[28:31], v[226:229], v[194:197], v[28:31]
	v_mfma_f32_16x16x32_bf16 v[24:27], v[234:237], v[194:197], v[24:27]
	v_mfma_f32_16x16x32_bf16 v[20:23], v[226:229], v[202:205], v[20:23]
	v_mfma_f32_16x16x32_bf16 v[16:19], v[234:237], v[202:205], v[16:19]
	v_mfma_f32_16x16x32_bf16 v[12:15], v[226:229], v[210:213], v[12:15]
	v_mfma_f32_16x16x32_bf16 v[8:11], v[234:237], v[210:213], v[8:11]
	v_mfma_f32_16x16x32_bf16 v[4:7], v[226:229], v[218:221], v[4:7]
	v_mfma_f32_16x16x32_bf16 v[0:3], v[234:237], v[218:221], v[0:3]
	v_add_u32_e32 v173, v157, v159
	v_add_u32_e32 v175, v157, v161
	s_barrier
	v_add_u32_e32 v174, v157, v160
	ds_read_b128 v[182:185], v173
	ds_read_b128 v[186:189], v174
	v_add_u32_e32 v176, v157, v162
	ds_read_b128 v[190:193], v175
	ds_read_b128 v[194:197], v176
	v_mov_b32_e32 v128, v130
	v_mov_b32_e32 v178, v131
	ds_read_b128 v[198:201], v132 offset:32768
	ds_read_b128 v[202:205], v133 offset:32768
	ds_read_b128 v[206:209], v135 offset:32768
	ds_read_b128 v[210:213], v136 offset:32768
	ds_read_b128 v[214:217], v137 offset:32768
	ds_read_b128 v[218:221], v138 offset:32768
	ds_read_b128 v[222:225], v139 offset:32768
	ds_read_b128 v[226:229], v140 offset:32768
	v_readfirstlane_b32 s75, v147
	v_lshl_add_u64 v[180:181], s[36:37], 0, v[128:129]
	v_mov_b32_e32 v179, v129
	v_lshl_add_u64 v[180:181], v[180:181], 0, s[22:23]
	s_mov_b32 m0, s75
	v_lshl_add_u64 v[178:179], s[36:37], 0, v[178:179]
	v_readfirstlane_b32 s75, v148
	global_load_lds_dwordx4 v[180:181], off
	v_lshl_add_u64 v[178:179], v[178:179], 0, s[22:23]
	s_mov_b32 m0, s75
	s_nop 0
	global_load_lds_dwordx4 v[178:179], off
	s_waitcnt lgkmcnt(8)
	s_barrier
	s_waitcnt lgkmcnt(0)
	s_waitcnt lgkmcnt(0)
	v_mfma_f32_16x16x32_bf16 v[124:127], v[182:185], v[198:201], v[124:127]
	v_mfma_f32_16x16x32_bf16 v[120:123], v[190:193], v[198:201], v[120:123]
	v_mfma_f32_16x16x32_bf16 v[116:119], v[182:185], v[206:209], v[116:119]
	v_mfma_f32_16x16x32_bf16 v[112:115], v[190:193], v[206:209], v[112:115]
	v_mfma_f32_16x16x32_bf16 v[108:111], v[182:185], v[214:217], v[108:111]
	v_mfma_f32_16x16x32_bf16 v[104:107], v[190:193], v[214:217], v[104:107]
	v_mfma_f32_16x16x32_bf16 v[100:103], v[182:185], v[222:225], v[100:103]
	v_mfma_f32_16x16x32_bf16 v[96:99], v[190:193], v[222:225], v[96:99]
	v_mfma_f32_16x16x32_bf16 v[124:127], v[186:189], v[202:205], v[124:127]
	v_mfma_f32_16x16x32_bf16 v[120:123], v[194:197], v[202:205], v[120:123]
	v_mfma_f32_16x16x32_bf16 v[116:119], v[186:189], v[210:213], v[116:119]
	v_mfma_f32_16x16x32_bf16 v[112:115], v[194:197], v[210:213], v[112:115]
	v_mfma_f32_16x16x32_bf16 v[108:111], v[186:189], v[218:221], v[108:111]
	v_mfma_f32_16x16x32_bf16 v[104:107], v[194:197], v[218:221], v[104:107]
	v_mfma_f32_16x16x32_bf16 v[100:103], v[186:189], v[226:229], v[100:103]
	v_mfma_f32_16x16x32_bf16 v[96:99], v[194:197], v[226:229], v[96:99]
	s_barrier
	v_add_u32_e32 v177, v158, v159
	v_add_u32_e32 v179, v158, v161
	v_mov_b32_e32 v128, v130
	v_mov_b32_e32 v246, v131
	v_add_u32_e32 v178, v158, v160
	ds_read_b128 v[230:233], v177
	ds_read_b128 v[234:237], v178
	v_add_u32_e32 v180, v158, v162
	ds_read_b128 v[238:241], v179
	ds_read_b128 v[242:245], v180
	v_readfirstlane_b32 s75, v149
	v_lshl_add_u64 v[248:249], s[38:39], 0, v[128:129]
	v_mov_b32_e32 v247, v129
	v_lshl_add_u64 v[248:249], v[248:249], 0, s[24:25]
	s_mov_b32 m0, s75
	v_lshl_add_u64 v[246:247], s[38:39], 0, v[246:247]
	v_readfirstlane_b32 s75, v150
	global_load_lds_dwordx4 v[248:249], off
	v_lshl_add_u64 v[246:247], v[246:247], 0, s[24:25]
	s_mov_b32 m0, s75
	s_nop 0
	global_load_lds_dwordx4 v[246:247], off
	s_barrier
; #define LDA(dst, b, h) for (int m = 0; m < 4; ++m) for (int k = 0; k < 2; ++k) \
;     dst[m][k] = *reinterpret_cast<const bf16x8*>((char*)SA(b, h) + lds_byte(wr * 64 + m * 16 + fr, k * 32 + fq * 8))
; #define LDB(dst, b, h) for (int n = 0; n < 2; ++n) for (int k = 0; k < 2; ++k) \
;     dst[n][k] = *reinterpret_cast<const bf16x8*>((char*)SB(b, h) + lds_byte(wc * 32 + n * 16 + fr, k * 32 + fq * 8))
; #define MMA(ai, bj, At_, Bt_) do { __builtin_amdgcn_s_setprio(1); \
;     for (int m = 0; m < 4; ++m) for (int n = 0; n < 2; ++n) for (int k = 0; k < 2; ++k) \
;       acc[ai][bj][m][n] = MFMA16(Bt_[n][k], At_[m][k], acc[ai][bj][m][n]); \
;     __builtin_amdgcn_s_setprio(0); } while (0)
; #define WAIT_V(n) asm volatile("s_waitcnt vmcnt(" #n ")" ::: "memory")
; #define WAIT_L(n) asm volatile("s_waitcnt lgkmcnt(" #n ")" ::: "memory")
; #define BAR __builtin_amdgcn_s_barrier()
; #define SCHED __builtin_amdgcn_sched_barrier(0)
; template <int PART  , bool SYNC_FIRST = true>
; __device__ __forceinline__ void kloop_t(const u16* __restrict__ A, int lda, const u16* __restrict__ Bt, int ldb, int K, Acc& acc, const int wv) {
;     ...
;     BAR; WAIT_L(0); MMA(0, 1, At, B1); BAR;
;     LDA(At, 1, 1); STAGE(SA(1, 0), A, lda, 0, t + 3);
;     BAR; WAIT_L(0); MMA(1, 0, At, B0); BAR; SCHED;
;     STAGE(SB(1, 1), Bt, ldb, HALF, t + 3);
;     WAIT_V(6); BAR; MMA(1, 1, At, B1); BAR;
;   }
;   { LDB(B0, 0, 0); LDA(At, 0, 0); STAGE(SA(1, 1), A, lda, HALF, nt - 1);
	s_waitcnt lgkmcnt(0)
	s_waitcnt lgkmcnt(0)
	v_mfma_f32_16x16x32_bf16 v[92:95], v[230:233], v[198:201], v[92:95]
	v_mfma_f32_16x16x32_bf16 v[88:91], v[238:241], v[198:201], v[88:91]
	v_mfma_f32_16x16x32_bf16 v[84:87], v[230:233], v[206:209], v[84:87]
	v_mfma_f32_16x16x32_bf16 v[80:83], v[238:241], v[206:209], v[80:83]
	v_mfma_f32_16x16x32_bf16 v[76:79], v[230:233], v[214:217], v[76:79]
	v_mfma_f32_16x16x32_bf16 v[72:75], v[238:241], v[214:217], v[72:75]
	v_mfma_f32_16x16x32_bf16 v[68:71], v[230:233], v[222:225], v[68:71]
	v_mfma_f32_16x16x32_bf16 v[64:67], v[238:241], v[222:225], v[64:67]
	v_mfma_f32_16x16x32_bf16 v[92:95], v[234:237], v[202:205], v[92:95]
	v_mfma_f32_16x16x32_bf16 v[88:91], v[242:245], v[202:205], v[88:91]
	v_mfma_f32_16x16x32_bf16 v[84:87], v[234:237], v[210:213], v[84:87]
	v_mfma_f32_16x16x32_bf16 v[80:83], v[242:245], v[210:213], v[80:83]
	v_mfma_f32_16x16x32_bf16 v[76:79], v[234:237], v[218:221], v[76:79]
	v_mfma_f32_16x16x32_bf16 v[72:75], v[242:245], v[218:221], v[72:75]
	v_mfma_f32_16x16x32_bf16 v[68:71], v[234:237], v[226:229], v[68:71]
	v_mfma_f32_16x16x32_bf16 v[64:67], v[242:245], v[226:229], v[64:67]
	v_mov_b32_e32 v128, v130
	v_mov_b32_e32 v246, v131
	s_barrier
	ds_read_b128 v[198:201], v132 offset:49152
	ds_read_b128 v[202:205], v133 offset:49152
	ds_read_b128 v[206:209], v135 offset:49152
	ds_read_b128 v[210:213], v136 offset:49152
	ds_read_b128 v[214:217], v137 offset:49152
	ds_read_b128 v[218:221], v138 offset:49152
	ds_read_b128 v[222:225], v139 offset:49152
	ds_read_b128 v[226:229], v140 offset:49152
	v_readfirstlane_b32 s75, v151
	v_lshl_add_u64 v[248:249], s[36:37], 0, v[128:129]
	v_mov_b32_e32 v247, v129
	v_lshl_add_u64 v[248:249], v[248:249], 0, s[26:27]
	s_mov_b32 m0, s75
	v_lshl_add_u64 v[246:247], s[36:37], 0, v[246:247]
	v_readfirstlane_b32 s36, v152
	global_load_lds_dwordx4 v[248:249], off
	v_lshl_add_u64 v[246:247], v[246:247], 0, s[26:27]
	s_mov_b32 m0, s36
	s_nop 0
	global_load_lds_dwordx4 v[246:247], off
	s_barrier
	s_waitcnt lgkmcnt(0)
	s_waitcnt lgkmcnt(0)
	v_mfma_f32_16x16x32_bf16 v[60:63], v[182:185], v[198:201], v[60:63]
	v_mfma_f32_16x16x32_bf16 v[56:59], v[190:193], v[198:201], v[56:59]
	v_mfma_f32_16x16x32_bf16 v[52:55], v[182:185], v[206:209], v[52:55]
	v_mfma_f32_16x16x32_bf16 v[48:51], v[190:193], v[206:209], v[48:51]
	v_mfma_f32_16x16x32_bf16 v[44:47], v[182:185], v[214:217], v[44:47]
	v_mfma_f32_16x16x32_bf16 v[40:43], v[190:193], v[214:217], v[40:43]
	v_mfma_f32_16x16x32_bf16 v[36:39], v[182:185], v[222:225], v[36:39]
	v_mfma_f32_16x16x32_bf16 v[32:35], v[190:193], v[222:225], v[32:35]
	v_mfma_f32_16x16x32_bf16 v[60:63], v[186:189], v[202:205], v[60:63]
	v_mfma_f32_16x16x32_bf16 v[56:59], v[194:197], v[202:205], v[56:59]
	v_mfma_f32_16x16x32_bf16 v[52:55], v[186:189], v[210:213], v[52:55]
	v_mfma_f32_16x16x32_bf16 v[48:51], v[194:197], v[210:213], v[48:51]
	v_mfma_f32_16x16x32_bf16 v[44:47], v[186:189], v[218:221], v[44:47]
	v_mfma_f32_16x16x32_bf16 v[40:43], v[194:197], v[218:221], v[40:43]
	v_mfma_f32_16x16x32_bf16 v[36:39], v[186:189], v[226:229], v[36:39]
	v_mfma_f32_16x16x32_bf16 v[32:35], v[194:197], v[226:229], v[32:35]
	s_barrier
	v_mov_b32_e32 v128, v130
	v_mov_b32_e32 v182, v131
	v_readfirstlane_b32 s36, v153
	v_lshl_add_u64 v[184:185], s[38:39], 0, v[128:129]
	v_mov_b32_e32 v183, v129
	v_lshl_add_u64 v[184:185], v[184:185], 0, s[28:29]
	s_mov_b32 m0, s36
	v_lshl_add_u64 v[182:183], s[38:39], 0, v[182:183]
	v_readfirstlane_b32 s36, v154
	global_load_lds_dwordx4 v[184:185], off
	v_lshl_add_u64 v[182:183], v[182:183], 0, s[28:29]
	s_mov_b32 m0, s36
	s_nop 0
	global_load_lds_dwordx4 v[182:183], off
	s_waitcnt vmcnt(6)
	s_barrier
	v_mfma_f32_16x16x32_bf16 v[28:31], v[230:233], v[198:201], v[28:31]
	v_mfma_f32_16x16x32_bf16 v[24:27], v[238:241], v[198:201], v[24:27]
	v_mfma_f32_16x16x32_bf16 v[20:23], v[230:233], v[206:209], v[20:23]
	v_mfma_f32_16x16x32_bf16 v[16:19], v[238:241], v[206:209], v[16:19]
	v_mfma_f32_16x16x32_bf16 v[12:15], v[230:233], v[214:217], v[12:15]
	v_mfma_f32_16x16x32_bf16 v[8:11], v[238:241], v[214:217], v[8:11]
	v_mfma_f32_16x16x32_bf16 v[4:7], v[230:233], v[222:225], v[4:7]
	v_mfma_f32_16x16x32_bf16 v[0:3], v[238:241], v[222:225], v[0:3]
	v_mfma_f32_16x16x32_bf16 v[28:31], v[234:237], v[202:205], v[28:31]
	v_mfma_f32_16x16x32_bf16 v[24:27], v[242:245], v[202:205], v[24:27]
	v_mfma_f32_16x16x32_bf16 v[20:23], v[234:237], v[210:213], v[20:23]
	v_mfma_f32_16x16x32_bf16 v[16:19], v[242:245], v[210:213], v[16:19]
	v_mfma_f32_16x16x32_bf16 v[12:15], v[234:237], v[218:221], v[12:15]
	v_mfma_f32_16x16x32_bf16 v[8:11], v[242:245], v[218:221], v[8:11]
	v_mfma_f32_16x16x32_bf16 v[4:7], v[234:237], v[226:229], v[4:7]
	v_mfma_f32_16x16x32_bf16 v[0:3], v[242:245], v[226:229], v[0:3]
	s_add_i32 s74, s74, 2
	s_add_u32 s34, s34, 0x100
	s_addc_u32 s35, s35, 0
	s_cmp_lt_u32 s74, 12
	s_barrier
	s_cbranch_scc1 .LBB0_980
	s_add_u32 s30, s30, 0x40780
	v_readfirstlane_b32 s34, v167
	s_addc_u32 s31, s31, 0
	s_mov_b32 m0, s34
	v_readfirstlane_b32 s34, v168
	ds_read_b128 v[142:145], v163
	ds_read_b128 v[146:149], v164
	ds_read_b128 v[150:153], v165
	ds_read_b128 v[154:157], v166
	ds_read_b128 v[158:161], v132
	ds_read_b128 v[162:165], v133
	ds_read_b128 v[182:185], v135
	ds_read_b128 v[186:189], v136
	ds_read_b128 v[190:193], v137
	ds_read_b128 v[194:197], v138
	ds_read_b128 v[198:201], v139
	ds_read_b128 v[202:205], v140
	s_nop 0
	global_load_lds_dwordx4 v130, s[30:31]
	s_mov_b32 m0, s34
	s_nop 0
	global_load_lds_dwordx4 v131, s[30:31]
	s_barrier
; #define LDA(dst, b, h) for (int m = 0; m < 4; ++m) for (int k = 0; k < 2; ++k) \
;     dst[m][k] = *reinterpret_cast<const bf16x8*>((char*)SA(b, h) + lds_byte(wr * 64 + m * 16 + fr, k * 32 + fq * 8))
; #define LDB(dst, b, h) for (int n = 0; n < 2; ++n) for (int k = 0; k < 2; ++k) \
;     dst[n][k] = *reinterpret_cast<const bf16x8*>((char*)SB(b, h) + lds_byte(wc * 32 + n * 16 + fr, k * 32 + fq * 8))
; #define MMA(ai, bj, At_, Bt_) do { __builtin_amdgcn_s_setprio(1); \
;     for (int m = 0; m < 4; ++m) for (int n = 0; n < 2; ++n) for (int k = 0; k < 2; ++k) \
;       acc[ai][bj][m][n] = MFMA16(Bt_[n][k], At_[m][k], acc[ai][bj][m][n]); \
;     __builtin_amdgcn_s_setprio(0); } while (0)
; #define WAIT_V(n) asm volatile("s_waitcnt vmcnt(" #n ")" ::: "memory")
; #define WAIT_L(n) asm volatile("s_waitcnt lgkmcnt(" #n ")" ::: "memory")
; #define BAR __builtin_amdgcn_s_barrier()
; template <int PART  , bool SYNC_FIRST = true>
; __device__ __forceinline__ void kloop_t(const u16* __restrict__ A, int lda, const u16* __restrict__ Bt, int ldb, int K, Acc& acc, const int wv) {
;     ...
;   { LDB(B0, 0, 0); LDA(At, 0, 0); STAGE(SA(1, 1), A, lda, HALF, nt - 1);
;     BAR; WAIT_L(0); MMA(0, 0, At, B0); BAR;
;     LDB(B1, 0, 1); BAR; WAIT_L(0); MMA(0, 1, At, B1); BAR;
;     LDA(At, 0, 1); WAIT_V(4); BAR; WAIT_L(0); MMA(1, 0, At, B0); MMA(1, 1, At, B1); BAR; }
	s_waitcnt lgkmcnt(0)
	s_waitcnt lgkmcnt(0)
	v_mfma_f32_16x16x32_bf16 v[124:127], v[142:145], v[158:161], v[124:127]
	v_mfma_f32_16x16x32_bf16 v[116:119], v[142:145], v[182:185], v[116:119]
	v_mfma_f32_16x16x32_bf16 v[112:115], v[150:153], v[182:185], v[112:115]
	v_mfma_f32_16x16x32_bf16 v[100:103], v[142:145], v[198:201], v[100:103]
	v_mfma_f32_16x16x32_bf16 v[96:99], v[150:153], v[198:201], v[96:99]
	v_mfma_f32_16x16x32_bf16 v[124:127], v[146:149], v[162:165], v[124:127]
	v_mfma_f32_16x16x32_bf16 v[120:123], v[150:153], v[158:161], v[120:123]
	v_mfma_f32_16x16x32_bf16 v[116:119], v[146:149], v[186:189], v[116:119]
	v_mfma_f32_16x16x32_bf16 v[112:115], v[154:157], v[186:189], v[112:115]
	v_mfma_f32_16x16x32_bf16 v[108:111], v[142:145], v[190:193], v[108:111]
	v_mfma_f32_16x16x32_bf16 v[104:107], v[150:153], v[190:193], v[104:107]
	v_mfma_f32_16x16x32_bf16 v[100:103], v[146:149], v[202:205], v[100:103]
	v_mfma_f32_16x16x32_bf16 v[96:99], v[154:157], v[202:205], v[96:99]
	v_mfma_f32_16x16x32_bf16 v[206:209], v[154:157], v[162:165], v[120:123]
	v_mfma_f32_16x16x32_bf16 v[210:213], v[146:149], v[194:197], v[108:111]
	v_mfma_f32_16x16x32_bf16 v[214:217], v[154:157], v[194:197], v[104:107]
	s_barrier
	s_nop 0
	ds_read_b128 v[104:107], v169
	ds_read_b128 v[108:111], v170
	ds_read_b128 v[120:123], v171
	ds_read_b128 v[166:169], v172
	s_barrier
	s_waitcnt lgkmcnt(0)
	s_waitcnt lgkmcnt(0)
	v_mfma_f32_16x16x32_bf16 v[84:87], v[104:107], v[182:185], v[84:87]
	v_mfma_f32_16x16x32_bf16 v[80:83], v[120:123], v[182:185], v[80:83]
	v_mfma_f32_16x16x32_bf16 v[68:71], v[104:107], v[198:201], v[68:71]
	v_mfma_f32_16x16x32_bf16 v[64:67], v[120:123], v[198:201], v[64:67]
	v_mfma_f32_16x16x32_bf16 v[92:95], v[104:107], v[158:161], v[92:95]
	v_mfma_f32_16x16x32_bf16 v[88:91], v[120:123], v[158:161], v[88:91]
	v_mfma_f32_16x16x32_bf16 v[84:87], v[108:111], v[186:189], v[84:87]
	v_mfma_f32_16x16x32_bf16 v[80:83], v[166:169], v[186:189], v[80:83]
	v_mfma_f32_16x16x32_bf16 v[76:79], v[104:107], v[190:193], v[76:79]
	v_mfma_f32_16x16x32_bf16 v[72:75], v[120:123], v[190:193], v[72:75]
	v_mfma_f32_16x16x32_bf16 v[68:71], v[108:111], v[202:205], v[68:71]
	v_mfma_f32_16x16x32_bf16 v[64:67], v[166:169], v[202:205], v[64:67]
	v_mfma_f32_16x16x32_bf16 v[218:221], v[108:111], v[162:165], v[92:95]
	v_mfma_f32_16x16x32_bf16 v[158:161], v[166:169], v[162:165], v[88:91]
	v_mfma_f32_16x16x32_bf16 v[162:165], v[108:111], v[194:197], v[76:79]
	v_mfma_f32_16x16x32_bf16 v[182:185], v[166:169], v[194:197], v[72:75]
	s_barrier
	s_nop 0
	ds_read_b128 v[72:75], v132 offset:16384
	ds_read_b128 v[76:79], v133 offset:16384
	ds_read_b128 v[88:91], v135 offset:16384
	ds_read_b128 v[92:95], v136 offset:16384
	ds_read_b128 v[186:189], v137 offset:16384
	ds_read_b128 v[190:193], v138 offset:16384
	ds_read_b128 v[194:197], v139 offset:16384
	ds_read_b128 v[198:201], v140 offset:16384
	s_waitcnt vmcnt(4)
	s_barrier
	s_waitcnt lgkmcnt(0)
	s_waitcnt lgkmcnt(0)
	v_mfma_f32_16x16x32_bf16 v[60:63], v[142:145], v[72:75], v[60:63]
	v_mfma_f32_16x16x32_bf16 v[52:55], v[142:145], v[88:91], v[52:55]
	v_mfma_f32_16x16x32_bf16 v[48:51], v[150:153], v[88:91], v[48:51]
	v_mfma_f32_16x16x32_bf16 v[36:39], v[142:145], v[194:197], v[36:39]
	v_mfma_f32_16x16x32_bf16 v[32:35], v[150:153], v[194:197], v[32:35]
	v_mfma_f32_16x16x32_bf16 v[60:63], v[146:149], v[76:79], v[60:63]
	v_mfma_f32_16x16x32_bf16 v[56:59], v[150:153], v[72:75], v[56:59]
	v_mfma_f32_16x16x32_bf16 v[52:55], v[146:149], v[92:95], v[52:55]
	v_mfma_f32_16x16x32_bf16 v[48:51], v[154:157], v[92:95], v[48:51]
	v_mfma_f32_16x16x32_bf16 v[44:47], v[142:145], v[186:189], v[44:47]
	v_mfma_f32_16x16x32_bf16 v[40:43], v[150:153], v[186:189], v[40:43]
	v_mfma_f32_16x16x32_bf16 v[36:39], v[146:149], v[198:201], v[36:39]
	v_mfma_f32_16x16x32_bf16 v[32:35], v[154:157], v[198:201], v[32:35]
	v_mfma_f32_16x16x32_bf16 v[202:205], v[154:157], v[76:79], v[56:59]
	v_mfma_f32_16x16x32_bf16 v[222:225], v[146:149], v[190:193], v[44:47]
	v_mfma_f32_16x16x32_bf16 v[226:229], v[154:157], v[190:193], v[40:43]
	v_mfma_f32_16x16x32_bf16 v[20:23], v[104:107], v[88:91], v[20:23]
	v_mfma_f32_16x16x32_bf16 v[16:19], v[120:123], v[88:91], v[16:19]
	v_mfma_f32_16x16x32_bf16 v[4:7], v[104:107], v[194:197], v[4:7]
	v_mfma_f32_16x16x32_bf16 v[0:3], v[120:123], v[194:197], v[0:3]
	v_mfma_f32_16x16x32_bf16 v[28:31], v[104:107], v[72:75], v[28:31]
	v_mfma_f32_16x16x32_bf16 v[24:27], v[120:123], v[72:75], v[24:27]
	v_mfma_f32_16x16x32_bf16 v[20:23], v[108:111], v[92:95], v[20:23]
	v_mfma_f32_16x16x32_bf16 v[16:19], v[166:169], v[92:95], v[16:19]
	v_mfma_f32_16x16x32_bf16 v[12:15], v[104:107], v[186:189], v[12:15]
	v_mfma_f32_16x16x32_bf16 v[8:11], v[120:123], v[186:189], v[8:11]
	v_mfma_f32_16x16x32_bf16 v[4:7], v[108:111], v[198:201], v[4:7]
	v_mfma_f32_16x16x32_bf16 v[0:3], v[166:169], v[198:201], v[0:3]
	v_mfma_f32_16x16x32_bf16 v[142:145], v[108:111], v[76:79], v[28:31]
	v_mfma_f32_16x16x32_bf16 v[146:149], v[166:169], v[76:79], v[24:27]
	v_mfma_f32_16x16x32_bf16 v[150:153], v[108:111], v[190:193], v[12:15]
	v_mfma_f32_16x16x32_bf16 v[154:157], v[166:169], v[190:193], v[8:11]
	s_barrier
; #define LDA(dst, b, h) for (int m = 0; m < 4; ++m) for (int k = 0; k < 2; ++k) \
;     dst[m][k] = *reinterpret_cast<const bf16x8*>((char*)SA(b, h) + lds_byte(wr * 64 + m * 16 + fr, k * 32 + fq * 8))
; #define LDB(dst, b, h) for (int n = 0; n < 2; ++n) for (int k = 0; k < 2; ++k) \
;     dst[n][k] = *reinterpret_cast<const bf16x8*>((char*)SB(b, h) + lds_byte(wc * 32 + n * 16 + fr, k * 32 + fq * 8))
; #define MMA(ai, bj, At_, Bt_) do { __builtin_amdgcn_s_setprio(1); \
;     for (int m = 0; m < 4; ++m) for (int n = 0; n < 2; ++n) for (int k = 0; k < 2; ++k) \
;       acc[ai][bj][m][n] = MFMA16(Bt_[n][k], At_[m][k], acc[ai][bj][m][n]); \
;     __builtin_amdgcn_s_setprio(0); } while (0)
; #define WAIT_V(n) asm volatile("s_waitcnt vmcnt(" #n ")" ::: "memory")
; #define WAIT_L(n) asm volatile("s_waitcnt lgkmcnt(" #n ")" ::: "memory")
; #define BAR __builtin_amdgcn_s_barrier()
; template <int PART  , bool SYNC_FIRST = true>
; __device__ __forceinline__ void kloop_t(const u16* __restrict__ A, int lda, const u16* __restrict__ Bt, int ldb, int K, Acc& acc, const int wv) {
;     ...
;   { LDB(B0, 1, 0); LDA(At, 1, 0); WAIT_V(2); BAR; WAIT_L(0); MMA(0, 0, At, B0); BAR;
;     LDB(B1, 1, 1); WAIT_V(0); BAR; WAIT_L(0); MMA(0, 1, At, B1); BAR;
;     LDA(At, 1, 1); BAR; WAIT_L(0); MMA(1, 0, At, B0); MMA(1, 1, At, B1); BAR; }
;   if (wr == 0) BAR;
	s_nop 0
	ds_read_b128 v[8:11], v173
	ds_read_b128 v[12:15], v174
	ds_read_b128 v[166:169], v175
	ds_read_b128 v[170:173], v176
	ds_read_b128 v[24:27], v132 offset:32768
	ds_read_b128 v[28:31], v133 offset:32768
	ds_read_b128 v[40:43], v135 offset:32768
	ds_read_b128 v[44:47], v136 offset:32768
	ds_read_b128 v[56:59], v137 offset:32768
	ds_read_b128 v[186:189], v138 offset:32768
	ds_read_b128 v[190:193], v139 offset:32768
	ds_read_b128 v[194:197], v140 offset:32768
	s_waitcnt vmcnt(2)
	s_barrier
	s_waitcnt lgkmcnt(0)
	s_waitcnt lgkmcnt(0)
	v_mfma_f32_16x16x32_bf16 v[72:75], v[8:11], v[24:27], v[124:127]
	v_mfma_f32_16x16x32_bf16 v[120:123], v[12:15], v[28:31], v[72:75]
	v_mfma_f32_16x16x32_bf16 v[72:75], v[166:169], v[24:27], v[206:209]
	v_mfma_f32_16x16x32_bf16 v[124:127], v[170:173], v[28:31], v[72:75]
	v_mfma_f32_16x16x32_bf16 v[72:75], v[8:11], v[40:43], v[116:119]
	v_mfma_f32_16x16x32_bf16 v[104:107], v[12:15], v[44:47], v[72:75]
	v_mfma_f32_16x16x32_bf16 v[72:75], v[166:169], v[40:43], v[112:115]
	v_mfma_f32_16x16x32_bf16 v[108:111], v[170:173], v[44:47], v[72:75]
	v_mfma_f32_16x16x32_bf16 v[72:75], v[8:11], v[56:59], v[210:213]
	v_mfma_f32_16x16x32_bf16 v[88:91], v[12:15], v[186:189], v[72:75]
	v_mfma_f32_16x16x32_bf16 v[72:75], v[166:169], v[56:59], v[214:217]
	v_mfma_f32_16x16x32_bf16 v[92:95], v[170:173], v[186:189], v[72:75]
	v_mfma_f32_16x16x32_bf16 v[72:75], v[8:11], v[190:193], v[100:103]
	v_mfma_f32_16x16x32_bf16 v[76:79], v[166:169], v[190:193], v[96:99]
	v_mfma_f32_16x16x32_bf16 v[72:75], v[12:15], v[194:197], v[72:75]
	v_mfma_f32_16x16x32_bf16 v[76:79], v[170:173], v[194:197], v[76:79]
	s_barrier
	ds_read_b128 v[174:177], v177
	ds_read_b128 v[198:201], v178
	ds_read_b128 v[206:209], v179
	ds_read_b128 v[178:181], v180
	s_waitcnt vmcnt(0)
	s_barrier
	s_waitcnt lgkmcnt(0)
	s_waitcnt lgkmcnt(0)
	v_mfma_f32_16x16x32_bf16 v[96:99], v[174:177], v[24:27], v[218:221]
	v_mfma_f32_16x16x32_bf16 v[24:27], v[206:209], v[24:27], v[158:161]
	v_mfma_f32_16x16x32_bf16 v[112:115], v[178:181], v[28:31], v[24:27]
	v_mfma_f32_16x16x32_bf16 v[24:27], v[174:177], v[40:43], v[84:87]
	v_mfma_f32_16x16x32_bf16 v[100:103], v[198:201], v[44:47], v[24:27]
	v_mfma_f32_16x16x32_bf16 v[24:27], v[206:209], v[40:43], v[80:83]
	v_mfma_f32_16x16x32_bf16 v[116:119], v[198:201], v[28:31], v[96:99]
	v_mfma_f32_16x16x32_bf16 v[96:99], v[178:181], v[44:47], v[24:27]
	v_mfma_f32_16x16x32_bf16 v[24:27], v[174:177], v[56:59], v[162:165]
	v_mfma_f32_16x16x32_bf16 v[84:87], v[198:201], v[186:189], v[24:27]
	v_mfma_f32_16x16x32_bf16 v[24:27], v[206:209], v[56:59], v[182:185]
	v_mfma_f32_16x16x32_bf16 v[80:83], v[178:181], v[186:189], v[24:27]
	v_mfma_f32_16x16x32_bf16 v[24:27], v[174:177], v[190:193], v[68:71]
	v_mfma_f32_16x16x32_bf16 v[68:71], v[198:201], v[194:197], v[24:27]
	v_mfma_f32_16x16x32_bf16 v[24:27], v[206:209], v[190:193], v[64:67]
	v_mfma_f32_16x16x32_bf16 v[64:67], v[178:181], v[194:197], v[24:27]
	s_barrier
	ds_read_b128 v[158:161], v132 offset:49152
	ds_read_b128 v[130:133], v133 offset:49152
	ds_read_b128 v[162:165], v135 offset:49152
	ds_read_b128 v[182:185], v136 offset:49152
	ds_read_b128 v[186:189], v137 offset:49152
	ds_read_b128 v[190:193], v138 offset:49152
	ds_read_b128 v[136:139], v139 offset:49152
	ds_read_b128 v[194:197], v140 offset:49152
	s_barrier
	s_waitcnt lgkmcnt(0)
	s_waitcnt lgkmcnt(0)
	v_mfma_f32_16x16x32_bf16 v[24:27], v[8:11], v[158:161], v[60:63]
	v_mfma_f32_16x16x32_bf16 v[56:59], v[12:15], v[130:133], v[24:27]
	v_mfma_f32_16x16x32_bf16 v[24:27], v[166:169], v[158:161], v[202:205]
	v_mfma_f32_16x16x32_bf16 v[60:63], v[170:173], v[130:133], v[24:27]
	v_mfma_f32_16x16x32_bf16 v[24:27], v[8:11], v[162:165], v[52:55]
	v_mfma_f32_16x16x32_bf16 v[40:43], v[12:15], v[182:185], v[24:27]
	v_mfma_f32_16x16x32_bf16 v[24:27], v[166:169], v[162:165], v[48:51]
	v_mfma_f32_16x16x32_bf16 v[44:47], v[170:173], v[182:185], v[24:27]
	v_mfma_f32_16x16x32_bf16 v[24:27], v[8:11], v[186:189], v[222:225]
	v_mfma_f32_16x16x32_bf16 v[8:11], v[8:11], v[136:139], v[36:39]
	v_mfma_f32_16x16x32_bf16 v[24:27], v[12:15], v[190:193], v[24:27]
	v_mfma_f32_16x16x32_bf16 v[28:31], v[166:169], v[186:189], v[226:229]
	v_mfma_f32_16x16x32_bf16 v[8:11], v[12:15], v[194:197], v[8:11]
	v_mfma_f32_16x16x32_bf16 v[12:15], v[166:169], v[136:139], v[32:35]
	v_mfma_f32_16x16x32_bf16 v[28:31], v[170:173], v[190:193], v[28:31]
	v_mfma_f32_16x16x32_bf16 v[12:15], v[170:173], v[194:197], v[12:15]
	v_mfma_f32_16x16x32_bf16 v[32:35], v[174:177], v[158:161], v[142:145]
	v_mfma_f32_16x16x32_bf16 v[52:55], v[198:201], v[130:133], v[32:35]
	v_mfma_f32_16x16x32_bf16 v[32:35], v[206:209], v[158:161], v[146:149]
	v_mfma_f32_16x16x32_bf16 v[16:19], v[206:209], v[162:165], v[16:19]
	v_mfma_f32_16x16x32_bf16 v[48:51], v[178:181], v[130:133], v[32:35]
	v_mfma_f32_16x16x32_bf16 v[20:23], v[174:177], v[162:165], v[20:23]
	v_mfma_f32_16x16x32_bf16 v[32:35], v[178:181], v[182:185], v[16:19]
	v_mfma_f32_16x16x32_bf16 v[16:19], v[174:177], v[186:189], v[150:153]
	v_mfma_f32_16x16x32_bf16 v[36:39], v[198:201], v[182:185], v[20:23]
	v_mfma_f32_16x16x32_bf16 v[20:23], v[198:201], v[190:193], v[16:19]
	v_mfma_f32_16x16x32_bf16 v[16:19], v[206:209], v[186:189], v[154:157]
	v_mfma_f32_16x16x32_bf16 v[4:7], v[174:177], v[136:139], v[4:7]
	v_mfma_f32_16x16x32_bf16 v[0:3], v[206:209], v[136:139], v[0:3]
	v_mfma_f32_16x16x32_bf16 v[16:19], v[178:181], v[190:193], v[16:19]
	v_mfma_f32_16x16x32_bf16 v[4:7], v[198:201], v[194:197], v[4:7]
	v_mfma_f32_16x16x32_bf16 v[0:3], v[178:181], v[194:197], v[0:3]
	s_andn2_b64 vcc, exec, s[0:1]
	s_barrier
	s_cbranch_vccnz .LBB0_983
	s_barrier

; #define LDA(dst, b, h) for (int m = 0; m < 4; ++m) for (int k = 0; k < 2; ++k) \
;     dst[m][k] = *reinterpret_cast<const bf16x8*>((char*)SA(b, h) + lds_byte(wr * 64 + m * 16 + fr, k * 32 + fq * 8))
; #define LDB(dst, b, h) for (int n = 0; n < 2; ++n) for (int k = 0; k < 2; ++k) \
;     dst[n][k] = *reinterpret_cast<const bf16x8*>((char*)SB(b, h) + lds_byte(wc * 32 + n * 16 + fr, k * 32 + fq * 8))
; #define MMA(ai, bj, At_, Bt_) do { __builtin_amdgcn_s_setprio(1); \
;     for (int m = 0; m < 4; ++m) for (int n = 0; n < 2; ++n) for (int k = 0; k < 2; ++k) \
;       acc[ai][bj][m][n] = MFMA16(Bt_[n][k], At_[m][k], acc[ai][bj][m][n]); \
;     __builtin_amdgcn_s_setprio(0); } while (0)
; #define WAIT_L(n) asm volatile("s_waitcnt lgkmcnt(" #n ")" ::: "memory")
; #define BAR __builtin_amdgcn_s_barrier()
; #define SCHED __builtin_amdgcn_sched_barrier(0)
; template <int PART  , bool SYNC_FIRST = true>
; __device__ __forceinline__ void kloop_t(const u16* __restrict__ A, int lda, const u16* __restrict__ Bt, int ldb, int K, Acc& acc, const int wv) {
;     ...
;   for (int t = 0; t < nt - 2; t += 2) {
;     LDB(B0, 0, 0); SCHED; LDA(At, 0, 0); STAGE(SA(1, 1), A, lda, HALF, t + 1);
;     WAIT_L(8); BAR; WAIT_L(0); MMA(0, 0, At, B0); BAR; SCHED;
;     LDB(B1, 0, 1); STAGE(SB(0, 0), Bt, ldb, 0, t + 2);
;     BAR; WAIT_L(0); MMA(0, 1, At, B1); BAR;
;     LDA(At, 0, 1); STAGE(SA(0, 0), A, lda, 0, t + 2);
.LBB0_1069:
	v_add_u32_e32 v158, v150, v154
	v_add_u32_e32 v160, v150, v156
	v_add_u32_e32 v159, v150, v155
	ds_read_b128 v[168:171], v158
	ds_read_b128 v[172:175], v159
	v_add_u32_e32 v161, v150, v157
	ds_read_b128 v[176:179], v160
	ds_read_b128 v[180:183], v161
	s_add_u32 s40, s38, s79
	v_mov_b32_e32 v128, v140
	v_mov_b32_e32 v164, v142
	s_addc_u32 s41, s39, 0
	ds_read_b128 v[184:187], v130
	ds_read_b128 v[188:191], v131
	ds_read_b128 v[192:195], v134
	ds_read_b128 v[196:199], v135
	ds_read_b128 v[200:203], v136
	ds_read_b128 v[204:207], v137
	ds_read_b128 v[208:211], v138
	ds_read_b128 v[212:215], v139
	v_mov_b32_e32 v165, v129
	v_lshl_add_u64 v[162:163], s[40:41], 0, v[128:129]
	v_lshl_add_u64 v[166:167], v[162:163], 0, s[18:19]
	v_add_u32_e32 v162, 0xc000, v145
	v_add_u32_e32 v163, 0xe000, v145
	v_readfirstlane_b32 s42, v162
	s_mov_b32 m0, s42
	v_lshl_add_u64 v[164:165], s[40:41], 0, v[164:165]
	v_readfirstlane_b32 s42, v163
	global_load_lds_dwordx4 v[166:167], off
	v_lshl_add_u64 v[164:165], v[164:165], 0, s[18:19]
	s_mov_b32 m0, s42
	s_nop 0
	global_load_lds_dwordx4 v[164:165], off
	s_waitcnt lgkmcnt(8)
	s_barrier
	s_waitcnt lgkmcnt(0)
	s_waitcnt lgkmcnt(0)
	v_mfma_f32_16x16x32_bf16 v[124:127], v[168:171], v[184:187], v[124:127]
	v_mfma_f32_16x16x32_bf16 v[120:123], v[176:179], v[184:187], v[120:123]
	v_mfma_f32_16x16x32_bf16 v[116:119], v[168:171], v[192:195], v[116:119]
	v_mfma_f32_16x16x32_bf16 v[112:115], v[176:179], v[192:195], v[112:115]
	v_mfma_f32_16x16x32_bf16 v[108:111], v[168:171], v[200:203], v[108:111]
	v_mfma_f32_16x16x32_bf16 v[104:107], v[176:179], v[200:203], v[104:107]
	v_mfma_f32_16x16x32_bf16 v[100:103], v[168:171], v[208:211], v[100:103]
	v_mfma_f32_16x16x32_bf16 v[96:99], v[176:179], v[208:211], v[96:99]
	v_mfma_f32_16x16x32_bf16 v[124:127], v[172:175], v[188:191], v[124:127]
	v_mfma_f32_16x16x32_bf16 v[120:123], v[180:183], v[188:191], v[120:123]
	v_mfma_f32_16x16x32_bf16 v[116:119], v[172:175], v[196:199], v[116:119]
	v_mfma_f32_16x16x32_bf16 v[112:115], v[180:183], v[196:199], v[112:115]
	v_mfma_f32_16x16x32_bf16 v[108:111], v[172:175], v[204:207], v[108:111]
	v_mfma_f32_16x16x32_bf16 v[104:107], v[180:183], v[204:207], v[104:107]
	v_mfma_f32_16x16x32_bf16 v[100:103], v[172:175], v[212:215], v[100:103]
	v_mfma_f32_16x16x32_bf16 v[96:99], v[180:183], v[212:215], v[96:99]
	s_barrier
	v_add_u32_e32 v164, v151, v154
	v_add_u32_e32 v166, v151, v156
	v_mov_b32_e32 v128, v140
	v_mov_b32_e32 v232, v142
	s_add_u32 s42, s38, s80
	v_add_u32_e32 v165, v151, v155
	ds_read_b128 v[216:219], v164
	ds_read_b128 v[220:223], v165
	v_add_u32_e32 v167, v151, v157
	ds_read_b128 v[224:227], v166
	ds_read_b128 v[228:231], v167
	s_addc_u32 s43, s39, 0
	v_lshl_add_u64 v[234:235], s[42:43], 0, v[128:129]
	v_add_u32_e32 v128, s54, v141
	v_mov_b32_e32 v233, v129
	v_readfirstlane_b32 s82, v128
	v_add_u32_e32 v128, 0x2000, v128
	v_lshl_add_u64 v[234:235], v[234:235], 0, s[20:21]
	s_mov_b32 m0, s82
	v_lshl_add_u64 v[232:233], s[42:43], 0, v[232:233]
	v_readfirstlane_b32 s82, v128
	global_load_lds_dwordx4 v[234:235], off
	v_lshl_add_u64 v[232:233], v[232:233], 0, s[20:21]
	s_mov_b32 m0, s82
	s_nop 0
	global_load_lds_dwordx4 v[232:233], off
	s_barrier
	s_waitcnt lgkmcnt(0)
	s_waitcnt lgkmcnt(0)
	v_mfma_f32_16x16x32_bf16 v[92:95], v[216:219], v[184:187], v[92:95]
	v_mfma_f32_16x16x32_bf16 v[88:91], v[224:227], v[184:187], v[88:91]
	v_mfma_f32_16x16x32_bf16 v[84:87], v[216:219], v[192:195], v[84:87]
	v_mfma_f32_16x16x32_bf16 v[80:83], v[224:227], v[192:195], v[80:83]
	v_mfma_f32_16x16x32_bf16 v[76:79], v[216:219], v[200:203], v[76:79]
	v_mfma_f32_16x16x32_bf16 v[72:75], v[224:227], v[200:203], v[72:75]
	v_mfma_f32_16x16x32_bf16 v[68:71], v[216:219], v[208:211], v[68:71]
	v_mfma_f32_16x16x32_bf16 v[64:67], v[224:227], v[208:211], v[64:67]
	v_mfma_f32_16x16x32_bf16 v[92:95], v[220:223], v[188:191], v[92:95]
	v_mfma_f32_16x16x32_bf16 v[88:91], v[228:231], v[188:191], v[88:91]
	v_mfma_f32_16x16x32_bf16 v[84:87], v[220:223], v[196:199], v[84:87]
	v_mfma_f32_16x16x32_bf16 v[80:83], v[228:231], v[196:199], v[80:83]
	v_mfma_f32_16x16x32_bf16 v[76:79], v[220:223], v[204:207], v[76:79]
	v_mfma_f32_16x16x32_bf16 v[72:75], v[228:231], v[204:207], v[72:75]
	v_mfma_f32_16x16x32_bf16 v[68:71], v[220:223], v[212:215], v[68:71]
	v_mfma_f32_16x16x32_bf16 v[64:67], v[228:231], v[212:215], v[64:67]
	v_mov_b32_e32 v128, v140
	v_mov_b32_e32 v232, v142
	s_barrier
	ds_read_b128 v[184:187], v130 offset:16384
	ds_read_b128 v[188:191], v131 offset:16384
	ds_read_b128 v[192:195], v134 offset:16384
	ds_read_b128 v[196:199], v135 offset:16384
	ds_read_b128 v[200:203], v136 offset:16384
	ds_read_b128 v[204:207], v137 offset:16384
	ds_read_b128 v[208:211], v138 offset:16384
	ds_read_b128 v[212:215], v139 offset:16384
	v_readfirstlane_b32 s82, v145
	v_lshl_add_u64 v[234:235], s[40:41], 0, v[128:129]
	v_mov_b32_e32 v233, v129
	v_add_u32_e32 v128, 0x2000, v145
	v_lshl_add_u64 v[234:235], v[234:235], 0, s[22:23]
	s_mov_b32 m0, s82
	v_lshl_add_u64 v[232:233], s[40:41], 0, v[232:233]
	v_readfirstlane_b32 s82, v128
	global_load_lds_dwordx4 v[234:235], off
	v_lshl_add_u64 v[232:233], v[232:233], 0, s[22:23]
	s_mov_b32 m0, s82
	s_nop 0
	global_load_lds_dwordx4 v[232:233], off
	s_barrier
; #define LDA(dst, b, h) for (int m = 0; m < 4; ++m) for (int k = 0; k < 2; ++k) \
;     dst[m][k] = *reinterpret_cast<const bf16x8*>((char*)SA(b, h) + lds_byte(wr * 64 + m * 16 + fr, k * 32 + fq * 8))
; #define LDB(dst, b, h) for (int n = 0; n < 2; ++n) for (int k = 0; k < 2; ++k) \
;     dst[n][k] = *reinterpret_cast<const bf16x8*>((char*)SB(b, h) + lds_byte(wc * 32 + n * 16 + fr, k * 32 + fq * 8))
; #define MMA(ai, bj, At_, Bt_) do { __builtin_amdgcn_s_setprio(1); \
;     for (int m = 0; m < 4; ++m) for (int n = 0; n < 2; ++n) for (int k = 0; k < 2; ++k) \
;       acc[ai][bj][m][n] = MFMA16(Bt_[n][k], At_[m][k], acc[ai][bj][m][n]); \
;     __builtin_amdgcn_s_setprio(0); } while (0)
; #define WAIT_V(n) asm volatile("s_waitcnt vmcnt(" #n ")" ::: "memory")
; #define WAIT_L(n) asm volatile("s_waitcnt lgkmcnt(" #n ")" ::: "memory")
; #define BAR __builtin_amdgcn_s_barrier()
; #define SCHED __builtin_amdgcn_sched_barrier(0)
; template <int PART  , bool SYNC_FIRST = true>
; __device__ __forceinline__ void kloop_t(const u16* __restrict__ A, int lda, const u16* __restrict__ Bt, int ldb, int K, Acc& acc, const int wv) {
;     ...
;     BAR; WAIT_L(0); MMA(1, 0, At, B0); BAR; SCHED;
;     STAGE(SB(0, 1), Bt, ldb, HALF, t + 2);
;     WAIT_V(6); BAR; MMA(1, 1, At, B1); BAR;
;     LDB(B0, 1, 0); SCHED; LDA(At, 1, 0); STAGE(SA(0, 1), A, lda, HALF, t + 2);
;     WAIT_L(8); BAR; WAIT_L(0); MMA(0, 0, At, B0); BAR; SCHED;
;     LDB(B1, 1, 1); STAGE(SB(1, 0), Bt, ldb, 0, t + 3);
	s_waitcnt lgkmcnt(0)
	s_waitcnt lgkmcnt(0)
	v_mfma_f32_16x16x32_bf16 v[60:63], v[168:171], v[184:187], v[60:63]
	v_mfma_f32_16x16x32_bf16 v[56:59], v[176:179], v[184:187], v[56:59]
	v_mfma_f32_16x16x32_bf16 v[52:55], v[168:171], v[192:195], v[52:55]
	v_mfma_f32_16x16x32_bf16 v[48:51], v[176:179], v[192:195], v[48:51]
	v_mfma_f32_16x16x32_bf16 v[44:47], v[168:171], v[200:203], v[44:47]
	v_mfma_f32_16x16x32_bf16 v[40:43], v[176:179], v[200:203], v[40:43]
	v_mfma_f32_16x16x32_bf16 v[36:39], v[168:171], v[208:211], v[36:39]
	v_mfma_f32_16x16x32_bf16 v[32:35], v[176:179], v[208:211], v[32:35]
	v_mfma_f32_16x16x32_bf16 v[60:63], v[172:175], v[188:191], v[60:63]
	v_mfma_f32_16x16x32_bf16 v[56:59], v[180:183], v[188:191], v[56:59]
	v_mfma_f32_16x16x32_bf16 v[52:55], v[172:175], v[196:199], v[52:55]
	v_mfma_f32_16x16x32_bf16 v[48:51], v[180:183], v[196:199], v[48:51]
	v_mfma_f32_16x16x32_bf16 v[44:47], v[172:175], v[204:207], v[44:47]
	v_mfma_f32_16x16x32_bf16 v[40:43], v[180:183], v[204:207], v[40:43]
	v_mfma_f32_16x16x32_bf16 v[36:39], v[172:175], v[212:215], v[36:39]
	v_mfma_f32_16x16x32_bf16 v[32:35], v[180:183], v[212:215], v[32:35]
	s_barrier
	v_mov_b32_e32 v128, v140
	v_mov_b32_e32 v168, v142
	v_mov_b32_e32 v169, v129
	v_lshl_add_u64 v[170:171], s[42:43], 0, v[128:129]
	v_add_u32_e32 v128, s55, v141
	v_lshl_add_u64 v[170:171], v[170:171], 0, s[24:25]
	v_readfirstlane_b32 s82, v128
	v_add_u32_e32 v128, 0x2000, v128
	s_mov_b32 m0, s82
	v_lshl_add_u64 v[168:169], s[42:43], 0, v[168:169]
	v_readfirstlane_b32 s82, v128
	global_load_lds_dwordx4 v[170:171], off
	v_lshl_add_u64 v[168:169], v[168:169], 0, s[24:25]
	s_mov_b32 m0, s82
	s_nop 0
	global_load_lds_dwordx4 v[168:169], off
	s_waitcnt vmcnt(6)
	s_barrier
	v_mfma_f32_16x16x32_bf16 v[28:31], v[216:219], v[184:187], v[28:31]
	v_mfma_f32_16x16x32_bf16 v[24:27], v[224:227], v[184:187], v[24:27]
	v_mfma_f32_16x16x32_bf16 v[20:23], v[216:219], v[192:195], v[20:23]
	v_mfma_f32_16x16x32_bf16 v[16:19], v[224:227], v[192:195], v[16:19]
	v_mfma_f32_16x16x32_bf16 v[12:15], v[216:219], v[200:203], v[12:15]
	v_mfma_f32_16x16x32_bf16 v[8:11], v[224:227], v[200:203], v[8:11]
	v_mfma_f32_16x16x32_bf16 v[4:7], v[216:219], v[208:211], v[4:7]
	v_mfma_f32_16x16x32_bf16 v[0:3], v[224:227], v[208:211], v[0:3]
	v_mfma_f32_16x16x32_bf16 v[28:31], v[220:223], v[188:191], v[28:31]
	v_mfma_f32_16x16x32_bf16 v[24:27], v[228:231], v[188:191], v[24:27]
	v_mfma_f32_16x16x32_bf16 v[20:23], v[220:223], v[196:199], v[20:23]
	v_mfma_f32_16x16x32_bf16 v[16:19], v[228:231], v[196:199], v[16:19]
	v_mfma_f32_16x16x32_bf16 v[12:15], v[220:223], v[204:207], v[12:15]
	v_mfma_f32_16x16x32_bf16 v[8:11], v[228:231], v[204:207], v[8:11]
	v_mfma_f32_16x16x32_bf16 v[4:7], v[220:223], v[212:215], v[4:7]
	v_mfma_f32_16x16x32_bf16 v[0:3], v[228:231], v[212:215], v[0:3]
	v_add_u32_e32 v168, v152, v154
	v_add_u32_e32 v170, v152, v156
	s_barrier
	v_add_u32_e32 v169, v152, v155
	ds_read_b128 v[176:179], v168
	ds_read_b128 v[180:183], v169
	v_add_u32_e32 v171, v152, v157
	ds_read_b128 v[184:187], v170
	ds_read_b128 v[188:191], v171
	v_mov_b32_e32 v128, v140
	v_mov_b32_e32 v172, v142
	ds_read_b128 v[192:195], v130 offset:32768
	ds_read_b128 v[196:199], v131 offset:32768
	ds_read_b128 v[200:203], v134 offset:32768
	ds_read_b128 v[204:207], v135 offset:32768
	ds_read_b128 v[208:211], v136 offset:32768
	ds_read_b128 v[212:215], v137 offset:32768
	ds_read_b128 v[216:219], v138 offset:32768
	ds_read_b128 v[220:223], v139 offset:32768
	v_mov_b32_e32 v173, v129
	v_lshl_add_u64 v[174:175], s[40:41], 0, v[128:129]
	v_add_u32_e32 v128, 0x4000, v145
	v_lshl_add_u64 v[174:175], v[174:175], 0, s[26:27]
	v_readfirstlane_b32 s82, v128
	v_add_u32_e32 v128, 0x6000, v145
	s_mov_b32 m0, s82
	v_lshl_add_u64 v[172:173], s[40:41], 0, v[172:173]
	v_readfirstlane_b32 s82, v128
	global_load_lds_dwordx4 v[174:175], off
	v_lshl_add_u64 v[172:173], v[172:173], 0, s[26:27]
	s_mov_b32 m0, s82
	s_nop 0
	global_load_lds_dwordx4 v[172:173], off
	s_waitcnt lgkmcnt(8)
	s_barrier
	s_waitcnt lgkmcnt(0)
	s_waitcnt lgkmcnt(0)
	v_mfma_f32_16x16x32_bf16 v[124:127], v[176:179], v[192:195], v[124:127]
	v_mfma_f32_16x16x32_bf16 v[120:123], v[184:187], v[192:195], v[120:123]
	v_mfma_f32_16x16x32_bf16 v[116:119], v[176:179], v[200:203], v[116:119]
	v_mfma_f32_16x16x32_bf16 v[112:115], v[184:187], v[200:203], v[112:115]
	v_mfma_f32_16x16x32_bf16 v[108:111], v[176:179], v[208:211], v[108:111]
	v_mfma_f32_16x16x32_bf16 v[104:107], v[184:187], v[208:211], v[104:107]
	v_mfma_f32_16x16x32_bf16 v[100:103], v[176:179], v[216:219], v[100:103]
	v_mfma_f32_16x16x32_bf16 v[96:99], v[184:187], v[216:219], v[96:99]
	v_mfma_f32_16x16x32_bf16 v[124:127], v[180:183], v[196:199], v[124:127]
	v_mfma_f32_16x16x32_bf16 v[120:123], v[188:191], v[196:199], v[120:123]
	v_mfma_f32_16x16x32_bf16 v[116:119], v[180:183], v[204:207], v[116:119]
	v_mfma_f32_16x16x32_bf16 v[112:115], v[188:191], v[204:207], v[112:115]
	v_mfma_f32_16x16x32_bf16 v[108:111], v[180:183], v[212:215], v[108:111]
	v_mfma_f32_16x16x32_bf16 v[104:107], v[188:191], v[212:215], v[104:107]
	v_mfma_f32_16x16x32_bf16 v[100:103], v[180:183], v[220:223], v[100:103]
	v_mfma_f32_16x16x32_bf16 v[96:99], v[188:191], v[220:223], v[96:99]
	s_barrier
	v_add_u32_e32 v172, v153, v154
	v_add_u32_e32 v174, v153, v156
	v_mov_b32_e32 v128, v140
	v_mov_b32_e32 v240, v142
	v_add_u32_e32 v173, v153, v155
	ds_read_b128 v[224:227], v172
	ds_read_b128 v[228:231], v173
	v_add_u32_e32 v175, v153, v157
	ds_read_b128 v[232:235], v174
	ds_read_b128 v[236:239], v175
	v_readfirstlane_b32 s82, v143
	v_lshl_add_u64 v[242:243], s[42:43], 0, v[128:129]
	v_mov_b32_e32 v241, v129
	v_lshl_add_u64 v[242:243], v[242:243], 0, s[28:29]
	s_mov_b32 m0, s82
	v_lshl_add_u64 v[240:241], s[42:43], 0, v[240:241]
	v_readfirstlane_b32 s82, v144
	global_load_lds_dwordx4 v[242:243], off
	v_lshl_add_u64 v[240:241], v[240:241], 0, s[28:29]
	s_mov_b32 m0, s82
	s_nop 0
	global_load_lds_dwordx4 v[240:241], off
	s_barrier
; #define LDA(dst, b, h) for (int m = 0; m < 4; ++m) for (int k = 0; k < 2; ++k) \
;     dst[m][k] = *reinterpret_cast<const bf16x8*>((char*)SA(b, h) + lds_byte(wr * 64 + m * 16 + fr, k * 32 + fq * 8))
; #define LDB(dst, b, h) for (int n = 0; n < 2; ++n) for (int k = 0; k < 2; ++k) \
;     dst[n][k] = *reinterpret_cast<const bf16x8*>((char*)SB(b, h) + lds_byte(wc * 32 + n * 16 + fr, k * 32 + fq * 8))
; #define MMA(ai, bj, At_, Bt_) do { __builtin_amdgcn_s_setprio(1); \
;     for (int m = 0; m < 4; ++m) for (int n = 0; n < 2; ++n) for (int k = 0; k < 2; ++k) \
;       acc[ai][bj][m][n] = MFMA16(Bt_[n][k], At_[m][k], acc[ai][bj][m][n]); \
;     __builtin_amdgcn_s_setprio(0); } while (0)
; #define WAIT_V(n) asm volatile("s_waitcnt vmcnt(" #n ")" ::: "memory")
; #define WAIT_L(n) asm volatile("s_waitcnt lgkmcnt(" #n ")" ::: "memory")
; #define BAR __builtin_amdgcn_s_barrier()
; #define SCHED __builtin_amdgcn_sched_barrier(0)
; template <int PART  , bool SYNC_FIRST = true>
; __device__ __forceinline__ void kloop_t(const u16* __restrict__ A, int lda, const u16* __restrict__ Bt, int ldb, int K, Acc& acc, const int wv) {
;     ...
;     BAR; WAIT_L(0); MMA(0, 1, At, B1); BAR;
;     LDA(At, 1, 1); STAGE(SA(1, 0), A, lda, 0, t + 3);
;     BAR; WAIT_L(0); MMA(1, 0, At, B0); BAR; SCHED;
;     STAGE(SB(1, 1), Bt, ldb, HALF, t + 3);
;     WAIT_V(6); BAR; MMA(1, 1, At, B1); BAR;
;   }
;   { LDB(B0, 0, 0); LDA(At, 0, 0); STAGE(SA(1, 1), A, lda, HALF, nt - 1);
	s_waitcnt lgkmcnt(0)
	s_waitcnt lgkmcnt(0)
	v_mfma_f32_16x16x32_bf16 v[92:95], v[224:227], v[192:195], v[92:95]
	v_mfma_f32_16x16x32_bf16 v[88:91], v[232:235], v[192:195], v[88:91]
	v_mfma_f32_16x16x32_bf16 v[84:87], v[224:227], v[200:203], v[84:87]
	v_mfma_f32_16x16x32_bf16 v[80:83], v[232:235], v[200:203], v[80:83]
	v_mfma_f32_16x16x32_bf16 v[76:79], v[224:227], v[208:211], v[76:79]
	v_mfma_f32_16x16x32_bf16 v[72:75], v[232:235], v[208:211], v[72:75]
	v_mfma_f32_16x16x32_bf16 v[68:71], v[224:227], v[216:219], v[68:71]
	v_mfma_f32_16x16x32_bf16 v[64:67], v[232:235], v[216:219], v[64:67]
	v_mfma_f32_16x16x32_bf16 v[92:95], v[228:231], v[196:199], v[92:95]
	v_mfma_f32_16x16x32_bf16 v[88:91], v[236:239], v[196:199], v[88:91]
	v_mfma_f32_16x16x32_bf16 v[84:87], v[228:231], v[204:207], v[84:87]
	v_mfma_f32_16x16x32_bf16 v[80:83], v[236:239], v[204:207], v[80:83]
	v_mfma_f32_16x16x32_bf16 v[76:79], v[228:231], v[212:215], v[76:79]
	v_mfma_f32_16x16x32_bf16 v[72:75], v[236:239], v[212:215], v[72:75]
	v_mfma_f32_16x16x32_bf16 v[68:71], v[228:231], v[220:223], v[68:71]
	v_mfma_f32_16x16x32_bf16 v[64:67], v[236:239], v[220:223], v[64:67]
	v_mov_b32_e32 v128, v140
	v_mov_b32_e32 v240, v142
	s_barrier
	ds_read_b128 v[192:195], v130 offset:49152
	ds_read_b128 v[196:199], v131 offset:49152
	ds_read_b128 v[200:203], v134 offset:49152
	ds_read_b128 v[204:207], v135 offset:49152
	ds_read_b128 v[208:211], v136 offset:49152
	ds_read_b128 v[212:215], v137 offset:49152
	ds_read_b128 v[216:219], v138 offset:49152
	ds_read_b128 v[220:223], v139 offset:49152
	v_readfirstlane_b32 s82, v146
	v_lshl_add_u64 v[242:243], s[40:41], 0, v[128:129]
	v_mov_b32_e32 v241, v129
	v_lshl_add_u64 v[242:243], v[242:243], 0, s[30:31]
	s_mov_b32 m0, s82
	v_lshl_add_u64 v[240:241], s[40:41], 0, v[240:241]
	v_readfirstlane_b32 s40, v147
	global_load_lds_dwordx4 v[242:243], off
	v_lshl_add_u64 v[240:241], v[240:241], 0, s[30:31]
	s_mov_b32 m0, s40
	s_nop 0
	global_load_lds_dwordx4 v[240:241], off
	s_barrier
	s_waitcnt lgkmcnt(0)
	s_waitcnt lgkmcnt(0)
	v_mfma_f32_16x16x32_bf16 v[60:63], v[176:179], v[192:195], v[60:63]
	v_mfma_f32_16x16x32_bf16 v[56:59], v[184:187], v[192:195], v[56:59]
	v_mfma_f32_16x16x32_bf16 v[52:55], v[176:179], v[200:203], v[52:55]
	v_mfma_f32_16x16x32_bf16 v[48:51], v[184:187], v[200:203], v[48:51]
	v_mfma_f32_16x16x32_bf16 v[44:47], v[176:179], v[208:211], v[44:47]
	v_mfma_f32_16x16x32_bf16 v[40:43], v[184:187], v[208:211], v[40:43]
	v_mfma_f32_16x16x32_bf16 v[36:39], v[176:179], v[216:219], v[36:39]
	v_mfma_f32_16x16x32_bf16 v[32:35], v[184:187], v[216:219], v[32:35]
	v_mfma_f32_16x16x32_bf16 v[60:63], v[180:183], v[196:199], v[60:63]
	v_mfma_f32_16x16x32_bf16 v[56:59], v[188:191], v[196:199], v[56:59]
	v_mfma_f32_16x16x32_bf16 v[52:55], v[180:183], v[204:207], v[52:55]
	v_mfma_f32_16x16x32_bf16 v[48:51], v[188:191], v[204:207], v[48:51]
	v_mfma_f32_16x16x32_bf16 v[44:47], v[180:183], v[212:215], v[44:47]
	v_mfma_f32_16x16x32_bf16 v[40:43], v[188:191], v[212:215], v[40:43]
	v_mfma_f32_16x16x32_bf16 v[36:39], v[180:183], v[220:223], v[36:39]
	v_mfma_f32_16x16x32_bf16 v[32:35], v[188:191], v[220:223], v[32:35]
	s_barrier
	v_mov_b32_e32 v128, v140
	v_mov_b32_e32 v176, v142
	v_readfirstlane_b32 s40, v148
	v_lshl_add_u64 v[178:179], s[42:43], 0, v[128:129]
	v_mov_b32_e32 v177, v129
	v_lshl_add_u64 v[178:179], v[178:179], 0, s[34:35]
	s_mov_b32 m0, s40
	v_lshl_add_u64 v[176:177], s[42:43], 0, v[176:177]
	v_readfirstlane_b32 s40, v149
	global_load_lds_dwordx4 v[178:179], off
	v_lshl_add_u64 v[176:177], v[176:177], 0, s[34:35]
	s_mov_b32 m0, s40
	s_nop 0
	global_load_lds_dwordx4 v[176:177], off
	s_waitcnt vmcnt(6)
	s_barrier
	v_mfma_f32_16x16x32_bf16 v[28:31], v[224:227], v[192:195], v[28:31]
	v_mfma_f32_16x16x32_bf16 v[24:27], v[232:235], v[192:195], v[24:27]
	v_mfma_f32_16x16x32_bf16 v[20:23], v[224:227], v[200:203], v[20:23]
	v_mfma_f32_16x16x32_bf16 v[16:19], v[232:235], v[200:203], v[16:19]
	v_mfma_f32_16x16x32_bf16 v[12:15], v[224:227], v[208:211], v[12:15]
	v_mfma_f32_16x16x32_bf16 v[8:11], v[232:235], v[208:211], v[8:11]
	v_mfma_f32_16x16x32_bf16 v[4:7], v[224:227], v[216:219], v[4:7]
	v_mfma_f32_16x16x32_bf16 v[0:3], v[232:235], v[216:219], v[0:3]
	v_mfma_f32_16x16x32_bf16 v[28:31], v[228:231], v[196:199], v[28:31]
	v_mfma_f32_16x16x32_bf16 v[24:27], v[236:239], v[196:199], v[24:27]
	v_mfma_f32_16x16x32_bf16 v[20:23], v[228:231], v[204:207], v[20:23]
	v_mfma_f32_16x16x32_bf16 v[16:19], v[236:239], v[204:207], v[16:19]
	v_mfma_f32_16x16x32_bf16 v[12:15], v[228:231], v[212:215], v[12:15]
	v_mfma_f32_16x16x32_bf16 v[8:11], v[236:239], v[212:215], v[8:11]
	v_mfma_f32_16x16x32_bf16 v[4:7], v[228:231], v[220:223], v[4:7]
	v_mfma_f32_16x16x32_bf16 v[0:3], v[236:239], v[220:223], v[0:3]
	s_add_i32 s81, s81, 2
	s_add_u32 s38, s38, 0x100
	s_addc_u32 s39, s39, 0
	s_cmp_lt_u32 s81, 12
	s_barrier
	s_cbranch_scc1 .LBB0_1069
	s_add_u32 s36, s36, 0x40780
	v_readfirstlane_b32 s38, v162
	s_addc_u32 s37, s37, 0
	s_mov_b32 m0, s38
	v_readfirstlane_b32 s38, v163
	ds_read_b128 v[144:147], v158
	ds_read_b128 v[148:151], v159
	ds_read_b128 v[152:155], v160
	ds_read_b128 v[156:159], v161
	ds_read_b128 v[176:179], v130
	ds_read_b128 v[180:183], v131
	ds_read_b128 v[184:187], v134
	ds_read_b128 v[188:191], v135
	ds_read_b128 v[192:195], v136
	ds_read_b128 v[196:199], v137
	ds_read_b128 v[200:203], v138
	ds_read_b128 v[204:207], v139
	s_nop 0
	global_load_lds_dwordx4 v140, s[36:37]
	s_mov_b32 m0, s38
	s_nop 0
	global_load_lds_dwordx4 v142, s[36:37]
	s_barrier
; #define LDA(dst, b, h) for (int m = 0; m < 4; ++m) for (int k = 0; k < 2; ++k) \
;     dst[m][k] = *reinterpret_cast<const bf16x8*>((char*)SA(b, h) + lds_byte(wr * 64 + m * 16 + fr, k * 32 + fq * 8))
; #define LDB(dst, b, h) for (int n = 0; n < 2; ++n) for (int k = 0; k < 2; ++k) \
;     dst[n][k] = *reinterpret_cast<const bf16x8*>((char*)SB(b, h) + lds_byte(wc * 32 + n * 16 + fr, k * 32 + fq * 8))
; #define MMA(ai, bj, At_, Bt_) do { __builtin_amdgcn_s_setprio(1); \
;     for (int m = 0; m < 4; ++m) for (int n = 0; n < 2; ++n) for (int k = 0; k < 2; ++k) \
;       acc[ai][bj][m][n] = MFMA16(Bt_[n][k], At_[m][k], acc[ai][bj][m][n]); \
;     __builtin_amdgcn_s_setprio(0); } while (0)
; #define WAIT_V(n) asm volatile("s_waitcnt vmcnt(" #n ")" ::: "memory")
; #define WAIT_L(n) asm volatile("s_waitcnt lgkmcnt(" #n ")" ::: "memory")
; #define BAR __builtin_amdgcn_s_barrier()
; template <int PART  , bool SYNC_FIRST = true>
; __device__ __forceinline__ void kloop_t(const u16* __restrict__ A, int lda, const u16* __restrict__ Bt, int ldb, int K, Acc& acc, const int wv) {
;     ...
;   { LDB(B0, 0, 0); LDA(At, 0, 0); STAGE(SA(1, 1), A, lda, HALF, nt - 1);
;     BAR; WAIT_L(0); MMA(0, 0, At, B0); BAR;
;     LDB(B1, 0, 1); BAR; WAIT_L(0); MMA(0, 1, At, B1); BAR;
;     LDA(At, 0, 1); WAIT_V(4); BAR; WAIT_L(0); MMA(1, 0, At, B0); MMA(1, 1, At, B1); BAR; }
	s_waitcnt lgkmcnt(0)
	s_waitcnt lgkmcnt(0)
	v_mfma_f32_16x16x32_bf16 v[124:127], v[144:147], v[176:179], v[124:127]
	v_mfma_f32_16x16x32_bf16 v[120:123], v[152:155], v[176:179], v[120:123]
	v_mfma_f32_16x16x32_bf16 v[116:119], v[144:147], v[184:187], v[116:119]
	v_mfma_f32_16x16x32_bf16 v[112:115], v[152:155], v[184:187], v[112:115]
	v_mfma_f32_16x16x32_bf16 v[100:103], v[144:147], v[200:203], v[100:103]
	v_mfma_f32_16x16x32_bf16 v[96:99], v[152:155], v[200:203], v[96:99]
	v_mfma_f32_16x16x32_bf16 v[124:127], v[148:151], v[180:183], v[124:127]
	v_mfma_f32_16x16x32_bf16 v[120:123], v[156:159], v[180:183], v[120:123]
	v_mfma_f32_16x16x32_bf16 v[116:119], v[148:151], v[188:191], v[116:119]
	v_mfma_f32_16x16x32_bf16 v[112:115], v[156:159], v[188:191], v[112:115]
	v_mfma_f32_16x16x32_bf16 v[108:111], v[144:147], v[192:195], v[108:111]
	v_mfma_f32_16x16x32_bf16 v[104:107], v[152:155], v[192:195], v[104:107]
	v_mfma_f32_16x16x32_bf16 v[100:103], v[148:151], v[204:207], v[100:103]
	v_mfma_f32_16x16x32_bf16 v[96:99], v[156:159], v[204:207], v[96:99]
	v_mfma_f32_16x16x32_bf16 v[140:143], v[148:151], v[196:199], v[108:111]
	v_mfma_f32_16x16x32_bf16 v[160:163], v[156:159], v[196:199], v[104:107]
	s_barrier
	s_nop 1
	ds_read_b128 v[104:107], v164
	ds_read_b128 v[108:111], v165
	ds_read_b128 v[208:211], v166
	ds_read_b128 v[164:167], v167
	s_barrier
	s_waitcnt lgkmcnt(0)
	s_waitcnt lgkmcnt(0)
	v_mfma_f32_16x16x32_bf16 v[84:87], v[104:107], v[184:187], v[84:87]
	v_mfma_f32_16x16x32_bf16 v[80:83], v[208:211], v[184:187], v[80:83]
	v_mfma_f32_16x16x32_bf16 v[68:71], v[104:107], v[200:203], v[68:71]
	v_mfma_f32_16x16x32_bf16 v[64:67], v[208:211], v[200:203], v[64:67]
	v_mfma_f32_16x16x32_bf16 v[92:95], v[104:107], v[176:179], v[92:95]
	v_mfma_f32_16x16x32_bf16 v[88:91], v[208:211], v[176:179], v[88:91]
	v_mfma_f32_16x16x32_bf16 v[84:87], v[108:111], v[188:191], v[84:87]
	v_mfma_f32_16x16x32_bf16 v[80:83], v[164:167], v[188:191], v[80:83]
	v_mfma_f32_16x16x32_bf16 v[76:79], v[104:107], v[192:195], v[76:79]
	v_mfma_f32_16x16x32_bf16 v[72:75], v[208:211], v[192:195], v[72:75]
	v_mfma_f32_16x16x32_bf16 v[68:71], v[108:111], v[204:207], v[68:71]
	v_mfma_f32_16x16x32_bf16 v[64:67], v[164:167], v[204:207], v[64:67]
	v_mfma_f32_16x16x32_bf16 v[212:215], v[108:111], v[180:183], v[92:95]
	v_mfma_f32_16x16x32_bf16 v[176:179], v[164:167], v[180:183], v[88:91]
	v_mfma_f32_16x16x32_bf16 v[180:183], v[108:111], v[196:199], v[76:79]
	v_mfma_f32_16x16x32_bf16 v[184:187], v[164:167], v[196:199], v[72:75]
	s_barrier
	s_nop 0
	ds_read_b128 v[72:75], v130 offset:16384
	ds_read_b128 v[76:79], v131 offset:16384
	ds_read_b128 v[88:91], v134 offset:16384
	ds_read_b128 v[92:95], v135 offset:16384
	ds_read_b128 v[188:191], v136 offset:16384
	ds_read_b128 v[192:195], v137 offset:16384
	ds_read_b128 v[196:199], v138 offset:16384
	ds_read_b128 v[200:203], v139 offset:16384
	s_waitcnt vmcnt(4)
	s_barrier
	s_waitcnt lgkmcnt(0)
	s_waitcnt lgkmcnt(0)
	v_mfma_f32_16x16x32_bf16 v[60:63], v[144:147], v[72:75], v[60:63]
	v_mfma_f32_16x16x32_bf16 v[56:59], v[152:155], v[72:75], v[56:59]
	v_mfma_f32_16x16x32_bf16 v[52:55], v[144:147], v[88:91], v[52:55]
	v_mfma_f32_16x16x32_bf16 v[48:51], v[152:155], v[88:91], v[48:51]
	v_mfma_f32_16x16x32_bf16 v[36:39], v[144:147], v[196:199], v[36:39]
	v_mfma_f32_16x16x32_bf16 v[32:35], v[152:155], v[196:199], v[32:35]
	v_mfma_f32_16x16x32_bf16 v[60:63], v[148:151], v[76:79], v[60:63]
	v_mfma_f32_16x16x32_bf16 v[56:59], v[156:159], v[76:79], v[56:59]
	v_mfma_f32_16x16x32_bf16 v[52:55], v[148:151], v[92:95], v[52:55]
	v_mfma_f32_16x16x32_bf16 v[48:51], v[156:159], v[92:95], v[48:51]
	v_mfma_f32_16x16x32_bf16 v[44:47], v[144:147], v[188:191], v[44:47]
	v_mfma_f32_16x16x32_bf16 v[40:43], v[152:155], v[188:191], v[40:43]
	v_mfma_f32_16x16x32_bf16 v[36:39], v[148:151], v[200:203], v[36:39]
	v_mfma_f32_16x16x32_bf16 v[32:35], v[156:159], v[200:203], v[32:35]
	v_mfma_f32_16x16x32_bf16 v[204:207], v[148:151], v[192:195], v[44:47]
	v_mfma_f32_16x16x32_bf16 v[216:219], v[156:159], v[192:195], v[40:43]
	v_mfma_f32_16x16x32_bf16 v[20:23], v[104:107], v[88:91], v[20:23]
	v_mfma_f32_16x16x32_bf16 v[16:19], v[208:211], v[88:91], v[16:19]
	v_mfma_f32_16x16x32_bf16 v[4:7], v[104:107], v[196:199], v[4:7]
	v_mfma_f32_16x16x32_bf16 v[0:3], v[208:211], v[196:199], v[0:3]
	v_mfma_f32_16x16x32_bf16 v[28:31], v[104:107], v[72:75], v[28:31]
	v_mfma_f32_16x16x32_bf16 v[24:27], v[208:211], v[72:75], v[24:27]
	v_mfma_f32_16x16x32_bf16 v[20:23], v[108:111], v[92:95], v[20:23]
	v_mfma_f32_16x16x32_bf16 v[16:19], v[164:167], v[92:95], v[16:19]
	v_mfma_f32_16x16x32_bf16 v[12:15], v[104:107], v[188:191], v[12:15]
	v_mfma_f32_16x16x32_bf16 v[8:11], v[208:211], v[188:191], v[8:11]
	v_mfma_f32_16x16x32_bf16 v[4:7], v[108:111], v[200:203], v[4:7]
	v_mfma_f32_16x16x32_bf16 v[0:3], v[164:167], v[200:203], v[0:3]
	v_mfma_f32_16x16x32_bf16 v[144:147], v[108:111], v[76:79], v[28:31]
	v_mfma_f32_16x16x32_bf16 v[148:151], v[164:167], v[76:79], v[24:27]
	v_mfma_f32_16x16x32_bf16 v[152:155], v[108:111], v[192:195], v[12:15]
	v_mfma_f32_16x16x32_bf16 v[156:159], v[164:167], v[192:195], v[8:11]
	s_barrier
; #define LDA(dst, b, h) for (int m = 0; m < 4; ++m) for (int k = 0; k < 2; ++k) \
;     dst[m][k] = *reinterpret_cast<const bf16x8*>((char*)SA(b, h) + lds_byte(wr * 64 + m * 16 + fr, k * 32 + fq * 8))
; #define LDB(dst, b, h) for (int n = 0; n < 2; ++n) for (int k = 0; k < 2; ++k) \
;     dst[n][k] = *reinterpret_cast<const bf16x8*>((char*)SB(b, h) + lds_byte(wc * 32 + n * 16 + fr, k * 32 + fq * 8))
; #define MMA(ai, bj, At_, Bt_) do { __builtin_amdgcn_s_setprio(1); \
;     for (int m = 0; m < 4; ++m) for (int n = 0; n < 2; ++n) for (int k = 0; k < 2; ++k) \
;       acc[ai][bj][m][n] = MFMA16(Bt_[n][k], At_[m][k], acc[ai][bj][m][n]); \
;     __builtin_amdgcn_s_setprio(0); } while (0)
; #define WAIT_V(n) asm volatile("s_waitcnt vmcnt(" #n ")" ::: "memory")
; #define WAIT_L(n) asm volatile("s_waitcnt lgkmcnt(" #n ")" ::: "memory")
; #define BAR __builtin_amdgcn_s_barrier()
; template <int PART  , bool SYNC_FIRST = true>
; __device__ __forceinline__ void kloop_t(const u16* __restrict__ A, int lda, const u16* __restrict__ Bt, int ldb, int K, Acc& acc, const int wv) {
;     ...
;   { LDB(B0, 1, 0); LDA(At, 1, 0); WAIT_V(2); BAR; WAIT_L(0); MMA(0, 0, At, B0); BAR;
;     LDB(B1, 1, 1); WAIT_V(0); BAR; WAIT_L(0); MMA(0, 1, At, B1); BAR;
;     LDA(At, 1, 1); BAR; WAIT_L(0); MMA(1, 0, At, B0); MMA(1, 1, At, B1); BAR; }
;   if (wr == 0) BAR;
	s_nop 0
	ds_read_b128 v[8:11], v168
	ds_read_b128 v[12:15], v169
	ds_read_b128 v[164:167], v170
	ds_read_b128 v[168:171], v171
	ds_read_b128 v[24:27], v130 offset:32768
	ds_read_b128 v[28:31], v131 offset:32768
	ds_read_b128 v[40:43], v134 offset:32768
	ds_read_b128 v[44:47], v135 offset:32768
	ds_read_b128 v[188:191], v136 offset:32768
	ds_read_b128 v[192:195], v137 offset:32768
	ds_read_b128 v[196:199], v138 offset:32768
	ds_read_b128 v[200:203], v139 offset:32768
	s_waitcnt vmcnt(2)
	s_barrier
	s_waitcnt lgkmcnt(0)
	s_waitcnt lgkmcnt(0)
	v_mfma_f32_16x16x32_bf16 v[72:75], v[8:11], v[24:27], v[124:127]
	v_mfma_f32_16x16x32_bf16 v[124:127], v[12:15], v[28:31], v[72:75]
	v_mfma_f32_16x16x32_bf16 v[72:75], v[164:167], v[24:27], v[120:123]
	v_mfma_f32_16x16x32_bf16 v[120:123], v[168:171], v[28:31], v[72:75]
	v_mfma_f32_16x16x32_bf16 v[72:75], v[8:11], v[40:43], v[116:119]
	v_mfma_f32_16x16x32_bf16 v[108:111], v[12:15], v[44:47], v[72:75]
	v_mfma_f32_16x16x32_bf16 v[72:75], v[164:167], v[40:43], v[112:115]
	v_mfma_f32_16x16x32_bf16 v[104:107], v[168:171], v[44:47], v[72:75]
	v_mfma_f32_16x16x32_bf16 v[72:75], v[8:11], v[188:191], v[140:143]
	v_mfma_f32_16x16x32_bf16 v[92:95], v[12:15], v[192:195], v[72:75]
	v_mfma_f32_16x16x32_bf16 v[72:75], v[164:167], v[188:191], v[160:163]
	v_mfma_f32_16x16x32_bf16 v[88:91], v[168:171], v[192:195], v[72:75]
	v_mfma_f32_16x16x32_bf16 v[72:75], v[8:11], v[196:199], v[100:103]
	v_mfma_f32_16x16x32_bf16 v[76:79], v[12:15], v[200:203], v[72:75]
	v_mfma_f32_16x16x32_bf16 v[72:75], v[164:167], v[196:199], v[96:99]
	v_mfma_f32_16x16x32_bf16 v[72:75], v[168:171], v[200:203], v[72:75]
	s_barrier
	ds_read_b128 v[140:143], v172
	ds_read_b128 v[160:163], v173
	ds_read_b128 v[208:211], v174
	ds_read_b128 v[172:175], v175
	s_waitcnt vmcnt(0)
	s_barrier
	s_waitcnt lgkmcnt(0)
	s_waitcnt lgkmcnt(0)
	v_mfma_f32_16x16x32_bf16 v[96:99], v[140:143], v[24:27], v[212:215]
	v_mfma_f32_16x16x32_bf16 v[24:27], v[208:211], v[24:27], v[176:179]
	v_mfma_f32_16x16x32_bf16 v[112:115], v[172:175], v[28:31], v[24:27]
	v_mfma_f32_16x16x32_bf16 v[24:27], v[140:143], v[40:43], v[84:87]
	v_mfma_f32_16x16x32_bf16 v[100:103], v[160:163], v[44:47], v[24:27]
	v_mfma_f32_16x16x32_bf16 v[24:27], v[208:211], v[40:43], v[80:83]
	v_mfma_f32_16x16x32_bf16 v[116:119], v[160:163], v[28:31], v[96:99]
	v_mfma_f32_16x16x32_bf16 v[96:99], v[172:175], v[44:47], v[24:27]
	v_mfma_f32_16x16x32_bf16 v[24:27], v[140:143], v[188:191], v[180:183]
	v_mfma_f32_16x16x32_bf16 v[84:87], v[160:163], v[192:195], v[24:27]
	v_mfma_f32_16x16x32_bf16 v[24:27], v[208:211], v[188:191], v[184:187]
	v_mfma_f32_16x16x32_bf16 v[80:83], v[172:175], v[192:195], v[24:27]
	v_mfma_f32_16x16x32_bf16 v[24:27], v[140:143], v[196:199], v[68:71]
	v_mfma_f32_16x16x32_bf16 v[68:71], v[160:163], v[200:203], v[24:27]
	v_mfma_f32_16x16x32_bf16 v[24:27], v[208:211], v[196:199], v[64:67]
	v_mfma_f32_16x16x32_bf16 v[64:67], v[172:175], v[200:203], v[24:27]
	s_barrier
	ds_read_b128 v[176:179], v130 offset:49152
	ds_read_b128 v[180:183], v131 offset:49152
	ds_read_b128 v[184:187], v134 offset:49152
	ds_read_b128 v[188:191], v135 offset:49152
	ds_read_b128 v[192:195], v136 offset:49152
	ds_read_b128 v[134:137], v137 offset:49152
	ds_read_b128 v[196:199], v138 offset:49152
	ds_read_b128 v[200:203], v139 offset:49152
	s_barrier
	s_waitcnt lgkmcnt(0)
	s_waitcnt lgkmcnt(0)
	v_mfma_f32_16x16x32_bf16 v[24:27], v[8:11], v[176:179], v[60:63]
	v_mfma_f32_16x16x32_bf16 v[60:63], v[12:15], v[180:183], v[24:27]
	v_mfma_f32_16x16x32_bf16 v[24:27], v[164:167], v[176:179], v[56:59]
	v_mfma_f32_16x16x32_bf16 v[56:59], v[168:171], v[180:183], v[24:27]
	v_mfma_f32_16x16x32_bf16 v[24:27], v[8:11], v[184:187], v[52:55]
	v_mfma_f32_16x16x32_bf16 v[44:47], v[12:15], v[188:191], v[24:27]
	v_mfma_f32_16x16x32_bf16 v[24:27], v[164:167], v[184:187], v[48:51]
	v_mfma_f32_16x16x32_bf16 v[40:43], v[168:171], v[188:191], v[24:27]
	v_mfma_f32_16x16x32_bf16 v[24:27], v[8:11], v[192:195], v[204:207]
	v_mfma_f32_16x16x32_bf16 v[8:11], v[8:11], v[196:199], v[36:39]
	v_mfma_f32_16x16x32_bf16 v[28:31], v[12:15], v[134:137], v[24:27]
	v_mfma_f32_16x16x32_bf16 v[24:27], v[164:167], v[192:195], v[216:219]
	v_mfma_f32_16x16x32_bf16 v[12:15], v[12:15], v[200:203], v[8:11]
	v_mfma_f32_16x16x32_bf16 v[8:11], v[164:167], v[196:199], v[32:35]
	v_mfma_f32_16x16x32_bf16 v[24:27], v[168:171], v[134:137], v[24:27]
	v_mfma_f32_16x16x32_bf16 v[8:11], v[168:171], v[200:203], v[8:11]
	v_mfma_f32_16x16x32_bf16 v[32:35], v[140:143], v[176:179], v[144:147]
	v_mfma_f32_16x16x32_bf16 v[52:55], v[160:163], v[180:183], v[32:35]
	v_mfma_f32_16x16x32_bf16 v[32:35], v[208:211], v[176:179], v[148:151]
	v_mfma_f32_16x16x32_bf16 v[16:19], v[208:211], v[184:187], v[16:19]
	v_mfma_f32_16x16x32_bf16 v[48:51], v[172:175], v[180:183], v[32:35]
	v_mfma_f32_16x16x32_bf16 v[20:23], v[140:143], v[184:187], v[20:23]
	v_mfma_f32_16x16x32_bf16 v[32:35], v[172:175], v[188:191], v[16:19]
	v_mfma_f32_16x16x32_bf16 v[16:19], v[140:143], v[192:195], v[152:155]
	v_mfma_f32_16x16x32_bf16 v[36:39], v[160:163], v[188:191], v[20:23]
	v_mfma_f32_16x16x32_bf16 v[20:23], v[160:163], v[134:137], v[16:19]
	v_mfma_f32_16x16x32_bf16 v[16:19], v[208:211], v[192:195], v[156:159]
	v_mfma_f32_16x16x32_bf16 v[4:7], v[140:143], v[196:199], v[4:7]
	v_mfma_f32_16x16x32_bf16 v[0:3], v[208:211], v[196:199], v[0:3]
	v_mfma_f32_16x16x32_bf16 v[16:19], v[172:175], v[134:137], v[16:19]
	v_mfma_f32_16x16x32_bf16 v[4:7], v[160:163], v[200:203], v[4:7]
	v_mfma_f32_16x16x32_bf16 v[0:3], v[172:175], v[200:203], v[0:3]
	s_andn2_b64 vcc, exec, s[14:15]
	s_barrier
	s_cbranch_vccnz .LBB0_1072
	s_barrier

; #define LDA(dst, b, h) for (int m = 0; m < 4; ++m) for (int k = 0; k < 2; ++k) \
;     dst[m][k] = *reinterpret_cast<const bf16x8*>((char*)SA(b, h) + lds_byte(wr * 64 + m * 16 + fr, k * 32 + fq * 8))
; #define LDB(dst, b, h) for (int n = 0; n < 2; ++n) for (int k = 0; k < 2; ++k) \
;     dst[n][k] = *reinterpret_cast<const bf16x8*>((char*)SB(b, h) + lds_byte(wc * 32 + n * 16 + fr, k * 32 + fq * 8))
; #define MMA(ai, bj, At_, Bt_) do { __builtin_amdgcn_s_setprio(1); \
;     for (int m = 0; m < 4; ++m) for (int n = 0; n < 2; ++n) for (int k = 0; k < 2; ++k) \
;       acc[ai][bj][m][n] = MFMA16(Bt_[n][k], At_[m][k], acc[ai][bj][m][n]); \
;     __builtin_amdgcn_s_setprio(0); } while (0)
; #define WAIT_L(n) asm volatile("s_waitcnt lgkmcnt(" #n ")" ::: "memory")
; #define BAR __builtin_amdgcn_s_barrier()
; #define SCHED __builtin_amdgcn_sched_barrier(0)
; template <int PART  , bool SYNC_FIRST = true>
; __device__ __forceinline__ void kloop_t(const u16* __restrict__ A, int lda, const u16* __restrict__ Bt, int ldb, int K, Acc& acc, const int wv) {
;     ...
;   for (int t = 0; t < nt - 2; t += 2) {
;     LDB(B0, 0, 0); SCHED; LDA(At, 0, 0); STAGE(SA(1, 1), A, lda, HALF, t + 1);
;     WAIT_L(8); BAR; WAIT_L(0); MMA(0, 0, At, B0); BAR; SCHED;
;     LDB(B1, 0, 1); STAGE(SB(0, 0), Bt, ldb, 0, t + 2);
;     BAR; WAIT_L(0); MMA(0, 1, At, B1); BAR;
;     LDA(At, 0, 1); STAGE(SA(0, 0), A, lda, 0, t + 2);
.LBB0_1139:
	v_add_u32_e32 v164, v156, v160
	v_add_u32_e32 v166, v156, v162
	v_add_u32_e32 v165, v156, v161
	ds_read_b128 v[174:177], v164
	ds_read_b128 v[178:181], v165
	v_add_u32_e32 v167, v156, v163
	ds_read_b128 v[182:185], v166
	ds_read_b128 v[186:189], v167
	s_add_u32 s44, s42, s56
	v_mov_b32_e32 v170, v131
	v_mov_b32_e32 v128, v130
	s_addc_u32 s45, s43, 0
	ds_read_b128 v[190:193], v132
	ds_read_b128 v[194:197], v133
	ds_read_b128 v[198:201], v134
	ds_read_b128 v[202:205], v135
	ds_read_b128 v[206:209], v136
	ds_read_b128 v[210:213], v137
	ds_read_b128 v[214:217], v138
	ds_read_b128 v[218:221], v139
	v_mov_b32_e32 v171, v129
	v_lshl_add_u64 v[168:169], s[44:45], 0, v[128:129]
	v_lshl_add_u64 v[172:173], v[168:169], 0, s[24:25]
	v_add_u32_e32 v168, 0xc000, v144
	v_add_u32_e32 v169, 0xe000, v144
	v_readfirstlane_b32 s52, v168
	s_mov_b32 m0, s52
	v_lshl_add_u64 v[170:171], s[44:45], 0, v[170:171]
	v_readfirstlane_b32 s52, v169
	global_load_lds_dwordx4 v[172:173], off
	v_lshl_add_u64 v[170:171], v[170:171], 0, s[24:25]
	s_mov_b32 m0, s52
	s_nop 0
	global_load_lds_dwordx4 v[170:171], off
	s_waitcnt lgkmcnt(8)
	s_barrier
	s_waitcnt lgkmcnt(0)
	s_waitcnt lgkmcnt(0)
	v_mfma_f32_16x16x32_bf16 v[124:127], v[174:177], v[190:193], v[124:127]
	v_mfma_f32_16x16x32_bf16 v[120:123], v[182:185], v[190:193], v[120:123]
	v_mfma_f32_16x16x32_bf16 v[116:119], v[174:177], v[198:201], v[116:119]
	v_mfma_f32_16x16x32_bf16 v[112:115], v[182:185], v[198:201], v[112:115]
	v_mfma_f32_16x16x32_bf16 v[108:111], v[174:177], v[206:209], v[108:111]
	v_mfma_f32_16x16x32_bf16 v[104:107], v[182:185], v[206:209], v[104:107]
	v_mfma_f32_16x16x32_bf16 v[100:103], v[174:177], v[214:217], v[100:103]
	v_mfma_f32_16x16x32_bf16 v[96:99], v[182:185], v[214:217], v[96:99]
	v_mfma_f32_16x16x32_bf16 v[124:127], v[178:181], v[194:197], v[124:127]
	v_mfma_f32_16x16x32_bf16 v[120:123], v[186:189], v[194:197], v[120:123]
	v_mfma_f32_16x16x32_bf16 v[116:119], v[178:181], v[202:205], v[116:119]
	v_mfma_f32_16x16x32_bf16 v[112:115], v[186:189], v[202:205], v[112:115]
	v_mfma_f32_16x16x32_bf16 v[108:111], v[178:181], v[210:213], v[108:111]
	v_mfma_f32_16x16x32_bf16 v[104:107], v[186:189], v[210:213], v[104:107]
	v_mfma_f32_16x16x32_bf16 v[100:103], v[178:181], v[218:221], v[100:103]
	v_mfma_f32_16x16x32_bf16 v[96:99], v[186:189], v[218:221], v[96:99]
	s_barrier
	s_add_u32 s52, s42, s55
	v_add_u32_e32 v170, v157, v160
	v_add_u32_e32 v172, v157, v162
	v_mov_b32_e32 v238, v131
	v_mov_b32_e32 v128, v130
	s_addc_u32 s53, s43, 0
	v_add_u32_e32 v171, v157, v161
	ds_read_b128 v[222:225], v170
	ds_read_b128 v[226:229], v171
	v_add_u32_e32 v173, v157, v163
	ds_read_b128 v[230:233], v172
	ds_read_b128 v[234:237], v173
	v_readfirstlane_b32 s87, v142
	v_lshl_add_u64 v[240:241], s[52:53], 0, v[128:129]
	v_mov_b32_e32 v239, v129
	v_lshl_add_u64 v[240:241], v[240:241], 0, s[26:27]
	s_mov_b32 m0, s87
	v_lshl_add_u64 v[238:239], s[52:53], 0, v[238:239]
	v_readfirstlane_b32 s87, v143
	global_load_lds_dwordx4 v[240:241], off
	v_lshl_add_u64 v[238:239], v[238:239], 0, s[26:27]
	s_mov_b32 m0, s87
	s_nop 0
	global_load_lds_dwordx4 v[238:239], off
	s_barrier
	s_waitcnt lgkmcnt(0)
	s_waitcnt lgkmcnt(0)
	v_mfma_f32_16x16x32_bf16 v[92:95], v[222:225], v[190:193], v[92:95]
	v_mfma_f32_16x16x32_bf16 v[88:91], v[230:233], v[190:193], v[88:91]
	v_mfma_f32_16x16x32_bf16 v[84:87], v[222:225], v[198:201], v[84:87]
	v_mfma_f32_16x16x32_bf16 v[80:83], v[230:233], v[198:201], v[80:83]
	v_mfma_f32_16x16x32_bf16 v[76:79], v[222:225], v[206:209], v[76:79]
	v_mfma_f32_16x16x32_bf16 v[72:75], v[230:233], v[206:209], v[72:75]
	v_mfma_f32_16x16x32_bf16 v[68:71], v[222:225], v[214:217], v[68:71]
	v_mfma_f32_16x16x32_bf16 v[64:67], v[230:233], v[214:217], v[64:67]
	v_mfma_f32_16x16x32_bf16 v[92:95], v[226:229], v[194:197], v[92:95]
	v_mfma_f32_16x16x32_bf16 v[88:91], v[234:237], v[194:197], v[88:91]
	v_mfma_f32_16x16x32_bf16 v[84:87], v[226:229], v[202:205], v[84:87]
	v_mfma_f32_16x16x32_bf16 v[80:83], v[234:237], v[202:205], v[80:83]
	v_mfma_f32_16x16x32_bf16 v[76:79], v[226:229], v[210:213], v[76:79]
	v_mfma_f32_16x16x32_bf16 v[72:75], v[234:237], v[210:213], v[72:75]
	v_mfma_f32_16x16x32_bf16 v[68:71], v[226:229], v[218:221], v[68:71]
	v_mfma_f32_16x16x32_bf16 v[64:67], v[234:237], v[218:221], v[64:67]
	v_mov_b32_e32 v238, v131
	v_mov_b32_e32 v128, v130
	s_barrier
	ds_read_b128 v[190:193], v132 offset:16384
	ds_read_b128 v[194:197], v133 offset:16384
	ds_read_b128 v[198:201], v134 offset:16384
	ds_read_b128 v[202:205], v135 offset:16384
	ds_read_b128 v[206:209], v136 offset:16384
	ds_read_b128 v[210:213], v137 offset:16384
	ds_read_b128 v[214:217], v138 offset:16384
	ds_read_b128 v[218:221], v139 offset:16384
	v_readfirstlane_b32 s87, v144
	v_lshl_add_u64 v[240:241], s[44:45], 0, v[128:129]
	v_mov_b32_e32 v239, v129
	v_lshl_add_u64 v[240:241], v[240:241], 0, s[28:29]
	s_mov_b32 m0, s87
	v_lshl_add_u64 v[238:239], s[44:45], 0, v[238:239]
	v_readfirstlane_b32 s87, v145
	global_load_lds_dwordx4 v[240:241], off
	v_lshl_add_u64 v[238:239], v[238:239], 0, s[28:29]
	s_mov_b32 m0, s87
	s_nop 0
	global_load_lds_dwordx4 v[238:239], off
	s_barrier
; #define LDA(dst, b, h) for (int m = 0; m < 4; ++m) for (int k = 0; k < 2; ++k) \
;     dst[m][k] = *reinterpret_cast<const bf16x8*>((char*)SA(b, h) + lds_byte(wr * 64 + m * 16 + fr, k * 32 + fq * 8))
; #define LDB(dst, b, h) for (int n = 0; n < 2; ++n) for (int k = 0; k < 2; ++k) \
;     dst[n][k] = *reinterpret_cast<const bf16x8*>((char*)SB(b, h) + lds_byte(wc * 32 + n * 16 + fr, k * 32 + fq * 8))
; #define MMA(ai, bj, At_, Bt_) do { __builtin_amdgcn_s_setprio(1); \
;     for (int m = 0; m < 4; ++m) for (int n = 0; n < 2; ++n) for (int k = 0; k < 2; ++k) \
;       acc[ai][bj][m][n] = MFMA16(Bt_[n][k], At_[m][k], acc[ai][bj][m][n]); \
;     __builtin_amdgcn_s_setprio(0); } while (0)
; #define WAIT_V(n) asm volatile("s_waitcnt vmcnt(" #n ")" ::: "memory")
; #define WAIT_L(n) asm volatile("s_waitcnt lgkmcnt(" #n ")" ::: "memory")
; #define BAR __builtin_amdgcn_s_barrier()
; #define SCHED __builtin_amdgcn_sched_barrier(0)
; template <int PART  , bool SYNC_FIRST = true>
; __device__ __forceinline__ void kloop_t(const u16* __restrict__ A, int lda, const u16* __restrict__ Bt, int ldb, int K, Acc& acc, const int wv) {
;     ...
;     BAR; WAIT_L(0); MMA(1, 0, At, B0); BAR; SCHED;
;     STAGE(SB(0, 1), Bt, ldb, HALF, t + 2);
;     WAIT_V(6); BAR; MMA(1, 1, At, B1); BAR;
;     LDB(B0, 1, 0); SCHED; LDA(At, 1, 0); STAGE(SA(0, 1), A, lda, HALF, t + 2);
;     WAIT_L(8); BAR; WAIT_L(0); MMA(0, 0, At, B0); BAR; SCHED;
;     LDB(B1, 1, 1); STAGE(SB(1, 0), Bt, ldb, 0, t + 3);
;     BAR; WAIT_L(0); MMA(0, 1, At, B1); BAR;
	s_waitcnt lgkmcnt(0)
	s_waitcnt lgkmcnt(0)
	v_mfma_f32_16x16x32_bf16 v[60:63], v[174:177], v[190:193], v[60:63]
	v_mfma_f32_16x16x32_bf16 v[56:59], v[182:185], v[190:193], v[56:59]
	v_mfma_f32_16x16x32_bf16 v[52:55], v[174:177], v[198:201], v[52:55]
	v_mfma_f32_16x16x32_bf16 v[48:51], v[182:185], v[198:201], v[48:51]
	v_mfma_f32_16x16x32_bf16 v[44:47], v[174:177], v[206:209], v[44:47]
	v_mfma_f32_16x16x32_bf16 v[40:43], v[182:185], v[206:209], v[40:43]
	v_mfma_f32_16x16x32_bf16 v[36:39], v[174:177], v[214:217], v[36:39]
	v_mfma_f32_16x16x32_bf16 v[32:35], v[182:185], v[214:217], v[32:35]
	v_mfma_f32_16x16x32_bf16 v[60:63], v[178:181], v[194:197], v[60:63]
	v_mfma_f32_16x16x32_bf16 v[56:59], v[186:189], v[194:197], v[56:59]
	v_mfma_f32_16x16x32_bf16 v[52:55], v[178:181], v[202:205], v[52:55]
	v_mfma_f32_16x16x32_bf16 v[48:51], v[186:189], v[202:205], v[48:51]
	v_mfma_f32_16x16x32_bf16 v[44:47], v[178:181], v[210:213], v[44:47]
	v_mfma_f32_16x16x32_bf16 v[40:43], v[186:189], v[210:213], v[40:43]
	v_mfma_f32_16x16x32_bf16 v[36:39], v[178:181], v[218:221], v[36:39]
	v_mfma_f32_16x16x32_bf16 v[32:35], v[186:189], v[218:221], v[32:35]
	s_barrier
	v_mov_b32_e32 v174, v131
	v_mov_b32_e32 v128, v130
	v_readfirstlane_b32 s87, v146
	v_lshl_add_u64 v[176:177], s[52:53], 0, v[128:129]
	v_mov_b32_e32 v175, v129
	v_lshl_add_u64 v[176:177], v[176:177], 0, s[30:31]
	s_mov_b32 m0, s87
	v_lshl_add_u64 v[174:175], s[52:53], 0, v[174:175]
	v_readfirstlane_b32 s87, v147
	global_load_lds_dwordx4 v[176:177], off
	v_lshl_add_u64 v[174:175], v[174:175], 0, s[30:31]
	s_mov_b32 m0, s87
	s_nop 0
	global_load_lds_dwordx4 v[174:175], off
	s_waitcnt vmcnt(6)
	s_barrier
	v_mfma_f32_16x16x32_bf16 v[28:31], v[222:225], v[190:193], v[28:31]
	v_mfma_f32_16x16x32_bf16 v[24:27], v[230:233], v[190:193], v[24:27]
	v_mfma_f32_16x16x32_bf16 v[20:23], v[222:225], v[198:201], v[20:23]
	v_mfma_f32_16x16x32_bf16 v[16:19], v[230:233], v[198:201], v[16:19]
	v_mfma_f32_16x16x32_bf16 v[12:15], v[222:225], v[206:209], v[12:15]
	v_mfma_f32_16x16x32_bf16 v[8:11], v[230:233], v[206:209], v[8:11]
	v_mfma_f32_16x16x32_bf16 v[4:7], v[222:225], v[214:217], v[4:7]
	v_mfma_f32_16x16x32_bf16 v[0:3], v[230:233], v[214:217], v[0:3]
	v_mfma_f32_16x16x32_bf16 v[28:31], v[226:229], v[194:197], v[28:31]
	v_mfma_f32_16x16x32_bf16 v[24:27], v[234:237], v[194:197], v[24:27]
	v_mfma_f32_16x16x32_bf16 v[20:23], v[226:229], v[202:205], v[20:23]
	v_mfma_f32_16x16x32_bf16 v[16:19], v[234:237], v[202:205], v[16:19]
	v_mfma_f32_16x16x32_bf16 v[12:15], v[226:229], v[210:213], v[12:15]
	v_mfma_f32_16x16x32_bf16 v[8:11], v[234:237], v[210:213], v[8:11]
	v_mfma_f32_16x16x32_bf16 v[4:7], v[226:229], v[218:221], v[4:7]
	v_mfma_f32_16x16x32_bf16 v[0:3], v[234:237], v[218:221], v[0:3]
	v_add_u32_e32 v174, v158, v160
	v_add_u32_e32 v176, v158, v162
	s_barrier
	v_add_u32_e32 v175, v158, v161
	ds_read_b128 v[182:185], v174
	ds_read_b128 v[186:189], v175
	v_add_u32_e32 v177, v158, v163
	ds_read_b128 v[190:193], v176
	ds_read_b128 v[194:197], v177
	v_mov_b32_e32 v178, v131
	v_mov_b32_e32 v128, v130
	ds_read_b128 v[198:201], v132 offset:32768
	ds_read_b128 v[202:205], v133 offset:32768
	ds_read_b128 v[206:209], v134 offset:32768
	ds_read_b128 v[210:213], v135 offset:32768
	ds_read_b128 v[214:217], v136 offset:32768
	ds_read_b128 v[218:221], v137 offset:32768
	ds_read_b128 v[222:225], v138 offset:32768
	ds_read_b128 v[226:229], v139 offset:32768
	v_readfirstlane_b32 s87, v148
	v_lshl_add_u64 v[180:181], s[44:45], 0, v[128:129]
	v_mov_b32_e32 v179, v129
	v_lshl_add_u64 v[180:181], v[180:181], 0, s[34:35]
	s_mov_b32 m0, s87
	v_lshl_add_u64 v[178:179], s[44:45], 0, v[178:179]
	v_readfirstlane_b32 s87, v149
	global_load_lds_dwordx4 v[180:181], off
	v_lshl_add_u64 v[178:179], v[178:179], 0, s[34:35]
	s_mov_b32 m0, s87
	s_nop 0
	global_load_lds_dwordx4 v[178:179], off
	s_waitcnt lgkmcnt(8)
	s_barrier
	s_waitcnt lgkmcnt(0)
	s_waitcnt lgkmcnt(0)
	v_mfma_f32_16x16x32_bf16 v[124:127], v[182:185], v[198:201], v[124:127]
	v_mfma_f32_16x16x32_bf16 v[120:123], v[190:193], v[198:201], v[120:123]
	v_mfma_f32_16x16x32_bf16 v[116:119], v[182:185], v[206:209], v[116:119]
	v_mfma_f32_16x16x32_bf16 v[112:115], v[190:193], v[206:209], v[112:115]
	v_mfma_f32_16x16x32_bf16 v[108:111], v[182:185], v[214:217], v[108:111]
	v_mfma_f32_16x16x32_bf16 v[104:107], v[190:193], v[214:217], v[104:107]
	v_mfma_f32_16x16x32_bf16 v[100:103], v[182:185], v[222:225], v[100:103]
	v_mfma_f32_16x16x32_bf16 v[96:99], v[190:193], v[222:225], v[96:99]
	v_mfma_f32_16x16x32_bf16 v[124:127], v[186:189], v[202:205], v[124:127]
	v_mfma_f32_16x16x32_bf16 v[120:123], v[194:197], v[202:205], v[120:123]
	v_mfma_f32_16x16x32_bf16 v[116:119], v[186:189], v[210:213], v[116:119]
	v_mfma_f32_16x16x32_bf16 v[112:115], v[194:197], v[210:213], v[112:115]
	v_mfma_f32_16x16x32_bf16 v[108:111], v[186:189], v[218:221], v[108:111]
	v_mfma_f32_16x16x32_bf16 v[104:107], v[194:197], v[218:221], v[104:107]
	v_mfma_f32_16x16x32_bf16 v[100:103], v[186:189], v[226:229], v[100:103]
	v_mfma_f32_16x16x32_bf16 v[96:99], v[194:197], v[226:229], v[96:99]
	s_barrier
	v_add_u32_e32 v178, v159, v160
	v_add_u32_e32 v180, v159, v162
	v_mov_b32_e32 v246, v131
	v_mov_b32_e32 v128, v130
	v_add_u32_e32 v179, v159, v161
	ds_read_b128 v[230:233], v178
	ds_read_b128 v[234:237], v179
	v_add_u32_e32 v181, v159, v163
	ds_read_b128 v[238:241], v180
	ds_read_b128 v[242:245], v181
	v_readfirstlane_b32 s87, v150
	v_lshl_add_u64 v[248:249], s[52:53], 0, v[128:129]
	v_mov_b32_e32 v247, v129
	v_lshl_add_u64 v[248:249], v[248:249], 0, s[36:37]
	s_mov_b32 m0, s87
	v_lshl_add_u64 v[246:247], s[52:53], 0, v[246:247]
	v_readfirstlane_b32 s87, v151
	global_load_lds_dwordx4 v[248:249], off
	v_lshl_add_u64 v[246:247], v[246:247], 0, s[36:37]
	s_mov_b32 m0, s87
	s_nop 0
	global_load_lds_dwordx4 v[246:247], off
	s_barrier
; #define LDA(dst, b, h) for (int m = 0; m < 4; ++m) for (int k = 0; k < 2; ++k) \
;     dst[m][k] = *reinterpret_cast<const bf16x8*>((char*)SA(b, h) + lds_byte(wr * 64 + m * 16 + fr, k * 32 + fq * 8))
; #define LDB(dst, b, h) for (int n = 0; n < 2; ++n) for (int k = 0; k < 2; ++k) \
;     dst[n][k] = *reinterpret_cast<const bf16x8*>((char*)SB(b, h) + lds_byte(wc * 32 + n * 16 + fr, k * 32 + fq * 8))
; #define MMA(ai, bj, At_, Bt_) do { __builtin_amdgcn_s_setprio(1); \
;     for (int m = 0; m < 4; ++m) for (int n = 0; n < 2; ++n) for (int k = 0; k < 2; ++k) \
;       acc[ai][bj][m][n] = MFMA16(Bt_[n][k], At_[m][k], acc[ai][bj][m][n]); \
;     __builtin_amdgcn_s_setprio(0); } while (0)
; #define WAIT_V(n) asm volatile("s_waitcnt vmcnt(" #n ")" ::: "memory")
; #define WAIT_L(n) asm volatile("s_waitcnt lgkmcnt(" #n ")" ::: "memory")
; #define BAR __builtin_amdgcn_s_barrier()
; #define SCHED __builtin_amdgcn_sched_barrier(0)
; template <int PART  , bool SYNC_FIRST = true>
; __device__ __forceinline__ void kloop_t(const u16* __restrict__ A, int lda, const u16* __restrict__ Bt, int ldb, int K, Acc& acc, const int wv) {
;     ...
;     BAR; WAIT_L(0); MMA(0, 1, At, B1); BAR;
;     LDA(At, 1, 1); STAGE(SA(1, 0), A, lda, 0, t + 3);
;     BAR; WAIT_L(0); MMA(1, 0, At, B0); BAR; SCHED;
;     STAGE(SB(1, 1), Bt, ldb, HALF, t + 3);
;     WAIT_V(6); BAR; MMA(1, 1, At, B1); BAR;
;   }
;   { LDB(B0, 0, 0); LDA(At, 0, 0); STAGE(SA(1, 1), A, lda, HALF, nt - 1);
	s_waitcnt lgkmcnt(0)
	s_waitcnt lgkmcnt(0)
	v_mfma_f32_16x16x32_bf16 v[92:95], v[230:233], v[198:201], v[92:95]
	v_mfma_f32_16x16x32_bf16 v[88:91], v[238:241], v[198:201], v[88:91]
	v_mfma_f32_16x16x32_bf16 v[84:87], v[230:233], v[206:209], v[84:87]
	v_mfma_f32_16x16x32_bf16 v[80:83], v[238:241], v[206:209], v[80:83]
	v_mfma_f32_16x16x32_bf16 v[76:79], v[230:233], v[214:217], v[76:79]
	v_mfma_f32_16x16x32_bf16 v[72:75], v[238:241], v[214:217], v[72:75]
	v_mfma_f32_16x16x32_bf16 v[68:71], v[230:233], v[222:225], v[68:71]
	v_mfma_f32_16x16x32_bf16 v[64:67], v[238:241], v[222:225], v[64:67]
	v_mfma_f32_16x16x32_bf16 v[92:95], v[234:237], v[202:205], v[92:95]
	v_mfma_f32_16x16x32_bf16 v[88:91], v[242:245], v[202:205], v[88:91]
	v_mfma_f32_16x16x32_bf16 v[84:87], v[234:237], v[210:213], v[84:87]
	v_mfma_f32_16x16x32_bf16 v[80:83], v[242:245], v[210:213], v[80:83]
	v_mfma_f32_16x16x32_bf16 v[76:79], v[234:237], v[218:221], v[76:79]
	v_mfma_f32_16x16x32_bf16 v[72:75], v[242:245], v[218:221], v[72:75]
	v_mfma_f32_16x16x32_bf16 v[68:71], v[234:237], v[226:229], v[68:71]
	v_mfma_f32_16x16x32_bf16 v[64:67], v[242:245], v[226:229], v[64:67]
	v_mov_b32_e32 v246, v131
	v_mov_b32_e32 v128, v130
	s_barrier
	ds_read_b128 v[198:201], v132 offset:49152
	ds_read_b128 v[202:205], v133 offset:49152
	ds_read_b128 v[206:209], v134 offset:49152
	ds_read_b128 v[210:213], v135 offset:49152
	ds_read_b128 v[214:217], v136 offset:49152
	ds_read_b128 v[218:221], v137 offset:49152
	ds_read_b128 v[222:225], v138 offset:49152
	ds_read_b128 v[226:229], v139 offset:49152
	v_readfirstlane_b32 s87, v152
	v_lshl_add_u64 v[248:249], s[44:45], 0, v[128:129]
	v_mov_b32_e32 v247, v129
	v_lshl_add_u64 v[248:249], v[248:249], 0, s[38:39]
	s_mov_b32 m0, s87
	v_lshl_add_u64 v[246:247], s[44:45], 0, v[246:247]
	v_readfirstlane_b32 s44, v153
	global_load_lds_dwordx4 v[248:249], off
	v_lshl_add_u64 v[246:247], v[246:247], 0, s[38:39]
	s_mov_b32 m0, s44
	s_nop 0
	global_load_lds_dwordx4 v[246:247], off
	s_barrier
	s_waitcnt lgkmcnt(0)
	s_waitcnt lgkmcnt(0)
	v_mfma_f32_16x16x32_bf16 v[60:63], v[182:185], v[198:201], v[60:63]
	v_mfma_f32_16x16x32_bf16 v[56:59], v[190:193], v[198:201], v[56:59]
	v_mfma_f32_16x16x32_bf16 v[52:55], v[182:185], v[206:209], v[52:55]
	v_mfma_f32_16x16x32_bf16 v[48:51], v[190:193], v[206:209], v[48:51]
	v_mfma_f32_16x16x32_bf16 v[44:47], v[182:185], v[214:217], v[44:47]
	v_mfma_f32_16x16x32_bf16 v[40:43], v[190:193], v[214:217], v[40:43]
	v_mfma_f32_16x16x32_bf16 v[36:39], v[182:185], v[222:225], v[36:39]
	v_mfma_f32_16x16x32_bf16 v[32:35], v[190:193], v[222:225], v[32:35]
	v_mfma_f32_16x16x32_bf16 v[60:63], v[186:189], v[202:205], v[60:63]
	v_mfma_f32_16x16x32_bf16 v[56:59], v[194:197], v[202:205], v[56:59]
	v_mfma_f32_16x16x32_bf16 v[52:55], v[186:189], v[210:213], v[52:55]
	v_mfma_f32_16x16x32_bf16 v[48:51], v[194:197], v[210:213], v[48:51]
	v_mfma_f32_16x16x32_bf16 v[44:47], v[186:189], v[218:221], v[44:47]
	v_mfma_f32_16x16x32_bf16 v[40:43], v[194:197], v[218:221], v[40:43]
	v_mfma_f32_16x16x32_bf16 v[36:39], v[186:189], v[226:229], v[36:39]
	v_mfma_f32_16x16x32_bf16 v[32:35], v[194:197], v[226:229], v[32:35]
	s_barrier
	v_mov_b32_e32 v182, v131
	v_mov_b32_e32 v128, v130
	v_readfirstlane_b32 s44, v154
	v_lshl_add_u64 v[184:185], s[52:53], 0, v[128:129]
	v_mov_b32_e32 v183, v129
	v_lshl_add_u64 v[184:185], v[184:185], 0, s[40:41]
	s_mov_b32 m0, s44
	v_lshl_add_u64 v[182:183], s[52:53], 0, v[182:183]
	v_readfirstlane_b32 s44, v155
	global_load_lds_dwordx4 v[184:185], off
	v_lshl_add_u64 v[182:183], v[182:183], 0, s[40:41]
	s_mov_b32 m0, s44
	s_nop 0
	global_load_lds_dwordx4 v[182:183], off
	s_waitcnt vmcnt(6)
	s_barrier
	v_mfma_f32_16x16x32_bf16 v[28:31], v[230:233], v[198:201], v[28:31]
	v_mfma_f32_16x16x32_bf16 v[24:27], v[238:241], v[198:201], v[24:27]
	v_mfma_f32_16x16x32_bf16 v[20:23], v[230:233], v[206:209], v[20:23]
	v_mfma_f32_16x16x32_bf16 v[16:19], v[238:241], v[206:209], v[16:19]
	v_mfma_f32_16x16x32_bf16 v[12:15], v[230:233], v[214:217], v[12:15]
	v_mfma_f32_16x16x32_bf16 v[8:11], v[238:241], v[214:217], v[8:11]
	v_mfma_f32_16x16x32_bf16 v[4:7], v[230:233], v[222:225], v[4:7]
	v_mfma_f32_16x16x32_bf16 v[0:3], v[238:241], v[222:225], v[0:3]
	v_mfma_f32_16x16x32_bf16 v[28:31], v[234:237], v[202:205], v[28:31]
	v_mfma_f32_16x16x32_bf16 v[24:27], v[242:245], v[202:205], v[24:27]
	v_mfma_f32_16x16x32_bf16 v[20:23], v[234:237], v[210:213], v[20:23]
	v_mfma_f32_16x16x32_bf16 v[16:19], v[242:245], v[210:213], v[16:19]
	v_mfma_f32_16x16x32_bf16 v[12:15], v[234:237], v[218:221], v[12:15]
	v_mfma_f32_16x16x32_bf16 v[8:11], v[242:245], v[218:221], v[8:11]
	v_mfma_f32_16x16x32_bf16 v[4:7], v[234:237], v[226:229], v[4:7]
	v_mfma_f32_16x16x32_bf16 v[0:3], v[242:245], v[226:229], v[0:3]
	s_add_i32 s57, s57, 2
	s_add_u32 s42, s42, 0x100
	s_addc_u32 s43, s43, 0
	s_cmp_lt_u32 s57, 60
	s_barrier
	s_cbranch_scc1 .LBB0_1139
	s_add_u32 s4, s4, 0x101f80
	v_readfirstlane_b32 s42, v168
	s_addc_u32 s5, s5, 0
	s_mov_b32 m0, s42
	v_readfirstlane_b32 s42, v169
	ds_read_b128 v[142:145], v164
	ds_read_b128 v[146:149], v165
	ds_read_b128 v[150:153], v166
	ds_read_b128 v[154:157], v167
	ds_read_b128 v[158:161], v132
	ds_read_b128 v[162:165], v133
	ds_read_b128 v[182:185], v134
	ds_read_b128 v[186:189], v135
	ds_read_b128 v[190:193], v136
	ds_read_b128 v[194:197], v137
	ds_read_b128 v[198:201], v138
	ds_read_b128 v[202:205], v139
	s_nop 0
	global_load_lds_dwordx4 v130, s[4:5]
	s_mov_b32 m0, s42
	s_nop 0
	global_load_lds_dwordx4 v131, s[4:5]
	s_barrier
; #define LDA(dst, b, h) for (int m = 0; m < 4; ++m) for (int k = 0; k < 2; ++k) \
;     dst[m][k] = *reinterpret_cast<const bf16x8*>((char*)SA(b, h) + lds_byte(wr * 64 + m * 16 + fr, k * 32 + fq * 8))
; #define LDB(dst, b, h) for (int n = 0; n < 2; ++n) for (int k = 0; k < 2; ++k) \
;     dst[n][k] = *reinterpret_cast<const bf16x8*>((char*)SB(b, h) + lds_byte(wc * 32 + n * 16 + fr, k * 32 + fq * 8))
; #define MMA(ai, bj, At_, Bt_) do { __builtin_amdgcn_s_setprio(1); \
;     for (int m = 0; m < 4; ++m) for (int n = 0; n < 2; ++n) for (int k = 0; k < 2; ++k) \
;       acc[ai][bj][m][n] = MFMA16(Bt_[n][k], At_[m][k], acc[ai][bj][m][n]); \
;     __builtin_amdgcn_s_setprio(0); } while (0)
; #define WAIT_V(n) asm volatile("s_waitcnt vmcnt(" #n ")" ::: "memory")
; #define WAIT_L(n) asm volatile("s_waitcnt lgkmcnt(" #n ")" ::: "memory")
; #define BAR __builtin_amdgcn_s_barrier()
; template <int PART  , bool SYNC_FIRST = true>
; __device__ __forceinline__ void kloop_t(const u16* __restrict__ A, int lda, const u16* __restrict__ Bt, int ldb, int K, Acc& acc, const int wv) {
;     ...
;     BAR; WAIT_L(0); MMA(0, 0, At, B0); BAR;
;     LDB(B1, 0, 1); BAR; WAIT_L(0); MMA(0, 1, At, B1); BAR;
;     LDA(At, 0, 1); WAIT_V(4); BAR; WAIT_L(0); MMA(1, 0, At, B0); MMA(1, 1, At, B1); BAR; }
;   { LDB(B0, 1, 0); LDA(At, 1, 0); WAIT_V(2); BAR; WAIT_L(0); MMA(0, 0, At, B0); BAR;
	s_waitcnt lgkmcnt(0)
	s_waitcnt lgkmcnt(0)
	v_mfma_f32_16x16x32_bf16 v[124:127], v[142:145], v[158:161], v[124:127]
	v_mfma_f32_16x16x32_bf16 v[120:123], v[150:153], v[158:161], v[120:123]
	v_mfma_f32_16x16x32_bf16 v[108:111], v[142:145], v[190:193], v[108:111]
	v_mfma_f32_16x16x32_bf16 v[104:107], v[150:153], v[190:193], v[104:107]
	v_mfma_f32_16x16x32_bf16 v[124:127], v[146:149], v[162:165], v[124:127]
	v_mfma_f32_16x16x32_bf16 v[120:123], v[154:157], v[162:165], v[120:123]
	v_mfma_f32_16x16x32_bf16 v[116:119], v[142:145], v[182:185], v[116:119]
	v_mfma_f32_16x16x32_bf16 v[112:115], v[150:153], v[182:185], v[112:115]
	v_mfma_f32_16x16x32_bf16 v[108:111], v[146:149], v[194:197], v[108:111]
	v_mfma_f32_16x16x32_bf16 v[104:107], v[154:157], v[194:197], v[104:107]
	v_mfma_f32_16x16x32_bf16 v[100:103], v[142:145], v[198:201], v[100:103]
	v_mfma_f32_16x16x32_bf16 v[96:99], v[150:153], v[198:201], v[96:99]
	v_mfma_f32_16x16x32_bf16 v[166:169], v[146:149], v[186:189], v[116:119]
	v_mfma_f32_16x16x32_bf16 v[206:209], v[154:157], v[186:189], v[112:115]
	v_mfma_f32_16x16x32_bf16 v[210:213], v[146:149], v[202:205], v[100:103]
	v_mfma_f32_16x16x32_bf16 v[214:217], v[154:157], v[202:205], v[96:99]
	s_barrier
	s_nop 1
	ds_read_b128 v[96:99], v170
	ds_read_b128 v[100:103], v171
	ds_read_b128 v[112:115], v172
	ds_read_b128 v[116:119], v173
	s_barrier
	s_waitcnt lgkmcnt(0)
	s_waitcnt lgkmcnt(0)
	v_mfma_f32_16x16x32_bf16 v[92:95], v[96:99], v[158:161], v[92:95]
	v_mfma_f32_16x16x32_bf16 v[88:91], v[112:115], v[158:161], v[88:91]
	v_mfma_f32_16x16x32_bf16 v[76:79], v[96:99], v[190:193], v[76:79]
	v_mfma_f32_16x16x32_bf16 v[72:75], v[112:115], v[190:193], v[72:75]
	v_mfma_f32_16x16x32_bf16 v[92:95], v[100:103], v[162:165], v[92:95]
	v_mfma_f32_16x16x32_bf16 v[88:91], v[116:119], v[162:165], v[88:91]
	v_mfma_f32_16x16x32_bf16 v[84:87], v[96:99], v[182:185], v[84:87]
	v_mfma_f32_16x16x32_bf16 v[80:83], v[112:115], v[182:185], v[80:83]
	v_mfma_f32_16x16x32_bf16 v[76:79], v[100:103], v[194:197], v[76:79]
	v_mfma_f32_16x16x32_bf16 v[72:75], v[116:119], v[194:197], v[72:75]
	v_mfma_f32_16x16x32_bf16 v[68:71], v[96:99], v[198:201], v[68:71]
	v_mfma_f32_16x16x32_bf16 v[64:67], v[112:115], v[198:201], v[64:67]
	v_mfma_f32_16x16x32_bf16 v[158:161], v[100:103], v[186:189], v[84:87]
	v_mfma_f32_16x16x32_bf16 v[162:165], v[116:119], v[186:189], v[80:83]
	v_mfma_f32_16x16x32_bf16 v[170:173], v[100:103], v[202:205], v[68:71]
	v_mfma_f32_16x16x32_bf16 v[182:185], v[116:119], v[202:205], v[64:67]
	s_barrier
	s_nop 1
	ds_read_b128 v[64:67], v132 offset:16384
	ds_read_b128 v[68:71], v133 offset:16384
	ds_read_b128 v[80:83], v134 offset:16384
	ds_read_b128 v[84:87], v135 offset:16384
	ds_read_b128 v[186:189], v136 offset:16384
	ds_read_b128 v[190:193], v137 offset:16384
	ds_read_b128 v[194:197], v138 offset:16384
	ds_read_b128 v[198:201], v139 offset:16384
	s_waitcnt vmcnt(4)
	s_barrier
	s_waitcnt lgkmcnt(0)
	s_waitcnt lgkmcnt(0)
	v_mfma_f32_16x16x32_bf16 v[60:63], v[142:145], v[64:67], v[60:63]
	v_mfma_f32_16x16x32_bf16 v[56:59], v[150:153], v[64:67], v[56:59]
	v_mfma_f32_16x16x32_bf16 v[44:47], v[142:145], v[186:189], v[44:47]
	v_mfma_f32_16x16x32_bf16 v[40:43], v[150:153], v[186:189], v[40:43]
	v_mfma_f32_16x16x32_bf16 v[60:63], v[146:149], v[68:71], v[60:63]
	v_mfma_f32_16x16x32_bf16 v[56:59], v[154:157], v[68:71], v[56:59]
	v_mfma_f32_16x16x32_bf16 v[52:55], v[142:145], v[80:83], v[52:55]
	v_mfma_f32_16x16x32_bf16 v[48:51], v[150:153], v[80:83], v[48:51]
	v_mfma_f32_16x16x32_bf16 v[44:47], v[146:149], v[190:193], v[44:47]
	v_mfma_f32_16x16x32_bf16 v[40:43], v[154:157], v[190:193], v[40:43]
	v_mfma_f32_16x16x32_bf16 v[36:39], v[142:145], v[194:197], v[36:39]
	v_mfma_f32_16x16x32_bf16 v[32:35], v[150:153], v[194:197], v[32:35]
	v_mfma_f32_16x16x32_bf16 v[202:205], v[146:149], v[84:87], v[52:55]
	v_mfma_f32_16x16x32_bf16 v[218:221], v[154:157], v[84:87], v[48:51]
	v_mfma_f32_16x16x32_bf16 v[142:145], v[146:149], v[198:201], v[36:39]
	v_mfma_f32_16x16x32_bf16 v[146:149], v[154:157], v[198:201], v[32:35]
	v_mfma_f32_16x16x32_bf16 v[28:31], v[96:99], v[64:67], v[28:31]
	v_mfma_f32_16x16x32_bf16 v[24:27], v[112:115], v[64:67], v[24:27]
	v_mfma_f32_16x16x32_bf16 v[12:15], v[96:99], v[186:189], v[12:15]
	v_mfma_f32_16x16x32_bf16 v[8:11], v[112:115], v[186:189], v[8:11]
	v_mfma_f32_16x16x32_bf16 v[28:31], v[100:103], v[68:71], v[28:31]
	v_mfma_f32_16x16x32_bf16 v[24:27], v[116:119], v[68:71], v[24:27]
	v_mfma_f32_16x16x32_bf16 v[20:23], v[96:99], v[80:83], v[20:23]
	v_mfma_f32_16x16x32_bf16 v[16:19], v[112:115], v[80:83], v[16:19]
	v_mfma_f32_16x16x32_bf16 v[12:15], v[100:103], v[190:193], v[12:15]
	v_mfma_f32_16x16x32_bf16 v[8:11], v[116:119], v[190:193], v[8:11]
	v_mfma_f32_16x16x32_bf16 v[4:7], v[96:99], v[194:197], v[4:7]
	v_mfma_f32_16x16x32_bf16 v[0:3], v[112:115], v[194:197], v[0:3]
	v_mfma_f32_16x16x32_bf16 v[150:153], v[100:103], v[84:87], v[20:23]
	v_mfma_f32_16x16x32_bf16 v[154:157], v[116:119], v[84:87], v[16:19]
	v_mfma_f32_16x16x32_bf16 v[186:189], v[100:103], v[198:201], v[4:7]
	v_mfma_f32_16x16x32_bf16 v[190:193], v[116:119], v[198:201], v[0:3]
	s_barrier
; #define LDA(dst, b, h) for (int m = 0; m < 4; ++m) for (int k = 0; k < 2; ++k) \
;     dst[m][k] = *reinterpret_cast<const bf16x8*>((char*)SA(b, h) + lds_byte(wr * 64 + m * 16 + fr, k * 32 + fq * 8))
; #define LDB(dst, b, h) for (int n = 0; n < 2; ++n) for (int k = 0; k < 2; ++k) \
;     dst[n][k] = *reinterpret_cast<const bf16x8*>((char*)SB(b, h) + lds_byte(wc * 32 + n * 16 + fr, k * 32 + fq * 8))
; #define MMA(ai, bj, At_, Bt_) do { __builtin_amdgcn_s_setprio(1); \
;     for (int m = 0; m < 4; ++m) for (int n = 0; n < 2; ++n) for (int k = 0; k < 2; ++k) \
;       acc[ai][bj][m][n] = MFMA16(Bt_[n][k], At_[m][k], acc[ai][bj][m][n]); \
;     __builtin_amdgcn_s_setprio(0); } while (0)
; #define WAIT_V(n) asm volatile("s_waitcnt vmcnt(" #n ")" ::: "memory")
; #define WAIT_L(n) asm volatile("s_waitcnt lgkmcnt(" #n ")" ::: "memory")
; #define BAR __builtin_amdgcn_s_barrier()
; template <int PART  , bool SYNC_FIRST = true>
; __device__ __forceinline__ void kloop_t(const u16* __restrict__ A, int lda, const u16* __restrict__ Bt, int ldb, int K, Acc& acc, const int wv) {
;     ...
;   { LDB(B0, 1, 0); LDA(At, 1, 0); WAIT_V(2); BAR; WAIT_L(0); MMA(0, 0, At, B0); BAR;
;     LDB(B1, 1, 1); WAIT_V(0); BAR; WAIT_L(0); MMA(0, 1, At, B1); BAR;
;     LDA(At, 1, 1); BAR; WAIT_L(0); MMA(1, 0, At, B0); MMA(1, 1, At, B1); BAR; }
	s_nop 1
	ds_read_b128 v[0:3], v174
	ds_read_b128 v[4:7], v175
	ds_read_b128 v[194:197], v176
	ds_read_b128 v[174:177], v177
	ds_read_b128 v[16:19], v132 offset:32768
	ds_read_b128 v[20:23], v133 offset:32768
	ds_read_b128 v[32:35], v134 offset:32768
	ds_read_b128 v[36:39], v135 offset:32768
	ds_read_b128 v[48:51], v136 offset:32768
	ds_read_b128 v[52:55], v137 offset:32768
	ds_read_b128 v[198:201], v138 offset:32768
	ds_read_b128 v[222:225], v139 offset:32768
	s_waitcnt vmcnt(2)
	s_barrier
	s_waitcnt lgkmcnt(0)
	s_waitcnt lgkmcnt(0)
	v_mfma_f32_16x16x32_bf16 v[64:67], v[0:3], v[16:19], v[124:127]
	v_mfma_f32_16x16x32_bf16 v[112:115], v[4:7], v[20:23], v[64:67]
	v_mfma_f32_16x16x32_bf16 v[64:67], v[194:197], v[16:19], v[120:123]
	v_mfma_f32_16x16x32_bf16 v[116:119], v[174:177], v[20:23], v[64:67]
	v_mfma_f32_16x16x32_bf16 v[64:67], v[0:3], v[32:35], v[166:169]
	v_mfma_f32_16x16x32_bf16 v[96:99], v[4:7], v[36:39], v[64:67]
	v_mfma_f32_16x16x32_bf16 v[64:67], v[194:197], v[32:35], v[206:209]
	v_mfma_f32_16x16x32_bf16 v[100:103], v[174:177], v[36:39], v[64:67]
	v_mfma_f32_16x16x32_bf16 v[64:67], v[0:3], v[48:51], v[108:111]
	v_mfma_f32_16x16x32_bf16 v[80:83], v[4:7], v[52:55], v[64:67]
	v_mfma_f32_16x16x32_bf16 v[64:67], v[194:197], v[48:51], v[104:107]
	v_mfma_f32_16x16x32_bf16 v[84:87], v[174:177], v[52:55], v[64:67]
	v_mfma_f32_16x16x32_bf16 v[64:67], v[0:3], v[198:201], v[210:213]
	v_mfma_f32_16x16x32_bf16 v[68:71], v[194:197], v[198:201], v[214:217]
	v_mfma_f32_16x16x32_bf16 v[64:67], v[4:7], v[222:225], v[64:67]
	v_mfma_f32_16x16x32_bf16 v[68:71], v[174:177], v[222:225], v[68:71]
	s_barrier
	ds_read_b128 v[166:169], v178
	ds_read_b128 v[206:209], v179
	ds_read_b128 v[210:213], v180
	ds_read_b128 v[178:181], v181
	s_waitcnt vmcnt(0)
	s_barrier
	s_waitcnt lgkmcnt(0)
	s_waitcnt lgkmcnt(0)
	v_mfma_f32_16x16x32_bf16 v[92:95], v[166:169], v[16:19], v[92:95]
	v_mfma_f32_16x16x32_bf16 v[16:19], v[210:213], v[16:19], v[88:91]
	v_mfma_f32_16x16x32_bf16 v[124:127], v[178:181], v[20:23], v[16:19]
	v_mfma_f32_16x16x32_bf16 v[16:19], v[166:169], v[32:35], v[158:161]
	v_mfma_f32_16x16x32_bf16 v[104:107], v[206:209], v[36:39], v[16:19]
	v_mfma_f32_16x16x32_bf16 v[16:19], v[210:213], v[32:35], v[162:165]
	v_mfma_f32_16x16x32_bf16 v[108:111], v[178:181], v[36:39], v[16:19]
	v_mfma_f32_16x16x32_bf16 v[16:19], v[166:169], v[48:51], v[76:79]
	v_mfma_f32_16x16x32_bf16 v[88:91], v[206:209], v[52:55], v[16:19]
	v_mfma_f32_16x16x32_bf16 v[16:19], v[210:213], v[48:51], v[72:75]
	v_mfma_f32_16x16x32_bf16 v[120:123], v[206:209], v[20:23], v[92:95]
	v_mfma_f32_16x16x32_bf16 v[92:95], v[178:181], v[52:55], v[16:19]
	v_mfma_f32_16x16x32_bf16 v[16:19], v[166:169], v[198:201], v[170:173]
	v_mfma_f32_16x16x32_bf16 v[72:75], v[206:209], v[222:225], v[16:19]
	v_mfma_f32_16x16x32_bf16 v[16:19], v[210:213], v[198:201], v[182:185]
	v_mfma_f32_16x16x32_bf16 v[76:79], v[178:181], v[222:225], v[16:19]
	s_barrier
	ds_read_b128 v[158:161], v132 offset:49152
	ds_read_b128 v[130:133], v133 offset:49152
	ds_read_b128 v[162:165], v134 offset:49152
	ds_read_b128 v[170:173], v135 offset:49152
	ds_read_b128 v[182:185], v136 offset:49152
	ds_read_b128 v[134:137], v137 offset:49152
	ds_read_b128 v[198:201], v138 offset:49152
	ds_read_b128 v[214:217], v139 offset:49152
	s_barrier
	s_waitcnt lgkmcnt(0)
	s_waitcnt lgkmcnt(0)
	v_mfma_f32_16x16x32_bf16 v[16:19], v[0:3], v[158:161], v[60:63]
	v_mfma_f32_16x16x32_bf16 v[48:51], v[4:7], v[130:133], v[16:19]
	v_mfma_f32_16x16x32_bf16 v[16:19], v[194:197], v[158:161], v[56:59]
	v_mfma_f32_16x16x32_bf16 v[52:55], v[174:177], v[130:133], v[16:19]
	v_mfma_f32_16x16x32_bf16 v[16:19], v[0:3], v[162:165], v[202:205]
	v_mfma_f32_16x16x32_bf16 v[32:35], v[4:7], v[170:173], v[16:19]
	v_mfma_f32_16x16x32_bf16 v[16:19], v[194:197], v[162:165], v[218:221]
	v_mfma_f32_16x16x32_bf16 v[36:39], v[174:177], v[170:173], v[16:19]
	v_mfma_f32_16x16x32_bf16 v[16:19], v[0:3], v[182:185], v[44:47]
	v_mfma_f32_16x16x32_bf16 v[0:3], v[0:3], v[198:201], v[142:145]
	v_mfma_f32_16x16x32_bf16 v[16:19], v[4:7], v[134:137], v[16:19]
	v_mfma_f32_16x16x32_bf16 v[20:23], v[194:197], v[182:185], v[40:43]
	v_mfma_f32_16x16x32_bf16 v[0:3], v[4:7], v[214:217], v[0:3]
	v_mfma_f32_16x16x32_bf16 v[4:7], v[194:197], v[198:201], v[146:149]
	v_mfma_f32_16x16x32_bf16 v[20:23], v[174:177], v[134:137], v[20:23]
	v_mfma_f32_16x16x32_bf16 v[4:7], v[174:177], v[214:217], v[4:7]
	v_mfma_f32_16x16x32_bf16 v[24:27], v[210:213], v[158:161], v[24:27]
	v_mfma_f32_16x16x32_bf16 v[60:63], v[178:181], v[130:133], v[24:27]
	v_mfma_f32_16x16x32_bf16 v[24:27], v[166:169], v[162:165], v[150:153]
	v_mfma_f32_16x16x32_bf16 v[28:31], v[166:169], v[158:161], v[28:31]
	v_mfma_f32_16x16x32_bf16 v[40:43], v[206:209], v[170:173], v[24:27]
	v_mfma_f32_16x16x32_bf16 v[24:27], v[210:213], v[162:165], v[154:157]
	v_mfma_f32_16x16x32_bf16 v[12:15], v[166:169], v[182:185], v[12:15]
	v_mfma_f32_16x16x32_bf16 v[8:11], v[210:213], v[182:185], v[8:11]
	v_mfma_f32_16x16x32_bf16 v[56:59], v[206:209], v[130:133], v[28:31]
	v_mfma_f32_16x16x32_bf16 v[44:47], v[178:181], v[170:173], v[24:27]
	v_mfma_f32_16x16x32_bf16 v[24:27], v[206:209], v[134:137], v[12:15]
	v_mfma_f32_16x16x32_bf16 v[28:31], v[178:181], v[134:137], v[8:11]
	v_mfma_f32_16x16x32_bf16 v[8:11], v[166:169], v[198:201], v[186:189]
	v_mfma_f32_16x16x32_bf16 v[12:15], v[210:213], v[198:201], v[190:193]
	v_mfma_f32_16x16x32_bf16 v[8:11], v[206:209], v[214:217], v[8:11]
	v_mfma_f32_16x16x32_bf16 v[12:15], v[178:181], v[214:217], v[12:15]
	s_andn2_b64 vcc, exec, s[16:17]
	s_barrier
	s_cbranch_vccnz .LBB0_1142
	s_barrier
